# GEMM K-loops: s_setprio/s_barrier handoff reordered, mid-segment setprio flips and redundant lgkmcnt(0) removed
# speedup vs baseline: 1.0028x; 1.0028x over previous
.LBB0_198:
	s_add_u32 s20, s16, 0xfffc0080
	s_addc_u32 s21, s17, -1
	s_add_i32 s49, 0, 0x10000
	s_cmp_eq_u32 s48, 12
	s_cselect_b32 s23, s13, s21
	s_cselect_b32 s22, s44, s20
	v_add_u32_e32 v140, s49, v143
	s_cselect_b32 s21, s11, s47
	s_cselect_b32 s20, s45, s46
	s_add_i32 s60, 0, 0x14000
	ds_read_b128 v[146:149], v140
	ds_read_b128 v[150:153], v140 offset:1024
	ds_read_b128 v[154:157], v140 offset:2048
	ds_read_b128 v[158:161], v140 offset:3072
	v_add_u32_e32 v140, s60, v143
	ds_read_b128 v[162:165], v140
	ds_read_b128 v[166:169], v140 offset:1024
	ds_read_b128 v[170:173], v140 offset:2048
	ds_read_b128 v[174:177], v140 offset:3072
	v_lshl_add_u64 v[140:141], s[16:17], 0, v[136:137]
	s_add_i32 m0, s33, 0xc000
	ds_read_b128 v[196:199], v145
	ds_read_b128 v[212:215], v145 offset:1024
	ds_read_b128 v[216:219], v145 offset:2048
	ds_read_b128 v[220:223], v145 offset:3072
	ds_read_b128 v[224:227], v145 offset:4096
	ds_read_b128 v[228:231], v145 offset:5120
	ds_read_b128 v[232:235], v145 offset:6144
	ds_read_b128 v[236:239], v145 offset:7168
	global_load_lds_dwordx4 v[140:141], off
	v_lshl_add_u64 v[140:141], s[16:17], 0, v[138:139]
	s_add_i32 m0, s33, 0xe000
	s_nop 0
	global_load_lds_dwordx4 v[140:141], off
	s_waitcnt vmcnt(8)
	s_waitcnt lgkmcnt(0)
	s_setprio 1
	s_barrier
	v_mfma_f32_16x16x32_bf16 v[126:129], v[146:149], v[196:199], v[126:129]
	v_mfma_f32_16x16x32_bf16 v[122:125], v[154:157], v[196:199], v[122:125]
	v_mfma_f32_16x16x32_bf16 v[114:117], v[146:149], v[216:219], v[114:117]
	v_mfma_f32_16x16x32_bf16 v[106:109], v[154:157], v[216:219], v[106:109]
	v_mfma_f32_16x16x32_bf16 v[98:101], v[146:149], v[224:227], v[98:101]
	v_mfma_f32_16x16x32_bf16 v[90:93], v[154:157], v[224:227], v[90:93]
	v_mfma_f32_16x16x32_bf16 v[82:85], v[146:149], v[232:235], v[82:85]
	v_mfma_f32_16x16x32_bf16 v[74:77], v[154:157], v[232:235], v[74:77]
	v_mfma_f32_16x16x32_bf16 v[126:129], v[150:153], v[212:215], v[126:129]
	v_mfma_f32_16x16x32_bf16 v[122:125], v[158:161], v[212:215], v[122:125]
	v_mfma_f32_16x16x32_bf16 v[114:117], v[150:153], v[220:223], v[114:117]
	v_mfma_f32_16x16x32_bf16 v[106:109], v[158:161], v[220:223], v[106:109]
	v_mfma_f32_16x16x32_bf16 v[98:101], v[150:153], v[228:231], v[98:101]
	v_mfma_f32_16x16x32_bf16 v[90:93], v[158:161], v[228:231], v[90:93]
	v_mfma_f32_16x16x32_bf16 v[82:85], v[150:153], v[236:239], v[82:85]
	v_mfma_f32_16x16x32_bf16 v[74:77], v[158:161], v[236:239], v[74:77]
	v_mfma_f32_16x16x32_bf16 v[118:121], v[162:165], v[196:199], v[118:121]
	v_mfma_f32_16x16x32_bf16 v[110:113], v[170:173], v[196:199], v[110:113]
	v_mfma_f32_16x16x32_bf16 v[102:105], v[162:165], v[216:219], v[102:105]
	v_mfma_f32_16x16x32_bf16 v[94:97], v[170:173], v[216:219], v[94:97]
	v_mfma_f32_16x16x32_bf16 v[86:89], v[162:165], v[224:227], v[86:89]
	v_mfma_f32_16x16x32_bf16 v[78:81], v[170:173], v[224:227], v[78:81]
	v_mfma_f32_16x16x32_bf16 v[70:73], v[162:165], v[232:235], v[70:73]
	v_mfma_f32_16x16x32_bf16 v[66:69], v[170:173], v[232:235], v[66:69]
	v_mfma_f32_16x16x32_bf16 v[118:121], v[166:169], v[212:215], v[118:121]
	v_mfma_f32_16x16x32_bf16 v[110:113], v[174:177], v[212:215], v[110:113]
	v_mfma_f32_16x16x32_bf16 v[102:105], v[166:169], v[220:223], v[102:105]
	v_mfma_f32_16x16x32_bf16 v[94:97], v[174:177], v[220:223], v[94:97]
	v_mfma_f32_16x16x32_bf16 v[86:89], v[166:169], v[228:231], v[86:89]
	v_mfma_f32_16x16x32_bf16 v[78:81], v[174:177], v[228:231], v[78:81]
	v_mfma_f32_16x16x32_bf16 v[70:73], v[166:169], v[236:239], v[70:73]
	v_mfma_f32_16x16x32_bf16 v[66:69], v[174:177], v[236:239], v[66:69]
	s_barrier
	s_setprio 0
	s_add_i32 s49, s49, s31
	v_lshl_add_u64 v[140:141], s[20:21], 0, v[178:179]
	s_mov_b32 m0, s49
	ds_read_b128 v[196:199], v145 offset:16384
	ds_read_b128 v[212:215], v145 offset:17408
	ds_read_b128 v[216:219], v145 offset:18432
	ds_read_b128 v[220:223], v145 offset:19456
	ds_read_b128 v[224:227], v145 offset:20480
	ds_read_b128 v[228:231], v145 offset:21504
	ds_read_b128 v[232:235], v145 offset:22528
	ds_read_b128 v[236:239], v145 offset:23552
	global_load_lds_dwordx4 v[140:141], off
	s_add_i32 m0, s49, 0x2000
	s_add_u32 s50, s20, 0x40000
	v_lshl_add_u64 v[240:241], s[20:21], 0, v[130:131]
	s_addc_u32 s51, s21, 0
	s_add_i32 s49, s60, s31
	global_load_lds_dwordx4 v[240:241], off
	v_lshl_add_u64 v[242:243], s[50:51], 0, v[178:179]
	s_mov_b32 m0, s49
	v_lshl_add_u64 v[244:245], s[22:23], 0, v[132:133]
	global_load_lds_dwordx4 v[242:243], off
	v_lshl_add_u64 v[242:243], s[50:51], 0, v[130:131]
	s_add_i32 m0, s49, 0x2000
	s_nop 0
	global_load_lds_dwordx4 v[242:243], off
	v_lshl_add_u64 v[242:243], s[22:23], 0, v[134:135]
	s_mov_b32 m0, s33
	s_nop 0
	global_load_lds_dwordx4 v[242:243], off
	s_mov_b32 m0, s34
	s_nop 0
	global_load_lds_dwordx4 v[244:245], off
	s_waitcnt vmcnt(8)
	s_waitcnt lgkmcnt(0)
	s_setprio 1
	s_barrier
	v_mfma_f32_16x16x32_bf16 v[62:65], v[146:149], v[196:199], v[62:65]
	v_mfma_f32_16x16x32_bf16 v[58:61], v[154:157], v[196:199], v[58:61]
	v_mfma_f32_16x16x32_bf16 v[50:53], v[146:149], v[216:219], v[50:53]
	v_mfma_f32_16x16x32_bf16 v[42:45], v[154:157], v[216:219], v[42:45]
	v_mfma_f32_16x16x32_bf16 v[34:37], v[146:149], v[224:227], v[34:37]
	v_mfma_f32_16x16x32_bf16 v[26:29], v[154:157], v[224:227], v[26:29]
	v_mfma_f32_16x16x32_bf16 v[18:21], v[146:149], v[232:235], v[18:21]
	v_mfma_f32_16x16x32_bf16 v[10:13], v[154:157], v[232:235], v[10:13]
	v_mfma_f32_16x16x32_bf16 v[62:65], v[150:153], v[212:215], v[62:65]
	v_mfma_f32_16x16x32_bf16 v[58:61], v[158:161], v[212:215], v[58:61]
	v_mfma_f32_16x16x32_bf16 v[50:53], v[150:153], v[220:223], v[50:53]
	v_mfma_f32_16x16x32_bf16 v[42:45], v[158:161], v[220:223], v[42:45]
	v_mfma_f32_16x16x32_bf16 v[34:37], v[150:153], v[228:231], v[34:37]
	v_mfma_f32_16x16x32_bf16 v[26:29], v[158:161], v[228:231], v[26:29]
	v_mfma_f32_16x16x32_bf16 v[18:21], v[150:153], v[236:239], v[18:21]
	v_mfma_f32_16x16x32_bf16 v[10:13], v[158:161], v[236:239], v[10:13]
	v_mfma_f32_16x16x32_bf16 v[54:57], v[162:165], v[196:199], v[54:57]
	v_mfma_f32_16x16x32_bf16 v[46:49], v[170:173], v[196:199], v[46:49]
	v_mfma_f32_16x16x32_bf16 v[38:41], v[162:165], v[216:219], v[38:41]
	v_mfma_f32_16x16x32_bf16 v[30:33], v[170:173], v[216:219], v[30:33]
	v_mfma_f32_16x16x32_bf16 v[22:25], v[162:165], v[224:227], v[22:25]
	v_mfma_f32_16x16x32_bf16 v[14:17], v[170:173], v[224:227], v[14:17]
	v_mfma_f32_16x16x32_bf16 v[6:9], v[162:165], v[232:235], v[6:9]
	v_mfma_f32_16x16x32_bf16 v[2:5], v[170:173], v[232:235], v[2:5]
	v_mfma_f32_16x16x32_bf16 v[54:57], v[166:169], v[212:215], v[54:57]
	v_mfma_f32_16x16x32_bf16 v[46:49], v[174:177], v[212:215], v[46:49]
	v_mfma_f32_16x16x32_bf16 v[38:41], v[166:169], v[220:223], v[38:41]
	v_mfma_f32_16x16x32_bf16 v[30:33], v[174:177], v[220:223], v[30:33]
	v_mfma_f32_16x16x32_bf16 v[22:25], v[166:169], v[228:231], v[22:25]
	v_mfma_f32_16x16x32_bf16 v[14:17], v[174:177], v[228:231], v[14:17]
	v_mfma_f32_16x16x32_bf16 v[6:9], v[166:169], v[236:239], v[6:9]
	v_mfma_f32_16x16x32_bf16 v[2:5], v[174:177], v[236:239], v[2:5]
	s_barrier
	s_setprio 0
	s_add_i32 s49, 0, 0x18000
	s_add_i32 s50, 0, 0x1c000
	v_add_u32_e32 v158, s49, v143
	v_add_u32_e32 v174, s50, v143
	ds_read_b128 v[146:149], v158
	ds_read_b128 v[150:153], v158 offset:1024
	ds_read_b128 v[154:157], v158 offset:2048
	ds_read_b128 v[158:161], v158 offset:3072
	ds_read_b128 v[162:165], v174
	ds_read_b128 v[166:169], v174 offset:1024
	ds_read_b128 v[170:173], v174 offset:2048
	ds_read_b128 v[174:177], v174 offset:3072
	s_add_u32 s22, s22, 0x40000
	s_addc_u32 s23, s23, 0
	s_mov_b32 m0, s35
	v_lshl_add_u64 v[246:247], s[22:23], 0, v[134:135]
	ds_read_b128 v[196:199], v145 offset:32768
	ds_read_b128 v[212:215], v145 offset:33792
	ds_read_b128 v[216:219], v145 offset:34816
	ds_read_b128 v[220:223], v145 offset:35840
	ds_read_b128 v[224:227], v145 offset:36864
	ds_read_b128 v[228:231], v145 offset:37888
	ds_read_b128 v[232:235], v145 offset:38912
	ds_read_b128 v[236:239], v145 offset:39936
	global_load_lds_dwordx4 v[246:247], off
	v_lshl_add_u64 v[246:247], s[22:23], 0, v[132:133]
	s_mov_b32 m0, s38
	s_nop 0
	global_load_lds_dwordx4 v[246:247], off
	s_waitcnt vmcnt(8)
	s_waitcnt lgkmcnt(0)
	s_setprio 1
	s_barrier
	v_mfma_f32_16x16x32_bf16 v[126:129], v[146:149], v[196:199], v[126:129]
	v_mfma_f32_16x16x32_bf16 v[122:125], v[154:157], v[196:199], v[122:125]
	v_mfma_f32_16x16x32_bf16 v[114:117], v[146:149], v[216:219], v[114:117]
	v_mfma_f32_16x16x32_bf16 v[106:109], v[154:157], v[216:219], v[106:109]
	v_mfma_f32_16x16x32_bf16 v[98:101], v[146:149], v[224:227], v[98:101]
	v_mfma_f32_16x16x32_bf16 v[90:93], v[154:157], v[224:227], v[90:93]
	v_mfma_f32_16x16x32_bf16 v[82:85], v[146:149], v[232:235], v[82:85]
	v_mfma_f32_16x16x32_bf16 v[74:77], v[154:157], v[232:235], v[74:77]
	v_mfma_f32_16x16x32_bf16 v[126:129], v[150:153], v[212:215], v[126:129]
	v_mfma_f32_16x16x32_bf16 v[122:125], v[158:161], v[212:215], v[122:125]
	v_mfma_f32_16x16x32_bf16 v[114:117], v[150:153], v[220:223], v[114:117]
	v_mfma_f32_16x16x32_bf16 v[106:109], v[158:161], v[220:223], v[106:109]
	v_mfma_f32_16x16x32_bf16 v[98:101], v[150:153], v[228:231], v[98:101]
	v_mfma_f32_16x16x32_bf16 v[90:93], v[158:161], v[228:231], v[90:93]
	v_mfma_f32_16x16x32_bf16 v[82:85], v[150:153], v[236:239], v[82:85]
	v_mfma_f32_16x16x32_bf16 v[74:77], v[158:161], v[236:239], v[74:77]
	v_mfma_f32_16x16x32_bf16 v[118:121], v[162:165], v[196:199], v[118:121]
	v_mfma_f32_16x16x32_bf16 v[110:113], v[170:173], v[196:199], v[110:113]
	v_mfma_f32_16x16x32_bf16 v[102:105], v[162:165], v[216:219], v[102:105]
	v_mfma_f32_16x16x32_bf16 v[94:97], v[170:173], v[216:219], v[94:97]
	v_mfma_f32_16x16x32_bf16 v[86:89], v[162:165], v[224:227], v[86:89]
	v_mfma_f32_16x16x32_bf16 v[78:81], v[170:173], v[224:227], v[78:81]
	v_mfma_f32_16x16x32_bf16 v[70:73], v[162:165], v[232:235], v[70:73]
	v_mfma_f32_16x16x32_bf16 v[66:69], v[170:173], v[232:235], v[66:69]
	v_mfma_f32_16x16x32_bf16 v[118:121], v[166:169], v[212:215], v[118:121]
	v_mfma_f32_16x16x32_bf16 v[110:113], v[174:177], v[212:215], v[110:113]
	v_mfma_f32_16x16x32_bf16 v[102:105], v[166:169], v[220:223], v[102:105]
	v_mfma_f32_16x16x32_bf16 v[94:97], v[174:177], v[220:223], v[94:97]
	v_mfma_f32_16x16x32_bf16 v[86:89], v[166:169], v[228:231], v[86:89]
	v_mfma_f32_16x16x32_bf16 v[78:81], v[174:177], v[228:231], v[78:81]
	v_mfma_f32_16x16x32_bf16 v[70:73], v[166:169], v[236:239], v[70:73]
	v_mfma_f32_16x16x32_bf16 v[66:69], v[174:177], v[236:239], v[66:69]
	s_barrier
	s_setprio 0
	s_add_i32 s22, s49, s31
	v_lshl_add_u64 v[140:141], v[140:141], 0, s[90:91]
	s_mov_b32 m0, s22
	ds_read_b128 v[196:199], v145 offset:49152
	ds_read_b128 v[212:215], v145 offset:50176
	ds_read_b128 v[216:219], v145 offset:51200
	ds_read_b128 v[220:223], v145 offset:52224
	ds_read_b128 v[224:227], v145 offset:53248
	ds_read_b128 v[228:231], v145 offset:54272
	ds_read_b128 v[232:235], v145 offset:55296
	ds_read_b128 v[236:239], v145 offset:56320
	global_load_lds_dwordx4 v[140:141], off
	s_add_i32 m0, s22, 0x2000
	s_add_u32 s20, s20, 0x40080
	v_lshl_add_u64 v[140:141], v[240:241], 0, s[90:91]
	s_addc_u32 s21, s21, 0
	s_add_i32 s22, s50, s31
	global_load_lds_dwordx4 v[140:141], off
	v_lshl_add_u64 v[140:141], s[20:21], 0, v[178:179]
	s_mov_b32 m0, s22
	s_nop 0
	global_load_lds_dwordx4 v[140:141], off
	v_lshl_add_u64 v[140:141], s[20:21], 0, v[130:131]
	s_add_i32 m0, s22, 0x2000
	s_nop 0
	global_load_lds_dwordx4 v[140:141], off
	v_lshl_add_u64 v[140:141], v[242:243], 0, s[90:91]
	s_mov_b32 m0, s39
	s_nop 0
	global_load_lds_dwordx4 v[140:141], off
	v_lshl_add_u64 v[140:141], v[244:245], 0, s[90:91]
	s_mov_b32 m0, s40
	s_nop 0
	global_load_lds_dwordx4 v[140:141], off
	s_waitcnt vmcnt(8)
	s_waitcnt lgkmcnt(0)
	s_setprio 1
	s_barrier
	v_mfma_f32_16x16x32_bf16 v[62:65], v[146:149], v[196:199], v[62:65]
	v_mfma_f32_16x16x32_bf16 v[58:61], v[154:157], v[196:199], v[58:61]
	v_mfma_f32_16x16x32_bf16 v[50:53], v[146:149], v[216:219], v[50:53]
	v_mfma_f32_16x16x32_bf16 v[42:45], v[154:157], v[216:219], v[42:45]
	v_mfma_f32_16x16x32_bf16 v[34:37], v[146:149], v[224:227], v[34:37]
	v_mfma_f32_16x16x32_bf16 v[26:29], v[154:157], v[224:227], v[26:29]
	v_mfma_f32_16x16x32_bf16 v[18:21], v[146:149], v[232:235], v[18:21]
	v_mfma_f32_16x16x32_bf16 v[10:13], v[154:157], v[232:235], v[10:13]
	v_mfma_f32_16x16x32_bf16 v[62:65], v[150:153], v[212:215], v[62:65]
	v_mfma_f32_16x16x32_bf16 v[58:61], v[158:161], v[212:215], v[58:61]
	v_mfma_f32_16x16x32_bf16 v[50:53], v[150:153], v[220:223], v[50:53]
	v_mfma_f32_16x16x32_bf16 v[42:45], v[158:161], v[220:223], v[42:45]
	v_mfma_f32_16x16x32_bf16 v[34:37], v[150:153], v[228:231], v[34:37]
	v_mfma_f32_16x16x32_bf16 v[26:29], v[158:161], v[228:231], v[26:29]
	v_mfma_f32_16x16x32_bf16 v[18:21], v[150:153], v[236:239], v[18:21]
	v_mfma_f32_16x16x32_bf16 v[10:13], v[158:161], v[236:239], v[10:13]
	v_mfma_f32_16x16x32_bf16 v[54:57], v[162:165], v[196:199], v[54:57]
	v_mfma_f32_16x16x32_bf16 v[46:49], v[170:173], v[196:199], v[46:49]
	v_mfma_f32_16x16x32_bf16 v[38:41], v[162:165], v[216:219], v[38:41]
	v_mfma_f32_16x16x32_bf16 v[30:33], v[170:173], v[216:219], v[30:33]
	v_mfma_f32_16x16x32_bf16 v[22:25], v[162:165], v[224:227], v[22:25]
	v_mfma_f32_16x16x32_bf16 v[14:17], v[170:173], v[224:227], v[14:17]
	v_mfma_f32_16x16x32_bf16 v[6:9], v[162:165], v[232:235], v[6:9]
	v_mfma_f32_16x16x32_bf16 v[2:5], v[170:173], v[232:235], v[2:5]
	v_mfma_f32_16x16x32_bf16 v[54:57], v[166:169], v[212:215], v[54:57]
	v_mfma_f32_16x16x32_bf16 v[46:49], v[174:177], v[212:215], v[46:49]
	v_mfma_f32_16x16x32_bf16 v[38:41], v[166:169], v[220:223], v[38:41]
	v_mfma_f32_16x16x32_bf16 v[30:33], v[174:177], v[220:223], v[30:33]
	v_mfma_f32_16x16x32_bf16 v[22:25], v[166:169], v[228:231], v[22:25]
	v_mfma_f32_16x16x32_bf16 v[14:17], v[174:177], v[228:231], v[14:17]
	v_mfma_f32_16x16x32_bf16 v[6:9], v[166:169], v[236:239], v[6:9]
	v_mfma_f32_16x16x32_bf16 v[2:5], v[174:177], v[236:239], v[2:5]
	s_barrier
	s_setprio 0
	s_add_i32 s48, s48, 2
	s_add_u32 s16, s16, 0x100
	s_addc_u32 s17, s17, 0
	s_add_u32 s46, s46, 0x100
	s_addc_u32 s47, s47, 0
	s_cmp_gt_u32 s48, 13
	s_cbranch_scc0 .LBB0_198
	v_readlane_b32 s22, v255, 16
	s_and_b64 vcc, exec, s[6:7]
	v_readlane_b32 s23, v255, 17
	s_cbranch_vccz .LBB0_201
	s_barrier

.LBB0_215:
	s_add_u32 s16, s0, 0xfffc0080
	s_addc_u32 s17, s1, -1
	s_add_i32 s44, 0, 0x10000
	s_cmp_eq_u32 s43, 12
	s_cselect_b32 s21, s19, s17
	s_cselect_b32 s20, s33, s16
	v_add_u32_e32 v147, s44, v151
	s_cselect_b32 s17, s15, s42
	s_cselect_b32 s16, s40, s41
	s_add_i32 s46, 0, 0x14000
	ds_read_b128 v[154:157], v147
	ds_read_b128 v[158:161], v147 offset:1024
	ds_read_b128 v[162:165], v147 offset:2048
	ds_read_b128 v[166:169], v147 offset:3072
	v_add_u32_e32 v147, s46, v151
	ds_read_b128 v[170:173], v147
	ds_read_b128 v[174:177], v147 offset:1024
	ds_read_b128 v[196:199], v147 offset:2048
	ds_read_b128 v[212:215], v147 offset:3072
	v_lshl_add_u64 v[148:149], s[0:1], 0, v[142:143]
	s_add_i32 m0, s39, 0xc000
	ds_read_b128 v[216:219], v152
	ds_read_b128 v[220:223], v152 offset:1024
	ds_read_b128 v[224:227], v152 offset:2048
	ds_read_b128 v[228:231], v152 offset:3072
	ds_read_b128 v[232:235], v152 offset:4096
	ds_read_b128 v[236:239], v152 offset:5120
	ds_read_b128 v[240:243], v152 offset:6144
	ds_read_b128 v[244:247], v152 offset:7168
	global_load_lds_dwordx4 v[148:149], off
	v_lshl_add_u64 v[148:149], s[0:1], 0, v[144:145]
	s_add_i32 m0, s39, 0xe000
	s_nop 0
	global_load_lds_dwordx4 v[148:149], off
	s_waitcnt vmcnt(8)
	s_waitcnt lgkmcnt(0)
	s_setprio 1
	s_barrier
	v_mfma_f32_16x16x32_bf16 v[126:129], v[154:157], v[216:219], v[126:129]
	v_mfma_f32_16x16x32_bf16 v[122:125], v[162:165], v[216:219], v[122:125]
	v_mfma_f32_16x16x32_bf16 v[110:113], v[154:157], v[224:227], v[110:113]
	v_mfma_f32_16x16x32_bf16 v[106:109], v[162:165], v[224:227], v[106:109]
	v_mfma_f32_16x16x32_bf16 v[94:97], v[154:157], v[232:235], v[94:97]
	v_mfma_f32_16x16x32_bf16 v[90:93], v[162:165], v[232:235], v[90:93]
	v_mfma_f32_16x16x32_bf16 v[78:81], v[154:157], v[240:243], v[78:81]
	v_mfma_f32_16x16x32_bf16 v[74:77], v[162:165], v[240:243], v[74:77]
	v_mfma_f32_16x16x32_bf16 v[126:129], v[158:161], v[220:223], v[126:129]
	v_mfma_f32_16x16x32_bf16 v[122:125], v[166:169], v[220:223], v[122:125]
	v_mfma_f32_16x16x32_bf16 v[110:113], v[158:161], v[228:231], v[110:113]
	v_mfma_f32_16x16x32_bf16 v[106:109], v[166:169], v[228:231], v[106:109]
	v_mfma_f32_16x16x32_bf16 v[94:97], v[158:161], v[236:239], v[94:97]
	v_mfma_f32_16x16x32_bf16 v[90:93], v[166:169], v[236:239], v[90:93]
	v_mfma_f32_16x16x32_bf16 v[78:81], v[158:161], v[244:247], v[78:81]
	v_mfma_f32_16x16x32_bf16 v[74:77], v[166:169], v[244:247], v[74:77]
	v_mfma_f32_16x16x32_bf16 v[118:121], v[170:173], v[216:219], v[118:121]
	v_mfma_f32_16x16x32_bf16 v[114:117], v[196:199], v[216:219], v[114:117]
	v_mfma_f32_16x16x32_bf16 v[102:105], v[170:173], v[224:227], v[102:105]
	v_mfma_f32_16x16x32_bf16 v[98:101], v[196:199], v[224:227], v[98:101]
	v_mfma_f32_16x16x32_bf16 v[86:89], v[170:173], v[232:235], v[86:89]
	v_mfma_f32_16x16x32_bf16 v[82:85], v[196:199], v[232:235], v[82:85]
	v_mfma_f32_16x16x32_bf16 v[70:73], v[170:173], v[240:243], v[70:73]
	v_mfma_f32_16x16x32_bf16 v[66:69], v[196:199], v[240:243], v[66:69]
	v_mfma_f32_16x16x32_bf16 v[118:121], v[174:177], v[220:223], v[118:121]
	v_mfma_f32_16x16x32_bf16 v[114:117], v[212:215], v[220:223], v[114:117]
	v_mfma_f32_16x16x32_bf16 v[102:105], v[174:177], v[228:231], v[102:105]
	v_mfma_f32_16x16x32_bf16 v[98:101], v[212:215], v[228:231], v[98:101]
	v_mfma_f32_16x16x32_bf16 v[86:89], v[174:177], v[236:239], v[86:89]
	v_mfma_f32_16x16x32_bf16 v[82:85], v[212:215], v[236:239], v[82:85]
	v_mfma_f32_16x16x32_bf16 v[70:73], v[174:177], v[244:247], v[70:73]
	v_mfma_f32_16x16x32_bf16 v[66:69], v[212:215], v[244:247], v[66:69]
	s_barrier
	s_setprio 0
	s_add_i32 s44, s44, s38
	v_lshl_add_u64 v[148:149], s[16:17], 0, v[134:135]
	s_mov_b32 m0, s44
	ds_read_b128 v[216:219], v152 offset:16384
	ds_read_b128 v[220:223], v152 offset:17408
	ds_read_b128 v[224:227], v152 offset:18432
	ds_read_b128 v[228:231], v152 offset:19456
	ds_read_b128 v[232:235], v152 offset:20480
	ds_read_b128 v[236:239], v152 offset:21504
	ds_read_b128 v[240:243], v152 offset:22528
	ds_read_b128 v[244:247], v152 offset:23552
	global_load_lds_dwordx4 v[148:149], off
	s_add_i32 m0, s44, 0x2000
	s_add_u32 s44, s16, 0x40000
	v_lshl_add_u64 v[248:249], s[16:17], 0, v[130:131]
	s_addc_u32 s45, s17, 0
	s_add_i32 s46, s46, s38
	global_load_lds_dwordx4 v[248:249], off
	v_lshl_add_u64 v[250:251], s[44:45], 0, v[134:135]
	s_mov_b32 m0, s46
	v_lshl_add_u64 v[202:203], s[20:21], 0, v[132:133]
	global_load_lds_dwordx4 v[250:251], off
	v_lshl_add_u64 v[250:251], s[44:45], 0, v[130:131]
	s_add_i32 m0, s46, 0x2000
	s_nop 0
	global_load_lds_dwordx4 v[250:251], off
	v_lshl_add_u64 v[250:251], s[20:21], 0, v[136:137]
	s_mov_b32 m0, s39
	s_nop 0
	global_load_lds_dwordx4 v[250:251], off
	s_mov_b32 m0, s60
	s_nop 0
	global_load_lds_dwordx4 v[202:203], off
	s_waitcnt vmcnt(8)
	s_waitcnt lgkmcnt(0)
	s_setprio 1
	s_barrier
	v_mfma_f32_16x16x32_bf16 v[62:65], v[154:157], v[216:219], v[62:65]
	v_mfma_f32_16x16x32_bf16 v[58:61], v[162:165], v[216:219], v[58:61]
	v_mfma_f32_16x16x32_bf16 v[46:49], v[154:157], v[224:227], v[46:49]
	v_mfma_f32_16x16x32_bf16 v[42:45], v[162:165], v[224:227], v[42:45]
	v_mfma_f32_16x16x32_bf16 v[30:33], v[154:157], v[232:235], v[30:33]
	v_mfma_f32_16x16x32_bf16 v[26:29], v[162:165], v[232:235], v[26:29]
	v_mfma_f32_16x16x32_bf16 v[14:17], v[154:157], v[240:243], v[14:17]
	v_mfma_f32_16x16x32_bf16 v[10:13], v[162:165], v[240:243], v[10:13]
	v_mfma_f32_16x16x32_bf16 v[62:65], v[158:161], v[220:223], v[62:65]
	v_mfma_f32_16x16x32_bf16 v[58:61], v[166:169], v[220:223], v[58:61]
	v_mfma_f32_16x16x32_bf16 v[46:49], v[158:161], v[228:231], v[46:49]
	v_mfma_f32_16x16x32_bf16 v[42:45], v[166:169], v[228:231], v[42:45]
	v_mfma_f32_16x16x32_bf16 v[30:33], v[158:161], v[236:239], v[30:33]
	v_mfma_f32_16x16x32_bf16 v[26:29], v[166:169], v[236:239], v[26:29]
	v_mfma_f32_16x16x32_bf16 v[14:17], v[158:161], v[244:247], v[14:17]
	v_mfma_f32_16x16x32_bf16 v[10:13], v[166:169], v[244:247], v[10:13]
	v_mfma_f32_16x16x32_bf16 v[54:57], v[170:173], v[216:219], v[54:57]
	v_mfma_f32_16x16x32_bf16 v[50:53], v[196:199], v[216:219], v[50:53]
	v_mfma_f32_16x16x32_bf16 v[38:41], v[170:173], v[224:227], v[38:41]
	v_mfma_f32_16x16x32_bf16 v[34:37], v[196:199], v[224:227], v[34:37]
	v_mfma_f32_16x16x32_bf16 v[22:25], v[170:173], v[232:235], v[22:25]
	v_mfma_f32_16x16x32_bf16 v[18:21], v[196:199], v[232:235], v[18:21]
	v_mfma_f32_16x16x32_bf16 v[6:9], v[170:173], v[240:243], v[6:9]
	v_mfma_f32_16x16x32_bf16 v[2:5], v[196:199], v[240:243], v[2:5]
	v_mfma_f32_16x16x32_bf16 v[54:57], v[174:177], v[220:223], v[54:57]
	v_mfma_f32_16x16x32_bf16 v[50:53], v[212:215], v[220:223], v[50:53]
	v_mfma_f32_16x16x32_bf16 v[38:41], v[174:177], v[228:231], v[38:41]
	v_mfma_f32_16x16x32_bf16 v[34:37], v[212:215], v[228:231], v[34:37]
	v_mfma_f32_16x16x32_bf16 v[22:25], v[174:177], v[236:239], v[22:25]
	v_mfma_f32_16x16x32_bf16 v[18:21], v[212:215], v[236:239], v[18:21]
	v_mfma_f32_16x16x32_bf16 v[6:9], v[174:177], v[244:247], v[6:9]
	v_mfma_f32_16x16x32_bf16 v[2:5], v[212:215], v[244:247], v[2:5]
	s_barrier
	s_setprio 0
	s_add_i32 s44, 0, 0x18000
	v_add_u32_e32 v147, s44, v151
	s_add_i32 s45, 0, 0x1c000
	ds_read_b128 v[154:157], v147
	ds_read_b128 v[158:161], v147 offset:1024
	ds_read_b128 v[162:165], v147 offset:2048
	ds_read_b128 v[166:169], v147 offset:3072
	v_add_u32_e32 v147, s45, v151
	ds_read_b128 v[170:173], v147
	ds_read_b128 v[174:177], v147 offset:1024
	ds_read_b128 v[196:199], v147 offset:2048
	ds_read_b128 v[212:215], v147 offset:3072
	s_add_u32 s20, s20, 0x40000
	s_addc_u32 s21, s21, 0
	s_mov_b32 m0, s61
	v_lshl_add_u64 v[206:207], s[20:21], 0, v[136:137]
	ds_read_b128 v[216:219], v152 offset:32768
	ds_read_b128 v[220:223], v152 offset:33792
	ds_read_b128 v[224:227], v152 offset:34816
	ds_read_b128 v[228:231], v152 offset:35840
	ds_read_b128 v[232:235], v152 offset:36864
	ds_read_b128 v[236:239], v152 offset:37888
	ds_read_b128 v[240:243], v152 offset:38912
	ds_read_b128 v[244:247], v152 offset:39936
	global_load_lds_dwordx4 v[206:207], off
	v_lshl_add_u64 v[206:207], s[20:21], 0, v[132:133]
	s_mov_b32 m0, s88
	s_nop 0
	global_load_lds_dwordx4 v[206:207], off
	s_waitcnt vmcnt(8)
	s_waitcnt lgkmcnt(0)
	s_setprio 1
	s_barrier
	v_mfma_f32_16x16x32_bf16 v[126:129], v[154:157], v[216:219], v[126:129]
	v_mfma_f32_16x16x32_bf16 v[122:125], v[162:165], v[216:219], v[122:125]
	v_mfma_f32_16x16x32_bf16 v[110:113], v[154:157], v[224:227], v[110:113]
	v_mfma_f32_16x16x32_bf16 v[106:109], v[162:165], v[224:227], v[106:109]
	v_mfma_f32_16x16x32_bf16 v[94:97], v[154:157], v[232:235], v[94:97]
	v_mfma_f32_16x16x32_bf16 v[90:93], v[162:165], v[232:235], v[90:93]
	v_mfma_f32_16x16x32_bf16 v[78:81], v[154:157], v[240:243], v[78:81]
	v_mfma_f32_16x16x32_bf16 v[74:77], v[162:165], v[240:243], v[74:77]
	v_mfma_f32_16x16x32_bf16 v[126:129], v[158:161], v[220:223], v[126:129]
	v_mfma_f32_16x16x32_bf16 v[122:125], v[166:169], v[220:223], v[122:125]
	v_mfma_f32_16x16x32_bf16 v[110:113], v[158:161], v[228:231], v[110:113]
	v_mfma_f32_16x16x32_bf16 v[106:109], v[166:169], v[228:231], v[106:109]
	v_mfma_f32_16x16x32_bf16 v[94:97], v[158:161], v[236:239], v[94:97]
	v_mfma_f32_16x16x32_bf16 v[90:93], v[166:169], v[236:239], v[90:93]
	v_mfma_f32_16x16x32_bf16 v[78:81], v[158:161], v[244:247], v[78:81]
	v_mfma_f32_16x16x32_bf16 v[74:77], v[166:169], v[244:247], v[74:77]
	v_mfma_f32_16x16x32_bf16 v[118:121], v[170:173], v[216:219], v[118:121]
	v_mfma_f32_16x16x32_bf16 v[114:117], v[196:199], v[216:219], v[114:117]
	v_mfma_f32_16x16x32_bf16 v[102:105], v[170:173], v[224:227], v[102:105]
	v_mfma_f32_16x16x32_bf16 v[98:101], v[196:199], v[224:227], v[98:101]
	v_mfma_f32_16x16x32_bf16 v[86:89], v[170:173], v[232:235], v[86:89]
	v_mfma_f32_16x16x32_bf16 v[82:85], v[196:199], v[232:235], v[82:85]
	v_mfma_f32_16x16x32_bf16 v[70:73], v[170:173], v[240:243], v[70:73]
	v_mfma_f32_16x16x32_bf16 v[66:69], v[196:199], v[240:243], v[66:69]
	v_mfma_f32_16x16x32_bf16 v[118:121], v[174:177], v[220:223], v[118:121]
	v_mfma_f32_16x16x32_bf16 v[114:117], v[212:215], v[220:223], v[114:117]
	v_mfma_f32_16x16x32_bf16 v[102:105], v[174:177], v[228:231], v[102:105]
	v_mfma_f32_16x16x32_bf16 v[98:101], v[212:215], v[228:231], v[98:101]
	v_mfma_f32_16x16x32_bf16 v[86:89], v[174:177], v[236:239], v[86:89]
	v_mfma_f32_16x16x32_bf16 v[82:85], v[212:215], v[236:239], v[82:85]
	v_mfma_f32_16x16x32_bf16 v[70:73], v[174:177], v[244:247], v[70:73]
	v_mfma_f32_16x16x32_bf16 v[66:69], v[212:215], v[244:247], v[66:69]
	s_barrier
	s_setprio 0
	s_add_i32 s20, s44, s38
	v_lshl_add_u64 v[148:149], v[148:149], 0, s[90:91]
	s_mov_b32 m0, s20
	ds_read_b128 v[216:219], v152 offset:49152
	ds_read_b128 v[220:223], v152 offset:50176
	ds_read_b128 v[224:227], v152 offset:51200
	ds_read_b128 v[228:231], v152 offset:52224
	ds_read_b128 v[232:235], v152 offset:53248
	ds_read_b128 v[236:239], v152 offset:54272
	ds_read_b128 v[240:243], v152 offset:55296
	ds_read_b128 v[244:247], v152 offset:56320
	global_load_lds_dwordx4 v[148:149], off
	s_add_i32 m0, s20, 0x2000
	s_add_u32 s16, s16, 0x40080
	v_lshl_add_u64 v[148:149], v[248:249], 0, s[90:91]
	s_addc_u32 s17, s17, 0
	s_add_i32 s20, s45, s38
	global_load_lds_dwordx4 v[148:149], off
	v_lshl_add_u64 v[148:149], s[16:17], 0, v[134:135]
	s_mov_b32 m0, s20
	s_nop 0
	global_load_lds_dwordx4 v[148:149], off
	v_lshl_add_u64 v[148:149], s[16:17], 0, v[130:131]
	s_add_i32 m0, s20, 0x2000
	s_nop 0
	global_load_lds_dwordx4 v[148:149], off
	v_lshl_add_u64 v[148:149], v[250:251], 0, s[90:91]
	s_mov_b32 m0, s89
	s_nop 0
	global_load_lds_dwordx4 v[148:149], off
	v_lshl_add_u64 v[148:149], v[202:203], 0, s[90:91]
	s_mov_b32 m0, s92
	s_nop 0
	global_load_lds_dwordx4 v[148:149], off
	s_waitcnt vmcnt(8)
	s_waitcnt lgkmcnt(0)
	s_setprio 1
	s_barrier
	v_mfma_f32_16x16x32_bf16 v[62:65], v[154:157], v[216:219], v[62:65]
	v_mfma_f32_16x16x32_bf16 v[58:61], v[162:165], v[216:219], v[58:61]
	v_mfma_f32_16x16x32_bf16 v[46:49], v[154:157], v[224:227], v[46:49]
	v_mfma_f32_16x16x32_bf16 v[42:45], v[162:165], v[224:227], v[42:45]
	v_mfma_f32_16x16x32_bf16 v[30:33], v[154:157], v[232:235], v[30:33]
	v_mfma_f32_16x16x32_bf16 v[26:29], v[162:165], v[232:235], v[26:29]
	v_mfma_f32_16x16x32_bf16 v[14:17], v[154:157], v[240:243], v[14:17]
	v_mfma_f32_16x16x32_bf16 v[10:13], v[162:165], v[240:243], v[10:13]
	v_mfma_f32_16x16x32_bf16 v[62:65], v[158:161], v[220:223], v[62:65]
	v_mfma_f32_16x16x32_bf16 v[58:61], v[166:169], v[220:223], v[58:61]
	v_mfma_f32_16x16x32_bf16 v[46:49], v[158:161], v[228:231], v[46:49]
	v_mfma_f32_16x16x32_bf16 v[42:45], v[166:169], v[228:231], v[42:45]
	v_mfma_f32_16x16x32_bf16 v[30:33], v[158:161], v[236:239], v[30:33]
	v_mfma_f32_16x16x32_bf16 v[26:29], v[166:169], v[236:239], v[26:29]
	v_mfma_f32_16x16x32_bf16 v[14:17], v[158:161], v[244:247], v[14:17]
	v_mfma_f32_16x16x32_bf16 v[10:13], v[166:169], v[244:247], v[10:13]
	v_mfma_f32_16x16x32_bf16 v[54:57], v[170:173], v[216:219], v[54:57]
	v_mfma_f32_16x16x32_bf16 v[50:53], v[196:199], v[216:219], v[50:53]
	v_mfma_f32_16x16x32_bf16 v[38:41], v[170:173], v[224:227], v[38:41]
	v_mfma_f32_16x16x32_bf16 v[34:37], v[196:199], v[224:227], v[34:37]
	v_mfma_f32_16x16x32_bf16 v[22:25], v[170:173], v[232:235], v[22:25]
	v_mfma_f32_16x16x32_bf16 v[18:21], v[196:199], v[232:235], v[18:21]
	v_mfma_f32_16x16x32_bf16 v[6:9], v[170:173], v[240:243], v[6:9]
	v_mfma_f32_16x16x32_bf16 v[2:5], v[196:199], v[240:243], v[2:5]
	v_mfma_f32_16x16x32_bf16 v[54:57], v[174:177], v[220:223], v[54:57]
	v_mfma_f32_16x16x32_bf16 v[50:53], v[212:215], v[220:223], v[50:53]
	v_mfma_f32_16x16x32_bf16 v[38:41], v[174:177], v[228:231], v[38:41]
	v_mfma_f32_16x16x32_bf16 v[34:37], v[212:215], v[228:231], v[34:37]
	v_mfma_f32_16x16x32_bf16 v[22:25], v[174:177], v[236:239], v[22:25]
	v_mfma_f32_16x16x32_bf16 v[18:21], v[212:215], v[236:239], v[18:21]
	v_mfma_f32_16x16x32_bf16 v[6:9], v[174:177], v[244:247], v[6:9]
	v_mfma_f32_16x16x32_bf16 v[2:5], v[212:215], v[244:247], v[2:5]
	s_barrier
	s_setprio 0
	s_add_i32 s43, s43, 2
	s_add_u32 s0, s0, 0x100
	s_addc_u32 s1, s1, 0
	s_add_u32 s41, s41, 0x100
	s_addc_u32 s42, s42, 0
	s_cmp_gt_u32 s43, 13
	s_cbranch_scc0 .LBB0_215
	s_and_b64 vcc, exec, s[12:13]
	s_cbranch_vccz .LBB0_218
	s_barrier

.LBB0_355:
	s_add_u32 s16, s0, 0xfffc0080
	s_addc_u32 s17, s1, -1
	s_add_i32 s46, 0, 0x10000
	s_cmp_eq_u32 s45, 12
	s_cselect_b32 s21, s23, s17
	s_cselect_b32 s20, s41, s16
	v_add_u32_e32 v156, s46, v159
	s_cselect_b32 s17, s19, s44
	s_cselect_b32 s16, s42, s43
	s_add_i32 s48, 0, 0x14000
	ds_read_b128 v[130:133], v156
	ds_read_b128 v[134:137], v156 offset:1024
	ds_read_b128 v[152:155], v156 offset:2048
	ds_read_b128 v[162:165], v156 offset:3072
	v_add_u32_e32 v156, s48, v159
	ds_read_b128 v[166:169], v156
	ds_read_b128 v[170:173], v156 offset:1024
	ds_read_b128 v[174:177], v156 offset:2048
	ds_read_b128 v[196:199], v156 offset:3072
	v_lshl_add_u64 v[156:157], s[0:1], 0, v[148:149]
	s_add_i32 m0, s39, 0xc000
	ds_read_b128 v[212:215], v161
	ds_read_b128 v[216:219], v161 offset:1024
	ds_read_b128 v[220:223], v161 offset:2048
	ds_read_b128 v[224:227], v161 offset:3072
	ds_read_b128 v[228:231], v161 offset:4096
	ds_read_b128 v[232:235], v161 offset:5120
	ds_read_b128 v[236:239], v161 offset:6144
	ds_read_b128 v[240:243], v161 offset:7168
	global_load_lds_dwordx4 v[156:157], off
	v_lshl_add_u64 v[156:157], s[0:1], 0, v[150:151]
	s_add_i32 m0, s39, 0xe000
	s_nop 0
	global_load_lds_dwordx4 v[156:157], off
	s_waitcnt vmcnt(8)
	s_waitcnt lgkmcnt(0)
	s_setprio 1
	s_barrier
	v_mfma_f32_16x16x32_bf16 v[126:129], v[130:133], v[212:215], v[126:129]
	v_mfma_f32_16x16x32_bf16 v[122:125], v[152:155], v[212:215], v[122:125]
	v_mfma_f32_16x16x32_bf16 v[114:117], v[130:133], v[220:223], v[114:117]
	v_mfma_f32_16x16x32_bf16 v[106:109], v[152:155], v[220:223], v[106:109]
	v_mfma_f32_16x16x32_bf16 v[98:101], v[130:133], v[228:231], v[98:101]
	v_mfma_f32_16x16x32_bf16 v[90:93], v[152:155], v[228:231], v[90:93]
	v_mfma_f32_16x16x32_bf16 v[82:85], v[130:133], v[236:239], v[82:85]
	v_mfma_f32_16x16x32_bf16 v[74:77], v[152:155], v[236:239], v[74:77]
	v_mfma_f32_16x16x32_bf16 v[126:129], v[134:137], v[216:219], v[126:129]
	v_mfma_f32_16x16x32_bf16 v[122:125], v[162:165], v[216:219], v[122:125]
	v_mfma_f32_16x16x32_bf16 v[114:117], v[134:137], v[224:227], v[114:117]
	v_mfma_f32_16x16x32_bf16 v[106:109], v[162:165], v[224:227], v[106:109]
	v_mfma_f32_16x16x32_bf16 v[98:101], v[134:137], v[232:235], v[98:101]
	v_mfma_f32_16x16x32_bf16 v[90:93], v[162:165], v[232:235], v[90:93]
	v_mfma_f32_16x16x32_bf16 v[82:85], v[134:137], v[240:243], v[82:85]
	v_mfma_f32_16x16x32_bf16 v[74:77], v[162:165], v[240:243], v[74:77]
	v_mfma_f32_16x16x32_bf16 v[118:121], v[166:169], v[212:215], v[118:121]
	v_mfma_f32_16x16x32_bf16 v[110:113], v[174:177], v[212:215], v[110:113]
	v_mfma_f32_16x16x32_bf16 v[102:105], v[166:169], v[220:223], v[102:105]
	v_mfma_f32_16x16x32_bf16 v[94:97], v[174:177], v[220:223], v[94:97]
	v_mfma_f32_16x16x32_bf16 v[86:89], v[166:169], v[228:231], v[86:89]
	v_mfma_f32_16x16x32_bf16 v[78:81], v[174:177], v[228:231], v[78:81]
	v_mfma_f32_16x16x32_bf16 v[70:73], v[166:169], v[236:239], v[70:73]
	v_mfma_f32_16x16x32_bf16 v[66:69], v[174:177], v[236:239], v[66:69]
	v_mfma_f32_16x16x32_bf16 v[118:121], v[170:173], v[216:219], v[118:121]
	v_mfma_f32_16x16x32_bf16 v[110:113], v[196:199], v[216:219], v[110:113]
	v_mfma_f32_16x16x32_bf16 v[102:105], v[170:173], v[224:227], v[102:105]
	v_mfma_f32_16x16x32_bf16 v[94:97], v[196:199], v[224:227], v[94:97]
	v_mfma_f32_16x16x32_bf16 v[86:89], v[170:173], v[232:235], v[86:89]
	v_mfma_f32_16x16x32_bf16 v[78:81], v[196:199], v[232:235], v[78:81]
	v_mfma_f32_16x16x32_bf16 v[70:73], v[170:173], v[240:243], v[70:73]
	v_mfma_f32_16x16x32_bf16 v[66:69], v[196:199], v[240:243], v[66:69]
	s_barrier
	s_setprio 0
	s_add_i32 s46, s46, s38
	v_lshl_add_u64 v[156:157], s[16:17], 0, v[178:179]
	s_mov_b32 m0, s46
	ds_read_b128 v[212:215], v161 offset:16384
	ds_read_b128 v[216:219], v161 offset:17408
	ds_read_b128 v[220:223], v161 offset:18432
	ds_read_b128 v[224:227], v161 offset:19456
	ds_read_b128 v[228:231], v161 offset:20480
	ds_read_b128 v[232:235], v161 offset:21504
	ds_read_b128 v[236:239], v161 offset:22528
	ds_read_b128 v[240:243], v161 offset:23552
	global_load_lds_dwordx4 v[156:157], off
	s_add_i32 m0, s46, 0x2000
	s_add_u32 s46, s16, 0x40000
	v_lshl_add_u64 v[244:245], s[16:17], 0, v[138:139]
	s_addc_u32 s47, s17, 0
	s_add_i32 s48, s48, s38
	global_load_lds_dwordx4 v[244:245], off
	v_lshl_add_u64 v[246:247], s[46:47], 0, v[178:179]
	s_mov_b32 m0, s48
	v_lshl_add_u64 v[248:249], s[20:21], 0, v[140:141]
	global_load_lds_dwordx4 v[246:247], off
	v_lshl_add_u64 v[246:247], s[46:47], 0, v[138:139]
	s_add_i32 m0, s48, 0x2000
	s_nop 0
	global_load_lds_dwordx4 v[246:247], off
	v_lshl_add_u64 v[246:247], s[20:21], 0, v[142:143]
	s_mov_b32 m0, s39
	s_nop 0
	global_load_lds_dwordx4 v[246:247], off
	s_mov_b32 m0, s60
	s_nop 0
	global_load_lds_dwordx4 v[248:249], off
	s_waitcnt vmcnt(8)
	s_waitcnt lgkmcnt(0)
	s_setprio 1
	s_barrier
	v_mfma_f32_16x16x32_bf16 v[62:65], v[130:133], v[212:215], v[62:65]
	v_mfma_f32_16x16x32_bf16 v[58:61], v[152:155], v[212:215], v[58:61]
	v_mfma_f32_16x16x32_bf16 v[50:53], v[130:133], v[220:223], v[50:53]
	v_mfma_f32_16x16x32_bf16 v[42:45], v[152:155], v[220:223], v[42:45]
	v_mfma_f32_16x16x32_bf16 v[34:37], v[130:133], v[228:231], v[34:37]
	v_mfma_f32_16x16x32_bf16 v[26:29], v[152:155], v[228:231], v[26:29]
	v_mfma_f32_16x16x32_bf16 v[18:21], v[130:133], v[236:239], v[18:21]
	v_mfma_f32_16x16x32_bf16 v[10:13], v[152:155], v[236:239], v[10:13]
	v_mfma_f32_16x16x32_bf16 v[62:65], v[134:137], v[216:219], v[62:65]
	v_mfma_f32_16x16x32_bf16 v[58:61], v[162:165], v[216:219], v[58:61]
	v_mfma_f32_16x16x32_bf16 v[50:53], v[134:137], v[224:227], v[50:53]
	v_mfma_f32_16x16x32_bf16 v[42:45], v[162:165], v[224:227], v[42:45]
	v_mfma_f32_16x16x32_bf16 v[34:37], v[134:137], v[232:235], v[34:37]
	v_mfma_f32_16x16x32_bf16 v[26:29], v[162:165], v[232:235], v[26:29]
	v_mfma_f32_16x16x32_bf16 v[18:21], v[134:137], v[240:243], v[18:21]
	v_mfma_f32_16x16x32_bf16 v[10:13], v[162:165], v[240:243], v[10:13]
	v_mfma_f32_16x16x32_bf16 v[54:57], v[166:169], v[212:215], v[54:57]
	v_mfma_f32_16x16x32_bf16 v[46:49], v[174:177], v[212:215], v[46:49]
	v_mfma_f32_16x16x32_bf16 v[38:41], v[166:169], v[220:223], v[38:41]
	v_mfma_f32_16x16x32_bf16 v[30:33], v[174:177], v[220:223], v[30:33]
	v_mfma_f32_16x16x32_bf16 v[22:25], v[166:169], v[228:231], v[22:25]
	v_mfma_f32_16x16x32_bf16 v[14:17], v[174:177], v[228:231], v[14:17]
	v_mfma_f32_16x16x32_bf16 v[6:9], v[166:169], v[236:239], v[6:9]
	v_mfma_f32_16x16x32_bf16 v[2:5], v[174:177], v[236:239], v[2:5]
	v_mfma_f32_16x16x32_bf16 v[54:57], v[170:173], v[216:219], v[54:57]
	v_mfma_f32_16x16x32_bf16 v[46:49], v[196:199], v[216:219], v[46:49]
	v_mfma_f32_16x16x32_bf16 v[38:41], v[170:173], v[224:227], v[38:41]
	v_mfma_f32_16x16x32_bf16 v[30:33], v[196:199], v[224:227], v[30:33]
	v_mfma_f32_16x16x32_bf16 v[22:25], v[170:173], v[232:235], v[22:25]
	v_mfma_f32_16x16x32_bf16 v[14:17], v[196:199], v[232:235], v[14:17]
	v_mfma_f32_16x16x32_bf16 v[6:9], v[170:173], v[240:243], v[6:9]
	v_mfma_f32_16x16x32_bf16 v[2:5], v[196:199], v[240:243], v[2:5]
	s_barrier
	s_setprio 0
	s_add_i32 s46, 0, 0x18000
	s_add_i32 s47, 0, 0x1c000
	v_add_u32_e32 v162, s46, v159
	v_add_u32_e32 v185, s47, v159
	ds_read_b128 v[130:133], v162
	ds_read_b128 v[134:137], v162 offset:1024
	ds_read_b128 v[152:155], v162 offset:2048
	ds_read_b128 v[162:165], v162 offset:3072
	ds_read_b128 v[166:169], v185
	ds_read_b128 v[170:173], v185 offset:1024
	ds_read_b128 v[174:177], v185 offset:2048
	ds_read_b128 v[196:199], v185 offset:3072
	s_add_u32 s20, s20, 0x40000
	s_addc_u32 s21, s21, 0
	s_mov_b32 m0, s61
	v_lshl_add_u64 v[250:251], s[20:21], 0, v[142:143]
	ds_read_b128 v[212:215], v161 offset:32768
	ds_read_b128 v[216:219], v161 offset:33792
	ds_read_b128 v[220:223], v161 offset:34816
	ds_read_b128 v[224:227], v161 offset:35840
	ds_read_b128 v[228:231], v161 offset:36864
	ds_read_b128 v[232:235], v161 offset:37888
	ds_read_b128 v[236:239], v161 offset:38912
	ds_read_b128 v[240:243], v161 offset:39936
	global_load_lds_dwordx4 v[250:251], off
	v_lshl_add_u64 v[250:251], s[20:21], 0, v[140:141]
	s_mov_b32 m0, s88
	s_nop 0
	global_load_lds_dwordx4 v[250:251], off
	s_waitcnt vmcnt(8)
	s_waitcnt lgkmcnt(0)
	s_setprio 1
	s_barrier
	v_mfma_f32_16x16x32_bf16 v[126:129], v[130:133], v[212:215], v[126:129]
	v_mfma_f32_16x16x32_bf16 v[122:125], v[152:155], v[212:215], v[122:125]
	v_mfma_f32_16x16x32_bf16 v[114:117], v[130:133], v[220:223], v[114:117]
	v_mfma_f32_16x16x32_bf16 v[106:109], v[152:155], v[220:223], v[106:109]
	v_mfma_f32_16x16x32_bf16 v[98:101], v[130:133], v[228:231], v[98:101]
	v_mfma_f32_16x16x32_bf16 v[90:93], v[152:155], v[228:231], v[90:93]
	v_mfma_f32_16x16x32_bf16 v[82:85], v[130:133], v[236:239], v[82:85]
	v_mfma_f32_16x16x32_bf16 v[74:77], v[152:155], v[236:239], v[74:77]
	v_mfma_f32_16x16x32_bf16 v[126:129], v[134:137], v[216:219], v[126:129]
	v_mfma_f32_16x16x32_bf16 v[122:125], v[162:165], v[216:219], v[122:125]
	v_mfma_f32_16x16x32_bf16 v[114:117], v[134:137], v[224:227], v[114:117]
	v_mfma_f32_16x16x32_bf16 v[106:109], v[162:165], v[224:227], v[106:109]
	v_mfma_f32_16x16x32_bf16 v[98:101], v[134:137], v[232:235], v[98:101]
	v_mfma_f32_16x16x32_bf16 v[90:93], v[162:165], v[232:235], v[90:93]
	v_mfma_f32_16x16x32_bf16 v[82:85], v[134:137], v[240:243], v[82:85]
	v_mfma_f32_16x16x32_bf16 v[74:77], v[162:165], v[240:243], v[74:77]
	v_mfma_f32_16x16x32_bf16 v[118:121], v[166:169], v[212:215], v[118:121]
	v_mfma_f32_16x16x32_bf16 v[110:113], v[174:177], v[212:215], v[110:113]
	v_mfma_f32_16x16x32_bf16 v[102:105], v[166:169], v[220:223], v[102:105]
	v_mfma_f32_16x16x32_bf16 v[94:97], v[174:177], v[220:223], v[94:97]
	v_mfma_f32_16x16x32_bf16 v[86:89], v[166:169], v[228:231], v[86:89]
	v_mfma_f32_16x16x32_bf16 v[78:81], v[174:177], v[228:231], v[78:81]
	v_mfma_f32_16x16x32_bf16 v[70:73], v[166:169], v[236:239], v[70:73]
	v_mfma_f32_16x16x32_bf16 v[66:69], v[174:177], v[236:239], v[66:69]
	v_mfma_f32_16x16x32_bf16 v[118:121], v[170:173], v[216:219], v[118:121]
	v_mfma_f32_16x16x32_bf16 v[110:113], v[196:199], v[216:219], v[110:113]
	v_mfma_f32_16x16x32_bf16 v[102:105], v[170:173], v[224:227], v[102:105]
	v_mfma_f32_16x16x32_bf16 v[94:97], v[196:199], v[224:227], v[94:97]
	v_mfma_f32_16x16x32_bf16 v[86:89], v[170:173], v[232:235], v[86:89]
	v_mfma_f32_16x16x32_bf16 v[78:81], v[196:199], v[232:235], v[78:81]
	v_mfma_f32_16x16x32_bf16 v[70:73], v[170:173], v[240:243], v[70:73]
	v_mfma_f32_16x16x32_bf16 v[66:69], v[196:199], v[240:243], v[66:69]
	s_barrier
	s_setprio 0
	s_add_i32 s20, s46, s38
	v_lshl_add_u64 v[156:157], v[156:157], 0, s[90:91]
	s_mov_b32 m0, s20
	ds_read_b128 v[212:215], v161 offset:49152
	ds_read_b128 v[216:219], v161 offset:50176
	ds_read_b128 v[220:223], v161 offset:51200
	ds_read_b128 v[224:227], v161 offset:52224
	ds_read_b128 v[228:231], v161 offset:53248
	ds_read_b128 v[232:235], v161 offset:54272
	ds_read_b128 v[236:239], v161 offset:55296
	ds_read_b128 v[240:243], v161 offset:56320
	global_load_lds_dwordx4 v[156:157], off
	s_add_i32 m0, s20, 0x2000
	s_add_u32 s16, s16, 0x40080
	v_lshl_add_u64 v[156:157], v[244:245], 0, s[90:91]
	s_addc_u32 s17, s17, 0
	s_add_i32 s20, s47, s38
	global_load_lds_dwordx4 v[156:157], off
	v_lshl_add_u64 v[156:157], s[16:17], 0, v[178:179]
	s_mov_b32 m0, s20
	s_nop 0
	global_load_lds_dwordx4 v[156:157], off
	v_lshl_add_u64 v[156:157], s[16:17], 0, v[138:139]
	s_add_i32 m0, s20, 0x2000
	s_nop 0
	global_load_lds_dwordx4 v[156:157], off
	v_lshl_add_u64 v[156:157], v[246:247], 0, s[90:91]
	s_mov_b32 m0, s82
	s_nop 0
	global_load_lds_dwordx4 v[156:157], off
	v_lshl_add_u64 v[156:157], v[248:249], 0, s[90:91]
	s_mov_b32 m0, s89
	s_nop 0
	global_load_lds_dwordx4 v[156:157], off
	s_waitcnt vmcnt(8)
	s_waitcnt lgkmcnt(0)
	s_setprio 1
	s_barrier
	v_mfma_f32_16x16x32_bf16 v[62:65], v[130:133], v[212:215], v[62:65]
	v_mfma_f32_16x16x32_bf16 v[58:61], v[152:155], v[212:215], v[58:61]
	v_mfma_f32_16x16x32_bf16 v[50:53], v[130:133], v[220:223], v[50:53]
	v_mfma_f32_16x16x32_bf16 v[42:45], v[152:155], v[220:223], v[42:45]
	v_mfma_f32_16x16x32_bf16 v[34:37], v[130:133], v[228:231], v[34:37]
	v_mfma_f32_16x16x32_bf16 v[26:29], v[152:155], v[228:231], v[26:29]
	v_mfma_f32_16x16x32_bf16 v[18:21], v[130:133], v[236:239], v[18:21]
	v_mfma_f32_16x16x32_bf16 v[10:13], v[152:155], v[236:239], v[10:13]
	v_mfma_f32_16x16x32_bf16 v[62:65], v[134:137], v[216:219], v[62:65]
	v_mfma_f32_16x16x32_bf16 v[58:61], v[162:165], v[216:219], v[58:61]
	v_mfma_f32_16x16x32_bf16 v[50:53], v[134:137], v[224:227], v[50:53]
	v_mfma_f32_16x16x32_bf16 v[42:45], v[162:165], v[224:227], v[42:45]
	v_mfma_f32_16x16x32_bf16 v[34:37], v[134:137], v[232:235], v[34:37]
	v_mfma_f32_16x16x32_bf16 v[26:29], v[162:165], v[232:235], v[26:29]
	v_mfma_f32_16x16x32_bf16 v[18:21], v[134:137], v[240:243], v[18:21]
	v_mfma_f32_16x16x32_bf16 v[10:13], v[162:165], v[240:243], v[10:13]
	v_mfma_f32_16x16x32_bf16 v[54:57], v[166:169], v[212:215], v[54:57]
	v_mfma_f32_16x16x32_bf16 v[46:49], v[174:177], v[212:215], v[46:49]
	v_mfma_f32_16x16x32_bf16 v[38:41], v[166:169], v[220:223], v[38:41]
	v_mfma_f32_16x16x32_bf16 v[30:33], v[174:177], v[220:223], v[30:33]
	v_mfma_f32_16x16x32_bf16 v[22:25], v[166:169], v[228:231], v[22:25]
	v_mfma_f32_16x16x32_bf16 v[14:17], v[174:177], v[228:231], v[14:17]
	v_mfma_f32_16x16x32_bf16 v[6:9], v[166:169], v[236:239], v[6:9]
	v_mfma_f32_16x16x32_bf16 v[2:5], v[174:177], v[236:239], v[2:5]
	v_mfma_f32_16x16x32_bf16 v[54:57], v[170:173], v[216:219], v[54:57]
	v_mfma_f32_16x16x32_bf16 v[46:49], v[196:199], v[216:219], v[46:49]
	v_mfma_f32_16x16x32_bf16 v[38:41], v[170:173], v[224:227], v[38:41]
	v_mfma_f32_16x16x32_bf16 v[30:33], v[196:199], v[224:227], v[30:33]
	v_mfma_f32_16x16x32_bf16 v[22:25], v[170:173], v[232:235], v[22:25]
	v_mfma_f32_16x16x32_bf16 v[14:17], v[196:199], v[232:235], v[14:17]
	v_mfma_f32_16x16x32_bf16 v[6:9], v[170:173], v[240:243], v[6:9]
	v_mfma_f32_16x16x32_bf16 v[2:5], v[196:199], v[240:243], v[2:5]
	s_barrier
	s_setprio 0
	s_add_i32 s45, s45, 2
	s_add_u32 s0, s0, 0x100
	s_addc_u32 s1, s1, 0
	s_add_u32 s43, s43, 0x100
	s_addc_u32 s44, s44, 0
	s_cmp_gt_u32 s45, 13
	s_cbranch_scc0 .LBB0_355
	s_and_b64 vcc, exec, s[12:13]
	s_cbranch_vccnz .LBB0_360
	v_lshl_add_u32 v152, s40, 8, v158
	s_cmp_gt_i32 s33, 13
	s_mov_b64 s[0:1], -1
	s_cbranch_scc1 .LBB0_361

.LBB0_756:
	s_add_u32 s14, s34, s60
	s_addc_u32 s15, s35, s61
	s_add_u32 s14, s14, 0x100
	s_addc_u32 s15, s15, 0
	s_add_u32 s50, s45, s60
	s_addc_u32 s51, s84, s61
	s_add_i32 s62, 0, 0x10000
	s_cmpk_eq_i32 s60, 0x700
	s_cselect_b32 s93, s1, s15
	s_cselect_b32 s92, s46, s14
	v_add_u32_e32 v147, s62, v145
	s_cselect_b32 s15, s47, s51
	s_cselect_b32 s14, s48, s50
	s_add_i32 s63, 0, 0x14000
	ds_read_b128 v[148:151], v147
	ds_read_b128 v[152:155], v147 offset:1024
	ds_read_b128 v[156:159], v147 offset:2048
	ds_read_b128 v[160:163], v147 offset:3072
	v_add_u32_e32 v147, s63, v145
	ds_read_b128 v[170:173], v147
	ds_read_b128 v[174:177], v147 offset:1024
	ds_read_b128 v[196:199], v147 offset:2048
	ds_read_b128 v[212:215], v147 offset:3072
	v_lshl_add_u64 v[164:165], v[140:141], 0, s[60:61]
	s_add_i32 m0, s33, 0xc000
	ds_read_b128 v[216:219], v146
	ds_read_b128 v[220:223], v146 offset:1024
	ds_read_b128 v[224:227], v146 offset:2048
	ds_read_b128 v[228:231], v146 offset:3072
	ds_read_b128 v[232:235], v146 offset:4096
	ds_read_b128 v[236:239], v146 offset:5120
	ds_read_b128 v[240:243], v146 offset:6144
	ds_read_b128 v[244:247], v146 offset:7168
	global_load_lds_dwordx4 v[164:165], off
	v_lshl_add_u64 v[164:165], v[142:143], 0, s[60:61]
	s_add_i32 m0, s33, 0xe000
	s_nop 0
	global_load_lds_dwordx4 v[164:165], off
	s_waitcnt vmcnt(8)
	s_waitcnt lgkmcnt(0)
	s_setprio 1
	s_barrier
	v_mfma_f32_16x16x32_bf16 v[14:17], v[148:151], v[216:219], v[14:17]
	v_mfma_f32_16x16x32_bf16 v[10:13], v[156:159], v[216:219], v[10:13]
	v_mfma_f32_16x16x32_bf16 v[38:41], v[148:151], v[224:227], v[38:41]
	v_mfma_f32_16x16x32_bf16 v[34:37], v[156:159], v[224:227], v[34:37]
	v_mfma_f32_16x16x32_bf16 v[62:65], v[148:151], v[232:235], v[62:65]
	v_mfma_f32_16x16x32_bf16 v[58:61], v[156:159], v[232:235], v[58:61]
	v_mfma_f32_16x16x32_bf16 v[86:89], v[148:151], v[240:243], v[86:89]
	v_mfma_f32_16x16x32_bf16 v[82:85], v[156:159], v[240:243], v[82:85]
	v_mfma_f32_16x16x32_bf16 v[14:17], v[152:155], v[220:223], v[14:17]
	v_mfma_f32_16x16x32_bf16 v[10:13], v[160:163], v[220:223], v[10:13]
	v_mfma_f32_16x16x32_bf16 v[38:41], v[152:155], v[228:231], v[38:41]
	v_mfma_f32_16x16x32_bf16 v[34:37], v[160:163], v[228:231], v[34:37]
	v_mfma_f32_16x16x32_bf16 v[62:65], v[152:155], v[236:239], v[62:65]
	v_mfma_f32_16x16x32_bf16 v[58:61], v[160:163], v[236:239], v[58:61]
	v_mfma_f32_16x16x32_bf16 v[86:89], v[152:155], v[244:247], v[86:89]
	v_mfma_f32_16x16x32_bf16 v[82:85], v[160:163], v[244:247], v[82:85]
	v_mfma_f32_16x16x32_bf16 v[22:25], v[170:173], v[216:219], v[22:25]
	v_mfma_f32_16x16x32_bf16 v[18:21], v[196:199], v[216:219], v[18:21]
	v_mfma_f32_16x16x32_bf16 v[46:49], v[170:173], v[224:227], v[46:49]
	v_mfma_f32_16x16x32_bf16 v[42:45], v[196:199], v[224:227], v[42:45]
	v_mfma_f32_16x16x32_bf16 v[70:73], v[170:173], v[232:235], v[70:73]
	v_mfma_f32_16x16x32_bf16 v[66:69], v[196:199], v[232:235], v[66:69]
	v_mfma_f32_16x16x32_bf16 v[94:97], v[170:173], v[240:243], v[94:97]
	v_mfma_f32_16x16x32_bf16 v[90:93], v[196:199], v[240:243], v[90:93]
	v_mfma_f32_16x16x32_bf16 v[22:25], v[174:177], v[220:223], v[22:25]
	v_mfma_f32_16x16x32_bf16 v[18:21], v[212:215], v[220:223], v[18:21]
	v_mfma_f32_16x16x32_bf16 v[46:49], v[174:177], v[228:231], v[46:49]
	v_mfma_f32_16x16x32_bf16 v[42:45], v[212:215], v[228:231], v[42:45]
	v_mfma_f32_16x16x32_bf16 v[70:73], v[174:177], v[236:239], v[70:73]
	v_mfma_f32_16x16x32_bf16 v[66:69], v[212:215], v[236:239], v[66:69]
	v_mfma_f32_16x16x32_bf16 v[94:97], v[174:177], v[244:247], v[94:97]
	v_mfma_f32_16x16x32_bf16 v[90:93], v[212:215], v[244:247], v[90:93]
	s_barrier
	s_setprio 0
	s_add_i32 s50, s62, s13
	v_lshl_add_u64 v[164:165], s[14:15], 0, v[178:179]
	s_mov_b32 m0, s50
	ds_read_b128 v[216:219], v146 offset:16384
	ds_read_b128 v[220:223], v146 offset:17408
	ds_read_b128 v[224:227], v146 offset:18432
	ds_read_b128 v[228:231], v146 offset:19456
	ds_read_b128 v[232:235], v146 offset:20480
	ds_read_b128 v[236:239], v146 offset:21504
	ds_read_b128 v[240:243], v146 offset:22528
	ds_read_b128 v[244:247], v146 offset:23552
	global_load_lds_dwordx4 v[164:165], off
	s_add_i32 m0, s50, 0x2000
	s_add_u32 s50, s14, 0x40000
	v_lshl_add_u64 v[202:203], s[14:15], 0, v[130:131]
	s_addc_u32 s51, s15, 0
	s_add_i32 s62, s63, s13
	global_load_lds_dwordx4 v[202:203], off
	v_lshl_add_u64 v[206:207], s[50:51], 0, v[178:179]
	s_mov_b32 m0, s62
	v_lshl_add_u64 v[248:249], s[92:93], 0, v[132:133]
	global_load_lds_dwordx4 v[206:207], off
	v_lshl_add_u64 v[206:207], s[50:51], 0, v[130:131]
	s_add_i32 m0, s62, 0x2000
	s_nop 0
	global_load_lds_dwordx4 v[206:207], off
	v_lshl_add_u64 v[206:207], s[92:93], 0, v[134:135]
	s_mov_b32 m0, s33
	s_nop 0
	global_load_lds_dwordx4 v[206:207], off
	s_mov_b32 m0, s28
	s_nop 0
	global_load_lds_dwordx4 v[248:249], off
	s_waitcnt vmcnt(8)
	s_waitcnt lgkmcnt(0)
	s_setprio 1
	s_barrier
	v_mfma_f32_16x16x32_bf16 v[118:121], v[148:151], v[216:219], v[118:121]
	v_mfma_f32_16x16x32_bf16 v[114:117], v[156:159], v[216:219], v[114:117]
	v_mfma_f32_16x16x32_bf16 v[110:113], v[148:151], v[224:227], v[110:113]
	v_mfma_f32_16x16x32_bf16 v[106:109], v[156:159], v[224:227], v[106:109]
	v_mfma_f32_16x16x32_bf16 v[78:81], v[148:151], v[232:235], v[78:81]
	v_mfma_f32_16x16x32_bf16 v[74:77], v[156:159], v[232:235], v[74:77]
	v_mfma_f32_16x16x32_bf16 v[30:33], v[148:151], v[240:243], v[30:33]
	v_mfma_f32_16x16x32_bf16 v[26:29], v[156:159], v[240:243], v[26:29]
	v_mfma_f32_16x16x32_bf16 v[118:121], v[152:155], v[220:223], v[118:121]
	v_mfma_f32_16x16x32_bf16 v[114:117], v[160:163], v[220:223], v[114:117]
	v_mfma_f32_16x16x32_bf16 v[110:113], v[152:155], v[228:231], v[110:113]
	v_mfma_f32_16x16x32_bf16 v[106:109], v[160:163], v[228:231], v[106:109]
	v_mfma_f32_16x16x32_bf16 v[78:81], v[152:155], v[236:239], v[78:81]
	v_mfma_f32_16x16x32_bf16 v[74:77], v[160:163], v[236:239], v[74:77]
	v_mfma_f32_16x16x32_bf16 v[30:33], v[152:155], v[244:247], v[30:33]
	v_mfma_f32_16x16x32_bf16 v[26:29], v[160:163], v[244:247], v[26:29]
	v_mfma_f32_16x16x32_bf16 v[126:129], v[170:173], v[216:219], v[126:129]
	v_mfma_f32_16x16x32_bf16 v[122:125], v[196:199], v[216:219], v[122:125]
	v_mfma_f32_16x16x32_bf16 v[102:105], v[170:173], v[224:227], v[102:105]
	v_mfma_f32_16x16x32_bf16 v[98:101], v[196:199], v[224:227], v[98:101]
	v_mfma_f32_16x16x32_bf16 v[54:57], v[170:173], v[232:235], v[54:57]
	v_mfma_f32_16x16x32_bf16 v[50:53], v[196:199], v[232:235], v[50:53]
	v_mfma_f32_16x16x32_bf16 v[6:9], v[170:173], v[240:243], v[6:9]
	v_mfma_f32_16x16x32_bf16 v[2:5], v[196:199], v[240:243], v[2:5]
	v_mfma_f32_16x16x32_bf16 v[126:129], v[174:177], v[220:223], v[126:129]
	v_mfma_f32_16x16x32_bf16 v[122:125], v[212:215], v[220:223], v[122:125]
	v_mfma_f32_16x16x32_bf16 v[102:105], v[174:177], v[228:231], v[102:105]
	v_mfma_f32_16x16x32_bf16 v[98:101], v[212:215], v[228:231], v[98:101]
	v_mfma_f32_16x16x32_bf16 v[54:57], v[174:177], v[236:239], v[54:57]
	v_mfma_f32_16x16x32_bf16 v[50:53], v[212:215], v[236:239], v[50:53]
	v_mfma_f32_16x16x32_bf16 v[6:9], v[174:177], v[244:247], v[6:9]
	v_mfma_f32_16x16x32_bf16 v[2:5], v[212:215], v[244:247], v[2:5]
	s_barrier
	s_setprio 0
	s_add_i32 s62, 0, 0x18000
	v_add_u32_e32 v147, s62, v145
	s_add_i32 s63, 0, 0x1c000
	ds_read_b128 v[148:151], v147
	ds_read_b128 v[152:155], v147 offset:1024
	ds_read_b128 v[156:159], v147 offset:2048
	ds_read_b128 v[160:163], v147 offset:3072
	v_add_u32_e32 v147, s63, v145
	ds_read_b128 v[170:173], v147
	ds_read_b128 v[174:177], v147 offset:1024
	ds_read_b128 v[196:199], v147 offset:2048
	ds_read_b128 v[212:215], v147 offset:3072
	s_add_u32 s50, s92, 0x40000
	s_addc_u32 s51, s93, 0
	s_mov_b32 m0, s82
	v_lshl_add_u64 v[250:251], s[50:51], 0, v[134:135]
	ds_read_b128 v[216:219], v146 offset:32768
	ds_read_b128 v[220:223], v146 offset:33792
	ds_read_b128 v[224:227], v146 offset:34816
	ds_read_b128 v[228:231], v146 offset:35840
	ds_read_b128 v[232:235], v146 offset:36864
	ds_read_b128 v[236:239], v146 offset:37888
	ds_read_b128 v[240:243], v146 offset:38912
	ds_read_b128 v[244:247], v146 offset:39936
	global_load_lds_dwordx4 v[250:251], off
	v_lshl_add_u64 v[250:251], s[50:51], 0, v[132:133]
	s_mov_b32 m0, s40
	s_nop 0
	global_load_lds_dwordx4 v[250:251], off
	s_waitcnt vmcnt(8)
	s_waitcnt lgkmcnt(0)
	s_setprio 1
	s_barrier
	v_mfma_f32_16x16x32_bf16 v[14:17], v[148:151], v[216:219], v[14:17]
	v_mfma_f32_16x16x32_bf16 v[10:13], v[156:159], v[216:219], v[10:13]
	v_mfma_f32_16x16x32_bf16 v[38:41], v[148:151], v[224:227], v[38:41]
	v_mfma_f32_16x16x32_bf16 v[34:37], v[156:159], v[224:227], v[34:37]
	v_mfma_f32_16x16x32_bf16 v[62:65], v[148:151], v[232:235], v[62:65]
	v_mfma_f32_16x16x32_bf16 v[58:61], v[156:159], v[232:235], v[58:61]
	v_mfma_f32_16x16x32_bf16 v[86:89], v[148:151], v[240:243], v[86:89]
	v_mfma_f32_16x16x32_bf16 v[82:85], v[156:159], v[240:243], v[82:85]
	v_mfma_f32_16x16x32_bf16 v[14:17], v[152:155], v[220:223], v[14:17]
	v_mfma_f32_16x16x32_bf16 v[10:13], v[160:163], v[220:223], v[10:13]
	v_mfma_f32_16x16x32_bf16 v[38:41], v[152:155], v[228:231], v[38:41]
	v_mfma_f32_16x16x32_bf16 v[34:37], v[160:163], v[228:231], v[34:37]
	v_mfma_f32_16x16x32_bf16 v[62:65], v[152:155], v[236:239], v[62:65]
	v_mfma_f32_16x16x32_bf16 v[58:61], v[160:163], v[236:239], v[58:61]
	v_mfma_f32_16x16x32_bf16 v[86:89], v[152:155], v[244:247], v[86:89]
	v_mfma_f32_16x16x32_bf16 v[82:85], v[160:163], v[244:247], v[82:85]
	v_mfma_f32_16x16x32_bf16 v[22:25], v[170:173], v[216:219], v[22:25]
	v_mfma_f32_16x16x32_bf16 v[18:21], v[196:199], v[216:219], v[18:21]
	v_mfma_f32_16x16x32_bf16 v[46:49], v[170:173], v[224:227], v[46:49]
	v_mfma_f32_16x16x32_bf16 v[42:45], v[196:199], v[224:227], v[42:45]
	v_mfma_f32_16x16x32_bf16 v[70:73], v[170:173], v[232:235], v[70:73]
	v_mfma_f32_16x16x32_bf16 v[66:69], v[196:199], v[232:235], v[66:69]
	v_mfma_f32_16x16x32_bf16 v[94:97], v[170:173], v[240:243], v[94:97]
	v_mfma_f32_16x16x32_bf16 v[90:93], v[196:199], v[240:243], v[90:93]
	v_mfma_f32_16x16x32_bf16 v[22:25], v[174:177], v[220:223], v[22:25]
	v_mfma_f32_16x16x32_bf16 v[18:21], v[212:215], v[220:223], v[18:21]
	v_mfma_f32_16x16x32_bf16 v[46:49], v[174:177], v[228:231], v[46:49]
	v_mfma_f32_16x16x32_bf16 v[42:45], v[212:215], v[228:231], v[42:45]
	v_mfma_f32_16x16x32_bf16 v[70:73], v[174:177], v[236:239], v[70:73]
	v_mfma_f32_16x16x32_bf16 v[66:69], v[212:215], v[236:239], v[66:69]
	v_mfma_f32_16x16x32_bf16 v[94:97], v[174:177], v[244:247], v[94:97]
	v_mfma_f32_16x16x32_bf16 v[90:93], v[212:215], v[244:247], v[90:93]
	s_barrier
	s_setprio 0
	s_add_i32 s50, s62, s13
	v_lshl_add_u64 v[164:165], v[164:165], 0, s[90:91]
	s_mov_b32 m0, s50
	ds_read_b128 v[216:219], v146 offset:49152
	ds_read_b128 v[220:223], v146 offset:50176
	ds_read_b128 v[224:227], v146 offset:51200
	ds_read_b128 v[228:231], v146 offset:52224
	ds_read_b128 v[232:235], v146 offset:53248
	ds_read_b128 v[236:239], v146 offset:54272
	ds_read_b128 v[240:243], v146 offset:55296
	ds_read_b128 v[244:247], v146 offset:56320
	global_load_lds_dwordx4 v[164:165], off
	s_add_i32 m0, s50, 0x2000
	s_add_u32 s14, s14, 0x40080
	v_lshl_add_u64 v[164:165], v[202:203], 0, s[90:91]
	s_addc_u32 s15, s15, 0
	s_add_i32 s50, s63, s13
	global_load_lds_dwordx4 v[164:165], off
	v_lshl_add_u64 v[164:165], s[14:15], 0, v[178:179]
	s_mov_b32 m0, s50
	s_nop 0
	global_load_lds_dwordx4 v[164:165], off
	v_lshl_add_u64 v[164:165], s[14:15], 0, v[130:131]
	s_add_i32 m0, s50, 0x2000
	s_nop 0
	global_load_lds_dwordx4 v[164:165], off
	v_lshl_add_u64 v[164:165], v[206:207], 0, s[90:91]
	s_mov_b32 m0, s41
	s_nop 0
	global_load_lds_dwordx4 v[164:165], off
	v_lshl_add_u64 v[164:165], v[248:249], 0, s[90:91]
	s_mov_b32 m0, s42
	s_nop 0
	global_load_lds_dwordx4 v[164:165], off
	s_waitcnt vmcnt(8)
	s_waitcnt lgkmcnt(0)
	s_setprio 1
	s_barrier
	v_mfma_f32_16x16x32_bf16 v[118:121], v[148:151], v[216:219], v[118:121]
	v_mfma_f32_16x16x32_bf16 v[114:117], v[156:159], v[216:219], v[114:117]
	v_mfma_f32_16x16x32_bf16 v[110:113], v[148:151], v[224:227], v[110:113]
	v_mfma_f32_16x16x32_bf16 v[106:109], v[156:159], v[224:227], v[106:109]
	v_mfma_f32_16x16x32_bf16 v[78:81], v[148:151], v[232:235], v[78:81]
	v_mfma_f32_16x16x32_bf16 v[74:77], v[156:159], v[232:235], v[74:77]
	v_mfma_f32_16x16x32_bf16 v[30:33], v[148:151], v[240:243], v[30:33]
	v_mfma_f32_16x16x32_bf16 v[26:29], v[156:159], v[240:243], v[26:29]
	v_mfma_f32_16x16x32_bf16 v[118:121], v[152:155], v[220:223], v[118:121]
	v_mfma_f32_16x16x32_bf16 v[114:117], v[160:163], v[220:223], v[114:117]
	v_mfma_f32_16x16x32_bf16 v[110:113], v[152:155], v[228:231], v[110:113]
	v_mfma_f32_16x16x32_bf16 v[106:109], v[160:163], v[228:231], v[106:109]
	v_mfma_f32_16x16x32_bf16 v[78:81], v[152:155], v[236:239], v[78:81]
	v_mfma_f32_16x16x32_bf16 v[74:77], v[160:163], v[236:239], v[74:77]
	v_mfma_f32_16x16x32_bf16 v[30:33], v[152:155], v[244:247], v[30:33]
	v_mfma_f32_16x16x32_bf16 v[26:29], v[160:163], v[244:247], v[26:29]
	v_mfma_f32_16x16x32_bf16 v[126:129], v[170:173], v[216:219], v[126:129]
	v_mfma_f32_16x16x32_bf16 v[122:125], v[196:199], v[216:219], v[122:125]
	v_mfma_f32_16x16x32_bf16 v[102:105], v[170:173], v[224:227], v[102:105]
	v_mfma_f32_16x16x32_bf16 v[98:101], v[196:199], v[224:227], v[98:101]
	v_mfma_f32_16x16x32_bf16 v[54:57], v[170:173], v[232:235], v[54:57]
	v_mfma_f32_16x16x32_bf16 v[50:53], v[196:199], v[232:235], v[50:53]
	v_mfma_f32_16x16x32_bf16 v[6:9], v[170:173], v[240:243], v[6:9]
	v_mfma_f32_16x16x32_bf16 v[2:5], v[196:199], v[240:243], v[2:5]
	v_mfma_f32_16x16x32_bf16 v[126:129], v[174:177], v[220:223], v[126:129]
	v_mfma_f32_16x16x32_bf16 v[122:125], v[212:215], v[220:223], v[122:125]
	v_mfma_f32_16x16x32_bf16 v[102:105], v[174:177], v[228:231], v[102:105]
	v_mfma_f32_16x16x32_bf16 v[98:101], v[212:215], v[228:231], v[98:101]
	v_mfma_f32_16x16x32_bf16 v[54:57], v[174:177], v[236:239], v[54:57]
	v_mfma_f32_16x16x32_bf16 v[50:53], v[212:215], v[236:239], v[50:53]
	v_mfma_f32_16x16x32_bf16 v[6:9], v[174:177], v[244:247], v[6:9]
	v_mfma_f32_16x16x32_bf16 v[2:5], v[212:215], v[244:247], v[2:5]
	s_barrier
	s_setprio 0
	s_add_i32 s49, s49, 2
	s_add_u32 s60, s60, 0x100
	s_addc_u32 s61, s61, 0
	s_cmp_gt_u32 s49, 13
	s_cbranch_scc0 .LBB0_756
	s_add_u32 s14, s45, 0xffffff00
	s_addc_u32 s15, s84, -1
	s_andn2_b64 vcc, exec, s[6:7]
	s_cbranch_vccnz .LBB0_759
	v_mov_b32_e32 v2, 0
	s_mov_b32 s8, s88
	s_mov_b32 s11, s0
	s_mov_b64 s[34:35], s[16:17]
	s_mov_b32 s43, s44
	v_mov_b32_e32 v3, v2
	v_mov_b32_e32 v4, v2
	v_mov_b32_e32 v5, v2
	v_mov_b32_e32 v6, v2
	v_mov_b32_e32 v7, v2
	v_mov_b32_e32 v8, v2
	v_mov_b32_e32 v9, v2
	v_mov_b32_e32 v50, v2
	v_mov_b32_e32 v51, v2
	v_mov_b32_e32 v52, v2
	v_mov_b32_e32 v53, v2
	v_mov_b32_e32 v54, v2
	v_mov_b32_e32 v55, v2
	v_mov_b32_e32 v56, v2
	v_mov_b32_e32 v57, v2
	v_mov_b32_e32 v98, v2
	v_mov_b32_e32 v99, v2
	v_mov_b32_e32 v100, v2
	v_mov_b32_e32 v101, v2
	v_mov_b32_e32 v102, v2
	v_mov_b32_e32 v103, v2
	v_mov_b32_e32 v104, v2
	v_mov_b32_e32 v105, v2
	v_mov_b32_e32 v122, v2
	v_mov_b32_e32 v123, v2
	v_mov_b32_e32 v124, v2
	v_mov_b32_e32 v125, v2
	v_mov_b32_e32 v126, v2
	v_mov_b32_e32 v127, v2
	v_mov_b32_e32 v128, v2
	v_mov_b32_e32 v129, v2
	v_mov_b32_e32 v26, v2
	v_mov_b32_e32 v27, v2
	v_mov_b32_e32 v28, v2
	v_mov_b32_e32 v29, v2
	v_mov_b32_e32 v30, v2
	v_mov_b32_e32 v31, v2
	v_mov_b32_e32 v32, v2
	v_mov_b32_e32 v33, v2
	v_mov_b32_e32 v74, v2
	v_mov_b32_e32 v75, v2
	v_mov_b32_e32 v76, v2
	v_mov_b32_e32 v77, v2
	v_mov_b32_e32 v78, v2
	v_mov_b32_e32 v79, v2
	v_mov_b32_e32 v80, v2
	v_mov_b32_e32 v81, v2
	v_mov_b32_e32 v106, v2
	v_mov_b32_e32 v107, v2
	v_mov_b32_e32 v108, v2
	v_mov_b32_e32 v109, v2
	v_mov_b32_e32 v110, v2
	v_mov_b32_e32 v111, v2
	v_mov_b32_e32 v112, v2
	v_mov_b32_e32 v113, v2
	v_mov_b32_e32 v114, v2
	v_mov_b32_e32 v115, v2
	v_mov_b32_e32 v116, v2
	v_mov_b32_e32 v117, v2
	v_mov_b32_e32 v118, v2
	v_mov_b32_e32 v119, v2
	v_mov_b32_e32 v120, v2
	v_mov_b32_e32 v121, v2
	v_mov_b32_e32 v90, v2
	v_mov_b32_e32 v91, v2
	v_mov_b32_e32 v92, v2
	v_mov_b32_e32 v93, v2
	v_mov_b32_e32 v94, v2
	v_mov_b32_e32 v95, v2
	v_mov_b32_e32 v96, v2
	v_mov_b32_e32 v97, v2
	v_mov_b32_e32 v66, v2
	v_mov_b32_e32 v67, v2
	v_mov_b32_e32 v68, v2
	v_mov_b32_e32 v69, v2
	v_mov_b32_e32 v70, v2
	v_mov_b32_e32 v71, v2
	v_mov_b32_e32 v72, v2
	v_mov_b32_e32 v73, v2
	v_mov_b32_e32 v42, v2
	v_mov_b32_e32 v43, v2
	v_mov_b32_e32 v44, v2
	v_mov_b32_e32 v45, v2
	v_mov_b32_e32 v46, v2
	v_mov_b32_e32 v47, v2
	v_mov_b32_e32 v48, v2
	v_mov_b32_e32 v49, v2
	v_mov_b32_e32 v18, v2
	v_mov_b32_e32 v19, v2
	v_mov_b32_e32 v20, v2
	v_mov_b32_e32 v21, v2
	v_mov_b32_e32 v22, v2
	v_mov_b32_e32 v23, v2
	v_mov_b32_e32 v24, v2
	v_mov_b32_e32 v25, v2
	v_mov_b32_e32 v82, v2
	v_mov_b32_e32 v83, v2
	v_mov_b32_e32 v84, v2
	v_mov_b32_e32 v85, v2
	v_mov_b32_e32 v86, v2
	v_mov_b32_e32 v87, v2
	v_mov_b32_e32 v88, v2
	v_mov_b32_e32 v89, v2
	v_mov_b32_e32 v58, v2
	v_mov_b32_e32 v59, v2
	v_mov_b32_e32 v60, v2
	v_mov_b32_e32 v61, v2
	v_mov_b32_e32 v62, v2
	v_mov_b32_e32 v63, v2
	v_mov_b32_e32 v64, v2
	v_mov_b32_e32 v65, v2
	v_mov_b32_e32 v34, v2
	v_mov_b32_e32 v35, v2
	v_mov_b32_e32 v36, v2
	v_mov_b32_e32 v37, v2
	v_mov_b32_e32 v38, v2
	v_mov_b32_e32 v39, v2
	v_mov_b32_e32 v40, v2
	v_mov_b32_e32 v41, v2
	v_mov_b32_e32 v10, v2
	v_mov_b32_e32 v11, v2
	v_mov_b32_e32 v12, v2
	v_mov_b32_e32 v13, v2
	v_mov_b32_e32 v14, v2
	v_mov_b32_e32 v15, v2
	v_mov_b32_e32 v16, v2
	v_mov_b32_e32 v17, v2
	s_branch .LBB0_760

.LBB0_818:
	s_add_u32 s14, s88, s60
	s_addc_u32 s15, s89, s61
	s_add_u32 s14, s14, 0x100
	s_addc_u32 s15, s15, 0
	s_add_u32 s50, s45, s60
	s_addc_u32 s51, s96, s61
	s_add_i32 s62, 0, 0x10000
	s_cmpk_eq_i32 s60, 0x700
	s_cselect_b32 s95, s1, s15
	s_cselect_b32 s94, s46, s14
	s_cselect_b32 s15, s47, s51
	s_cselect_b32 s14, s48, s50
	s_add_i32 s63, 0, 0x14000
	v_add_u32_e32 v158, s62, v144
	v_add_u32_e32 v166, s63, v144
	ds_read_b128 v[146:149], v158
	ds_read_b128 v[150:153], v158 offset:1024
	ds_read_b128 v[154:157], v158 offset:2048
	ds_read_b128 v[158:161], v158 offset:3072
	ds_read_b128 v[162:165], v166
	ds_read_b128 v[172:175], v166 offset:1024
	ds_read_b128 v[196:199], v166 offset:2048
	ds_read_b128 v[212:215], v166 offset:3072
	v_lshl_add_u64 v[166:167], v[140:141], 0, s[60:61]
	s_add_i32 m0, s28, 0xc000
	ds_read_b128 v[216:219], v145
	ds_read_b128 v[220:223], v145 offset:1024
	ds_read_b128 v[224:227], v145 offset:2048
	ds_read_b128 v[228:231], v145 offset:3072
	ds_read_b128 v[232:235], v145 offset:4096
	ds_read_b128 v[236:239], v145 offset:5120
	ds_read_b128 v[240:243], v145 offset:6144
	ds_read_b128 v[244:247], v145 offset:7168
	global_load_lds_dwordx4 v[166:167], off
	v_lshl_add_u64 v[166:167], v[142:143], 0, s[60:61]
	s_add_i32 m0, s28, 0xe000
	s_nop 0
	global_load_lds_dwordx4 v[166:167], off
	s_waitcnt vmcnt(8)
	s_waitcnt lgkmcnt(0)
	s_setprio 1
	s_barrier
	v_mfma_f32_16x16x32_bf16 v[126:129], v[146:149], v[216:219], v[126:129]
	v_mfma_f32_16x16x32_bf16 v[122:125], v[154:157], v[216:219], v[122:125]
	v_mfma_f32_16x16x32_bf16 v[110:113], v[146:149], v[224:227], v[110:113]
	v_mfma_f32_16x16x32_bf16 v[106:109], v[154:157], v[224:227], v[106:109]
	v_mfma_f32_16x16x32_bf16 v[94:97], v[146:149], v[232:235], v[94:97]
	v_mfma_f32_16x16x32_bf16 v[90:93], v[154:157], v[232:235], v[90:93]
	v_mfma_f32_16x16x32_bf16 v[78:81], v[146:149], v[240:243], v[78:81]
	v_mfma_f32_16x16x32_bf16 v[74:77], v[154:157], v[240:243], v[74:77]
	v_mfma_f32_16x16x32_bf16 v[126:129], v[150:153], v[220:223], v[126:129]
	v_mfma_f32_16x16x32_bf16 v[122:125], v[158:161], v[220:223], v[122:125]
	v_mfma_f32_16x16x32_bf16 v[110:113], v[150:153], v[228:231], v[110:113]
	v_mfma_f32_16x16x32_bf16 v[106:109], v[158:161], v[228:231], v[106:109]
	v_mfma_f32_16x16x32_bf16 v[94:97], v[150:153], v[236:239], v[94:97]
	v_mfma_f32_16x16x32_bf16 v[90:93], v[158:161], v[236:239], v[90:93]
	v_mfma_f32_16x16x32_bf16 v[78:81], v[150:153], v[244:247], v[78:81]
	v_mfma_f32_16x16x32_bf16 v[74:77], v[158:161], v[244:247], v[74:77]
	v_mfma_f32_16x16x32_bf16 v[118:121], v[162:165], v[216:219], v[118:121]
	v_mfma_f32_16x16x32_bf16 v[114:117], v[196:199], v[216:219], v[114:117]
	v_mfma_f32_16x16x32_bf16 v[102:105], v[162:165], v[224:227], v[102:105]
	v_mfma_f32_16x16x32_bf16 v[98:101], v[196:199], v[224:227], v[98:101]
	v_mfma_f32_16x16x32_bf16 v[86:89], v[162:165], v[232:235], v[86:89]
	v_mfma_f32_16x16x32_bf16 v[82:85], v[196:199], v[232:235], v[82:85]
	v_mfma_f32_16x16x32_bf16 v[70:73], v[162:165], v[240:243], v[70:73]
	v_mfma_f32_16x16x32_bf16 v[66:69], v[196:199], v[240:243], v[66:69]
	v_mfma_f32_16x16x32_bf16 v[118:121], v[172:175], v[220:223], v[118:121]
	v_mfma_f32_16x16x32_bf16 v[114:117], v[212:215], v[220:223], v[114:117]
	v_mfma_f32_16x16x32_bf16 v[102:105], v[172:175], v[228:231], v[102:105]
	v_mfma_f32_16x16x32_bf16 v[98:101], v[212:215], v[228:231], v[98:101]
	v_mfma_f32_16x16x32_bf16 v[86:89], v[172:175], v[236:239], v[86:89]
	v_mfma_f32_16x16x32_bf16 v[82:85], v[212:215], v[236:239], v[82:85]
	v_mfma_f32_16x16x32_bf16 v[70:73], v[172:175], v[244:247], v[70:73]
	v_mfma_f32_16x16x32_bf16 v[66:69], v[212:215], v[244:247], v[66:69]
	s_barrier
	s_setprio 0
	s_add_i32 s50, s62, s33
	v_lshl_add_u64 v[166:167], s[14:15], 0, v[178:179]
	s_mov_b32 m0, s50
	ds_read_b128 v[216:219], v145 offset:16384
	ds_read_b128 v[220:223], v145 offset:17408
	ds_read_b128 v[224:227], v145 offset:18432
	ds_read_b128 v[228:231], v145 offset:19456
	ds_read_b128 v[232:235], v145 offset:20480
	ds_read_b128 v[236:239], v145 offset:21504
	ds_read_b128 v[240:243], v145 offset:22528
	ds_read_b128 v[244:247], v145 offset:23552
	global_load_lds_dwordx4 v[166:167], off
	s_add_i32 m0, s50, 0x2000
	s_add_u32 s50, s14, 0x40000
	v_lshl_add_u64 v[176:177], s[14:15], 0, v[130:131]
	s_addc_u32 s51, s15, 0
	s_add_i32 s62, s63, s33
	global_load_lds_dwordx4 v[176:177], off
	v_lshl_add_u64 v[202:203], s[50:51], 0, v[178:179]
	s_mov_b32 m0, s62
	v_lshl_add_u64 v[206:207], s[94:95], 0, v[132:133]
	global_load_lds_dwordx4 v[202:203], off
	v_lshl_add_u64 v[202:203], s[50:51], 0, v[130:131]
	s_add_i32 m0, s62, 0x2000
	s_nop 0
	global_load_lds_dwordx4 v[202:203], off
	v_lshl_add_u64 v[202:203], s[94:95], 0, v[134:135]
	s_mov_b32 m0, s28
	s_nop 0
	global_load_lds_dwordx4 v[202:203], off
	s_mov_b32 m0, s29
	s_nop 0
	global_load_lds_dwordx4 v[206:207], off
	s_waitcnt vmcnt(8)
	s_waitcnt lgkmcnt(0)
	s_setprio 1
	s_barrier
	v_mfma_f32_16x16x32_bf16 v[62:65], v[146:149], v[216:219], v[62:65]
	v_mfma_f32_16x16x32_bf16 v[58:61], v[154:157], v[216:219], v[58:61]
	v_mfma_f32_16x16x32_bf16 v[46:49], v[146:149], v[224:227], v[46:49]
	v_mfma_f32_16x16x32_bf16 v[42:45], v[154:157], v[224:227], v[42:45]
	v_mfma_f32_16x16x32_bf16 v[30:33], v[146:149], v[232:235], v[30:33]
	v_mfma_f32_16x16x32_bf16 v[26:29], v[154:157], v[232:235], v[26:29]
	v_mfma_f32_16x16x32_bf16 v[14:17], v[146:149], v[240:243], v[14:17]
	v_mfma_f32_16x16x32_bf16 v[10:13], v[154:157], v[240:243], v[10:13]
	v_mfma_f32_16x16x32_bf16 v[62:65], v[150:153], v[220:223], v[62:65]
	v_mfma_f32_16x16x32_bf16 v[58:61], v[158:161], v[220:223], v[58:61]
	v_mfma_f32_16x16x32_bf16 v[46:49], v[150:153], v[228:231], v[46:49]
	v_mfma_f32_16x16x32_bf16 v[42:45], v[158:161], v[228:231], v[42:45]
	v_mfma_f32_16x16x32_bf16 v[30:33], v[150:153], v[236:239], v[30:33]
	v_mfma_f32_16x16x32_bf16 v[26:29], v[158:161], v[236:239], v[26:29]
	v_mfma_f32_16x16x32_bf16 v[14:17], v[150:153], v[244:247], v[14:17]
	v_mfma_f32_16x16x32_bf16 v[10:13], v[158:161], v[244:247], v[10:13]
	v_mfma_f32_16x16x32_bf16 v[54:57], v[162:165], v[216:219], v[54:57]
	v_mfma_f32_16x16x32_bf16 v[50:53], v[196:199], v[216:219], v[50:53]
	v_mfma_f32_16x16x32_bf16 v[38:41], v[162:165], v[224:227], v[38:41]
	v_mfma_f32_16x16x32_bf16 v[34:37], v[196:199], v[224:227], v[34:37]
	v_mfma_f32_16x16x32_bf16 v[22:25], v[162:165], v[232:235], v[22:25]
	v_mfma_f32_16x16x32_bf16 v[18:21], v[196:199], v[232:235], v[18:21]
	v_mfma_f32_16x16x32_bf16 v[6:9], v[162:165], v[240:243], v[6:9]
	v_mfma_f32_16x16x32_bf16 v[2:5], v[196:199], v[240:243], v[2:5]
	v_mfma_f32_16x16x32_bf16 v[54:57], v[172:175], v[220:223], v[54:57]
	v_mfma_f32_16x16x32_bf16 v[50:53], v[212:215], v[220:223], v[50:53]
	v_mfma_f32_16x16x32_bf16 v[38:41], v[172:175], v[228:231], v[38:41]
	v_mfma_f32_16x16x32_bf16 v[34:37], v[212:215], v[228:231], v[34:37]
	v_mfma_f32_16x16x32_bf16 v[22:25], v[172:175], v[236:239], v[22:25]
	v_mfma_f32_16x16x32_bf16 v[18:21], v[212:215], v[236:239], v[18:21]
	v_mfma_f32_16x16x32_bf16 v[6:9], v[172:175], v[244:247], v[6:9]
	v_mfma_f32_16x16x32_bf16 v[2:5], v[212:215], v[244:247], v[2:5]
	s_barrier
	s_setprio 0
	s_add_i32 s62, 0, 0x18000
	s_add_i32 s63, 0, 0x1c000
	v_add_u32_e32 v158, s62, v144
	v_add_u32_e32 v185, s63, v144
	ds_read_b128 v[146:149], v158
	ds_read_b128 v[150:153], v158 offset:1024
	ds_read_b128 v[154:157], v158 offset:2048
	ds_read_b128 v[158:161], v158 offset:3072
	ds_read_b128 v[162:165], v185
	ds_read_b128 v[172:175], v185 offset:1024
	ds_read_b128 v[196:199], v185 offset:2048
	ds_read_b128 v[212:215], v185 offset:3072
	s_add_u32 s50, s94, 0x40000
	s_addc_u32 s51, s95, 0
	s_mov_b32 m0, s84
	v_lshl_add_u64 v[248:249], s[50:51], 0, v[134:135]
	ds_read_b128 v[216:219], v145 offset:32768
	ds_read_b128 v[220:223], v145 offset:33792
	ds_read_b128 v[224:227], v145 offset:34816
	ds_read_b128 v[228:231], v145 offset:35840
	ds_read_b128 v[232:235], v145 offset:36864
	ds_read_b128 v[236:239], v145 offset:37888
	ds_read_b128 v[240:243], v145 offset:38912
	ds_read_b128 v[244:247], v145 offset:39936
	global_load_lds_dwordx4 v[248:249], off
	v_lshl_add_u64 v[248:249], s[50:51], 0, v[132:133]
	s_mov_b32 m0, s40
	s_nop 0
	global_load_lds_dwordx4 v[248:249], off
	s_waitcnt vmcnt(8)
	s_waitcnt lgkmcnt(0)
	s_setprio 1
	s_barrier
	v_mfma_f32_16x16x32_bf16 v[126:129], v[146:149], v[216:219], v[126:129]
	v_mfma_f32_16x16x32_bf16 v[122:125], v[154:157], v[216:219], v[122:125]
	v_mfma_f32_16x16x32_bf16 v[110:113], v[146:149], v[224:227], v[110:113]
	v_mfma_f32_16x16x32_bf16 v[106:109], v[154:157], v[224:227], v[106:109]
	v_mfma_f32_16x16x32_bf16 v[94:97], v[146:149], v[232:235], v[94:97]
	v_mfma_f32_16x16x32_bf16 v[90:93], v[154:157], v[232:235], v[90:93]
	v_mfma_f32_16x16x32_bf16 v[78:81], v[146:149], v[240:243], v[78:81]
	v_mfma_f32_16x16x32_bf16 v[74:77], v[154:157], v[240:243], v[74:77]
	v_mfma_f32_16x16x32_bf16 v[126:129], v[150:153], v[220:223], v[126:129]
	v_mfma_f32_16x16x32_bf16 v[122:125], v[158:161], v[220:223], v[122:125]
	v_mfma_f32_16x16x32_bf16 v[110:113], v[150:153], v[228:231], v[110:113]
	v_mfma_f32_16x16x32_bf16 v[106:109], v[158:161], v[228:231], v[106:109]
	v_mfma_f32_16x16x32_bf16 v[94:97], v[150:153], v[236:239], v[94:97]
	v_mfma_f32_16x16x32_bf16 v[90:93], v[158:161], v[236:239], v[90:93]
	v_mfma_f32_16x16x32_bf16 v[78:81], v[150:153], v[244:247], v[78:81]
	v_mfma_f32_16x16x32_bf16 v[74:77], v[158:161], v[244:247], v[74:77]
	v_mfma_f32_16x16x32_bf16 v[118:121], v[162:165], v[216:219], v[118:121]
	v_mfma_f32_16x16x32_bf16 v[114:117], v[196:199], v[216:219], v[114:117]
	v_mfma_f32_16x16x32_bf16 v[102:105], v[162:165], v[224:227], v[102:105]
	v_mfma_f32_16x16x32_bf16 v[98:101], v[196:199], v[224:227], v[98:101]
	v_mfma_f32_16x16x32_bf16 v[86:89], v[162:165], v[232:235], v[86:89]
	v_mfma_f32_16x16x32_bf16 v[82:85], v[196:199], v[232:235], v[82:85]
	v_mfma_f32_16x16x32_bf16 v[70:73], v[162:165], v[240:243], v[70:73]
	v_mfma_f32_16x16x32_bf16 v[66:69], v[196:199], v[240:243], v[66:69]
	v_mfma_f32_16x16x32_bf16 v[118:121], v[172:175], v[220:223], v[118:121]
	v_mfma_f32_16x16x32_bf16 v[114:117], v[212:215], v[220:223], v[114:117]
	v_mfma_f32_16x16x32_bf16 v[102:105], v[172:175], v[228:231], v[102:105]
	v_mfma_f32_16x16x32_bf16 v[98:101], v[212:215], v[228:231], v[98:101]
	v_mfma_f32_16x16x32_bf16 v[86:89], v[172:175], v[236:239], v[86:89]
	v_mfma_f32_16x16x32_bf16 v[82:85], v[212:215], v[236:239], v[82:85]
	v_mfma_f32_16x16x32_bf16 v[70:73], v[172:175], v[244:247], v[70:73]
	v_mfma_f32_16x16x32_bf16 v[66:69], v[212:215], v[244:247], v[66:69]
	s_barrier
	s_setprio 0
	s_add_i32 s50, s62, s33
	v_lshl_add_u64 v[166:167], v[166:167], 0, s[90:91]
	s_mov_b32 m0, s50
	ds_read_b128 v[216:219], v145 offset:49152
	ds_read_b128 v[220:223], v145 offset:50176
	ds_read_b128 v[224:227], v145 offset:51200
	ds_read_b128 v[228:231], v145 offset:52224
	ds_read_b128 v[232:235], v145 offset:53248
	ds_read_b128 v[236:239], v145 offset:54272
	ds_read_b128 v[240:243], v145 offset:55296
	ds_read_b128 v[244:247], v145 offset:56320
	global_load_lds_dwordx4 v[166:167], off
	s_add_i32 m0, s50, 0x2000
	s_add_u32 s14, s14, 0x40080
	v_lshl_add_u64 v[166:167], v[176:177], 0, s[90:91]
	s_addc_u32 s15, s15, 0
	s_add_i32 s50, s63, s33
	global_load_lds_dwordx4 v[166:167], off
	v_lshl_add_u64 v[166:167], s[14:15], 0, v[178:179]
	s_mov_b32 m0, s50
	s_nop 0
	global_load_lds_dwordx4 v[166:167], off
	v_lshl_add_u64 v[166:167], s[14:15], 0, v[130:131]
	s_add_i32 m0, s50, 0x2000
	s_nop 0
	global_load_lds_dwordx4 v[166:167], off
	v_lshl_add_u64 v[166:167], v[202:203], 0, s[90:91]
	s_mov_b32 m0, s85
	s_nop 0
	global_load_lds_dwordx4 v[166:167], off
	v_lshl_add_u64 v[166:167], v[206:207], 0, s[90:91]
	s_mov_b32 m0, s42
	s_nop 0
	global_load_lds_dwordx4 v[166:167], off
	s_waitcnt vmcnt(8)
	s_waitcnt lgkmcnt(0)
	s_setprio 1
	s_barrier
	v_mfma_f32_16x16x32_bf16 v[62:65], v[146:149], v[216:219], v[62:65]
	v_mfma_f32_16x16x32_bf16 v[58:61], v[154:157], v[216:219], v[58:61]
	v_mfma_f32_16x16x32_bf16 v[46:49], v[146:149], v[224:227], v[46:49]
	v_mfma_f32_16x16x32_bf16 v[42:45], v[154:157], v[224:227], v[42:45]
	v_mfma_f32_16x16x32_bf16 v[30:33], v[146:149], v[232:235], v[30:33]
	v_mfma_f32_16x16x32_bf16 v[26:29], v[154:157], v[232:235], v[26:29]
	v_mfma_f32_16x16x32_bf16 v[14:17], v[146:149], v[240:243], v[14:17]
	v_mfma_f32_16x16x32_bf16 v[10:13], v[154:157], v[240:243], v[10:13]
	v_mfma_f32_16x16x32_bf16 v[62:65], v[150:153], v[220:223], v[62:65]
	v_mfma_f32_16x16x32_bf16 v[58:61], v[158:161], v[220:223], v[58:61]
	v_mfma_f32_16x16x32_bf16 v[46:49], v[150:153], v[228:231], v[46:49]
	v_mfma_f32_16x16x32_bf16 v[42:45], v[158:161], v[228:231], v[42:45]
	v_mfma_f32_16x16x32_bf16 v[30:33], v[150:153], v[236:239], v[30:33]
	v_mfma_f32_16x16x32_bf16 v[26:29], v[158:161], v[236:239], v[26:29]
	v_mfma_f32_16x16x32_bf16 v[14:17], v[150:153], v[244:247], v[14:17]
	v_mfma_f32_16x16x32_bf16 v[10:13], v[158:161], v[244:247], v[10:13]
	v_mfma_f32_16x16x32_bf16 v[54:57], v[162:165], v[216:219], v[54:57]
	v_mfma_f32_16x16x32_bf16 v[50:53], v[196:199], v[216:219], v[50:53]
	v_mfma_f32_16x16x32_bf16 v[38:41], v[162:165], v[224:227], v[38:41]
	v_mfma_f32_16x16x32_bf16 v[34:37], v[196:199], v[224:227], v[34:37]
	v_mfma_f32_16x16x32_bf16 v[22:25], v[162:165], v[232:235], v[22:25]
	v_mfma_f32_16x16x32_bf16 v[18:21], v[196:199], v[232:235], v[18:21]
	v_mfma_f32_16x16x32_bf16 v[6:9], v[162:165], v[240:243], v[6:9]
	v_mfma_f32_16x16x32_bf16 v[2:5], v[196:199], v[240:243], v[2:5]
	v_mfma_f32_16x16x32_bf16 v[54:57], v[172:175], v[220:223], v[54:57]
	v_mfma_f32_16x16x32_bf16 v[50:53], v[212:215], v[220:223], v[50:53]
	v_mfma_f32_16x16x32_bf16 v[38:41], v[172:175], v[228:231], v[38:41]
	v_mfma_f32_16x16x32_bf16 v[34:37], v[212:215], v[228:231], v[34:37]
	v_mfma_f32_16x16x32_bf16 v[22:25], v[172:175], v[236:239], v[22:25]
	v_mfma_f32_16x16x32_bf16 v[18:21], v[212:215], v[236:239], v[18:21]
	v_mfma_f32_16x16x32_bf16 v[6:9], v[172:175], v[244:247], v[6:9]
	v_mfma_f32_16x16x32_bf16 v[2:5], v[212:215], v[244:247], v[2:5]
	s_barrier
	s_setprio 0
	s_add_i32 s49, s49, 2
	s_add_u32 s60, s60, 0x100
	s_addc_u32 s61, s61, 0
	s_cmp_gt_u32 s49, 13
	s_cbranch_scc0 .LBB0_818
	s_add_u32 s14, s45, 0xffffff00
	s_addc_u32 s15, s96, -1
	s_andn2_b64 vcc, exec, s[6:7]
	s_cbranch_vccnz .LBB0_821
	v_mov_b32_e32 v2, 0
	s_mov_b32 s8, s92
	s_mov_b32 s82, s0
	s_mov_b64 s[88:89], s[16:17]
	s_mov_b32 s43, s44
	v_mov_b32_e32 v3, v2
	v_mov_b32_e32 v4, v2
	v_mov_b32_e32 v5, v2
	v_mov_b32_e32 v6, v2
	v_mov_b32_e32 v7, v2
	v_mov_b32_e32 v8, v2
	v_mov_b32_e32 v9, v2
	v_mov_b32_e32 v18, v2
	v_mov_b32_e32 v19, v2
	v_mov_b32_e32 v20, v2
	v_mov_b32_e32 v21, v2
	v_mov_b32_e32 v22, v2
	v_mov_b32_e32 v23, v2
	v_mov_b32_e32 v24, v2
	v_mov_b32_e32 v25, v2
	v_mov_b32_e32 v34, v2
	v_mov_b32_e32 v35, v2
	v_mov_b32_e32 v36, v2
	v_mov_b32_e32 v37, v2
	v_mov_b32_e32 v38, v2
	v_mov_b32_e32 v39, v2
	v_mov_b32_e32 v40, v2
	v_mov_b32_e32 v41, v2
	v_mov_b32_e32 v50, v2
	v_mov_b32_e32 v51, v2
	v_mov_b32_e32 v52, v2
	v_mov_b32_e32 v53, v2
	v_mov_b32_e32 v54, v2
	v_mov_b32_e32 v55, v2
	v_mov_b32_e32 v56, v2
	v_mov_b32_e32 v57, v2
	v_mov_b32_e32 v10, v2
	v_mov_b32_e32 v11, v2
	v_mov_b32_e32 v12, v2
	v_mov_b32_e32 v13, v2
	v_mov_b32_e32 v14, v2
	v_mov_b32_e32 v15, v2
	v_mov_b32_e32 v16, v2
	v_mov_b32_e32 v17, v2
	v_mov_b32_e32 v26, v2
	v_mov_b32_e32 v27, v2
	v_mov_b32_e32 v28, v2
	v_mov_b32_e32 v29, v2
	v_mov_b32_e32 v30, v2
	v_mov_b32_e32 v31, v2
	v_mov_b32_e32 v32, v2
	v_mov_b32_e32 v33, v2
	v_mov_b32_e32 v42, v2
	v_mov_b32_e32 v43, v2
	v_mov_b32_e32 v44, v2
	v_mov_b32_e32 v45, v2
	v_mov_b32_e32 v46, v2
	v_mov_b32_e32 v47, v2
	v_mov_b32_e32 v48, v2
	v_mov_b32_e32 v49, v2
	v_mov_b32_e32 v58, v2
	v_mov_b32_e32 v59, v2
	v_mov_b32_e32 v60, v2
	v_mov_b32_e32 v61, v2
	v_mov_b32_e32 v62, v2
	v_mov_b32_e32 v63, v2
	v_mov_b32_e32 v64, v2
	v_mov_b32_e32 v65, v2
	v_mov_b32_e32 v66, v2
	v_mov_b32_e32 v67, v2
	v_mov_b32_e32 v68, v2
	v_mov_b32_e32 v69, v2
	v_mov_b32_e32 v70, v2
	v_mov_b32_e32 v71, v2
	v_mov_b32_e32 v72, v2
	v_mov_b32_e32 v73, v2
	v_mov_b32_e32 v82, v2
	v_mov_b32_e32 v83, v2
	v_mov_b32_e32 v84, v2
	v_mov_b32_e32 v85, v2
	v_mov_b32_e32 v86, v2
	v_mov_b32_e32 v87, v2
	v_mov_b32_e32 v88, v2
	v_mov_b32_e32 v89, v2
	v_mov_b32_e32 v98, v2
	v_mov_b32_e32 v99, v2
	v_mov_b32_e32 v100, v2
	v_mov_b32_e32 v101, v2
	v_mov_b32_e32 v102, v2
	v_mov_b32_e32 v103, v2
	v_mov_b32_e32 v104, v2
	v_mov_b32_e32 v105, v2
	v_mov_b32_e32 v114, v2
	v_mov_b32_e32 v115, v2
	v_mov_b32_e32 v116, v2
	v_mov_b32_e32 v117, v2
	v_mov_b32_e32 v118, v2
	v_mov_b32_e32 v119, v2
	v_mov_b32_e32 v120, v2
	v_mov_b32_e32 v121, v2
	v_mov_b32_e32 v74, v2
	v_mov_b32_e32 v75, v2
	v_mov_b32_e32 v76, v2
	v_mov_b32_e32 v77, v2
	v_mov_b32_e32 v78, v2
	v_mov_b32_e32 v79, v2
	v_mov_b32_e32 v80, v2
	v_mov_b32_e32 v81, v2
	v_mov_b32_e32 v90, v2
	v_mov_b32_e32 v91, v2
	v_mov_b32_e32 v92, v2
	v_mov_b32_e32 v93, v2
	v_mov_b32_e32 v94, v2
	v_mov_b32_e32 v95, v2
	v_mov_b32_e32 v96, v2
	v_mov_b32_e32 v97, v2
	v_mov_b32_e32 v106, v2
	v_mov_b32_e32 v107, v2
	v_mov_b32_e32 v108, v2
	v_mov_b32_e32 v109, v2
	v_mov_b32_e32 v110, v2
	v_mov_b32_e32 v111, v2
	v_mov_b32_e32 v112, v2
	v_mov_b32_e32 v113, v2
	v_mov_b32_e32 v122, v2
	v_mov_b32_e32 v123, v2
	v_mov_b32_e32 v124, v2
	v_mov_b32_e32 v125, v2
	v_mov_b32_e32 v126, v2
	v_mov_b32_e32 v127, v2
	v_mov_b32_e32 v128, v2
	v_mov_b32_e32 v129, v2
	s_movk_i32 s96, 0x80
	s_andn2_b64 vcc, exec, s[4:5]
	s_cbranch_vccnz .LBB0_822
	s_branch .LBB0_823

.LBB0_931:
	s_add_u32 s14, s16, 0xfffc0080
	s_addc_u32 s15, s17, -1
	s_add_i32 s49, 0, 0x10000
	s_cmp_eq_u32 s48, 12
	s_cselect_b32 s29, s21, s15
	s_cselect_b32 s28, s44, s14
	v_add_u32_e32 v140, s49, v144
	s_cselect_b32 s15, s19, s47
	s_cselect_b32 s14, s45, s46
	s_add_i32 s60, 0, 0x14000
	ds_read_b128 v[148:151], v140
	ds_read_b128 v[152:155], v140 offset:1024
	ds_read_b128 v[156:159], v140 offset:2048
	ds_read_b128 v[160:163], v140 offset:3072
	v_add_u32_e32 v140, s60, v144
	ds_read_b128 v[164:167], v140
	ds_read_b128 v[168:171], v140 offset:1024
	ds_read_b128 v[172:175], v140 offset:2048
	ds_read_b128 v[196:199], v140 offset:3072
	v_lshl_add_u64 v[142:143], s[16:17], 0, v[136:137]
	s_add_i32 m0, s33, 0xc000
	ds_read_b128 v[212:215], v146
	ds_read_b128 v[216:219], v146 offset:1024
	ds_read_b128 v[220:223], v146 offset:2048
	ds_read_b128 v[224:227], v146 offset:3072
	ds_read_b128 v[228:231], v146 offset:4096
	ds_read_b128 v[232:235], v146 offset:5120
	ds_read_b128 v[236:239], v146 offset:6144
	ds_read_b128 v[240:243], v146 offset:7168
	global_load_lds_dwordx4 v[142:143], off
	v_lshl_add_u64 v[142:143], s[16:17], 0, v[138:139]
	s_add_i32 m0, s33, 0xe000
	s_nop 0
	global_load_lds_dwordx4 v[142:143], off
	s_waitcnt vmcnt(8)
	s_waitcnt lgkmcnt(0)
	s_setprio 1
	s_barrier
	v_mfma_f32_16x16x32_bf16 v[126:129], v[148:151], v[212:215], v[126:129]
	v_mfma_f32_16x16x32_bf16 v[122:125], v[156:159], v[212:215], v[122:125]
	v_mfma_f32_16x16x32_bf16 v[110:113], v[148:151], v[220:223], v[110:113]
	v_mfma_f32_16x16x32_bf16 v[106:109], v[156:159], v[220:223], v[106:109]
	v_mfma_f32_16x16x32_bf16 v[94:97], v[148:151], v[228:231], v[94:97]
	v_mfma_f32_16x16x32_bf16 v[90:93], v[156:159], v[228:231], v[90:93]
	v_mfma_f32_16x16x32_bf16 v[78:81], v[148:151], v[236:239], v[78:81]
	v_mfma_f32_16x16x32_bf16 v[74:77], v[156:159], v[236:239], v[74:77]
	v_mfma_f32_16x16x32_bf16 v[126:129], v[152:155], v[216:219], v[126:129]
	v_mfma_f32_16x16x32_bf16 v[122:125], v[160:163], v[216:219], v[122:125]
	v_mfma_f32_16x16x32_bf16 v[110:113], v[152:155], v[224:227], v[110:113]
	v_mfma_f32_16x16x32_bf16 v[106:109], v[160:163], v[224:227], v[106:109]
	v_mfma_f32_16x16x32_bf16 v[94:97], v[152:155], v[232:235], v[94:97]
	v_mfma_f32_16x16x32_bf16 v[90:93], v[160:163], v[232:235], v[90:93]
	v_mfma_f32_16x16x32_bf16 v[78:81], v[152:155], v[240:243], v[78:81]
	v_mfma_f32_16x16x32_bf16 v[74:77], v[160:163], v[240:243], v[74:77]
	v_mfma_f32_16x16x32_bf16 v[118:121], v[164:167], v[212:215], v[118:121]
	v_mfma_f32_16x16x32_bf16 v[114:117], v[172:175], v[212:215], v[114:117]
	v_mfma_f32_16x16x32_bf16 v[102:105], v[164:167], v[220:223], v[102:105]
	v_mfma_f32_16x16x32_bf16 v[98:101], v[172:175], v[220:223], v[98:101]
	v_mfma_f32_16x16x32_bf16 v[86:89], v[164:167], v[228:231], v[86:89]
	v_mfma_f32_16x16x32_bf16 v[82:85], v[172:175], v[228:231], v[82:85]
	v_mfma_f32_16x16x32_bf16 v[70:73], v[164:167], v[236:239], v[70:73]
	v_mfma_f32_16x16x32_bf16 v[66:69], v[172:175], v[236:239], v[66:69]
	v_mfma_f32_16x16x32_bf16 v[118:121], v[168:171], v[216:219], v[118:121]
	v_mfma_f32_16x16x32_bf16 v[114:117], v[196:199], v[216:219], v[114:117]
	v_mfma_f32_16x16x32_bf16 v[102:105], v[168:171], v[224:227], v[102:105]
	v_mfma_f32_16x16x32_bf16 v[98:101], v[196:199], v[224:227], v[98:101]
	v_mfma_f32_16x16x32_bf16 v[86:89], v[168:171], v[232:235], v[86:89]
	v_mfma_f32_16x16x32_bf16 v[82:85], v[196:199], v[232:235], v[82:85]
	v_mfma_f32_16x16x32_bf16 v[70:73], v[168:171], v[240:243], v[70:73]
	v_mfma_f32_16x16x32_bf16 v[66:69], v[196:199], v[240:243], v[66:69]
	s_barrier
	s_setprio 0
	s_add_i32 s49, s49, s31
	v_lshl_add_u64 v[142:143], s[14:15], 0, v[178:179]
	s_mov_b32 m0, s49
	ds_read_b128 v[212:215], v146 offset:16384
	ds_read_b128 v[216:219], v146 offset:17408
	ds_read_b128 v[220:223], v146 offset:18432
	ds_read_b128 v[224:227], v146 offset:19456
	ds_read_b128 v[228:231], v146 offset:20480
	ds_read_b128 v[232:235], v146 offset:21504
	ds_read_b128 v[236:239], v146 offset:22528
	ds_read_b128 v[240:243], v146 offset:23552
	global_load_lds_dwordx4 v[142:143], off
	s_add_i32 m0, s49, 0x2000
	s_add_u32 s50, s14, 0x40000
	v_lshl_add_u64 v[176:177], s[14:15], 0, v[130:131]
	s_addc_u32 s51, s15, 0
	s_add_i32 s49, s60, s31
	global_load_lds_dwordx4 v[176:177], off
	v_lshl_add_u64 v[202:203], s[50:51], 0, v[178:179]
	s_mov_b32 m0, s49
	v_lshl_add_u64 v[206:207], s[28:29], 0, v[132:133]
	global_load_lds_dwordx4 v[202:203], off
	v_lshl_add_u64 v[202:203], s[50:51], 0, v[130:131]
	s_add_i32 m0, s49, 0x2000
	s_nop 0
	global_load_lds_dwordx4 v[202:203], off
	v_lshl_add_u64 v[202:203], s[28:29], 0, v[134:135]
	s_mov_b32 m0, s33
	s_nop 0
	global_load_lds_dwordx4 v[202:203], off
	s_mov_b32 m0, s34
	s_nop 0
	global_load_lds_dwordx4 v[206:207], off
	s_waitcnt vmcnt(8)
	s_waitcnt lgkmcnt(0)
	s_setprio 1
	s_barrier
	v_mfma_f32_16x16x32_bf16 v[62:65], v[148:151], v[212:215], v[62:65]
	v_mfma_f32_16x16x32_bf16 v[58:61], v[156:159], v[212:215], v[58:61]
	v_mfma_f32_16x16x32_bf16 v[50:53], v[148:151], v[220:223], v[50:53]
	v_mfma_f32_16x16x32_bf16 v[42:45], v[156:159], v[220:223], v[42:45]
	v_mfma_f32_16x16x32_bf16 v[34:37], v[148:151], v[228:231], v[34:37]
	v_mfma_f32_16x16x32_bf16 v[26:29], v[156:159], v[228:231], v[26:29]
	v_mfma_f32_16x16x32_bf16 v[18:21], v[148:151], v[236:239], v[18:21]
	v_mfma_f32_16x16x32_bf16 v[10:13], v[156:159], v[236:239], v[10:13]
	v_mfma_f32_16x16x32_bf16 v[62:65], v[152:155], v[216:219], v[62:65]
	v_mfma_f32_16x16x32_bf16 v[58:61], v[160:163], v[216:219], v[58:61]
	v_mfma_f32_16x16x32_bf16 v[50:53], v[152:155], v[224:227], v[50:53]
	v_mfma_f32_16x16x32_bf16 v[42:45], v[160:163], v[224:227], v[42:45]
	v_mfma_f32_16x16x32_bf16 v[34:37], v[152:155], v[232:235], v[34:37]
	v_mfma_f32_16x16x32_bf16 v[26:29], v[160:163], v[232:235], v[26:29]
	v_mfma_f32_16x16x32_bf16 v[18:21], v[152:155], v[240:243], v[18:21]
	v_mfma_f32_16x16x32_bf16 v[10:13], v[160:163], v[240:243], v[10:13]
	v_mfma_f32_16x16x32_bf16 v[54:57], v[164:167], v[212:215], v[54:57]
	v_mfma_f32_16x16x32_bf16 v[46:49], v[172:175], v[212:215], v[46:49]
	v_mfma_f32_16x16x32_bf16 v[38:41], v[164:167], v[220:223], v[38:41]
	v_mfma_f32_16x16x32_bf16 v[30:33], v[172:175], v[220:223], v[30:33]
	v_mfma_f32_16x16x32_bf16 v[22:25], v[164:167], v[228:231], v[22:25]
	v_mfma_f32_16x16x32_bf16 v[14:17], v[172:175], v[228:231], v[14:17]
	v_mfma_f32_16x16x32_bf16 v[6:9], v[164:167], v[236:239], v[6:9]
	v_mfma_f32_16x16x32_bf16 v[2:5], v[172:175], v[236:239], v[2:5]
	v_mfma_f32_16x16x32_bf16 v[54:57], v[168:171], v[216:219], v[54:57]
	v_mfma_f32_16x16x32_bf16 v[46:49], v[196:199], v[216:219], v[46:49]
	v_mfma_f32_16x16x32_bf16 v[38:41], v[168:171], v[224:227], v[38:41]
	v_mfma_f32_16x16x32_bf16 v[30:33], v[196:199], v[224:227], v[30:33]
	v_mfma_f32_16x16x32_bf16 v[22:25], v[168:171], v[232:235], v[22:25]
	v_mfma_f32_16x16x32_bf16 v[14:17], v[196:199], v[232:235], v[14:17]
	v_mfma_f32_16x16x32_bf16 v[6:9], v[168:171], v[240:243], v[6:9]
	v_mfma_f32_16x16x32_bf16 v[2:5], v[196:199], v[240:243], v[2:5]
	s_barrier
	s_setprio 0
	s_add_i32 s49, 0, 0x18000
	v_add_u32_e32 v140, s49, v144
	s_add_i32 s50, 0, 0x1c000
	ds_read_b128 v[148:151], v140
	ds_read_b128 v[152:155], v140 offset:1024
	ds_read_b128 v[156:159], v140 offset:2048
	ds_read_b128 v[160:163], v140 offset:3072
	v_add_u32_e32 v140, s50, v144
	ds_read_b128 v[164:167], v140
	ds_read_b128 v[168:171], v140 offset:1024
	ds_read_b128 v[172:175], v140 offset:2048
	ds_read_b128 v[196:199], v140 offset:3072
	s_add_u32 s28, s28, 0x40000
	s_addc_u32 s29, s29, 0
	s_mov_b32 m0, s35
	v_lshl_add_u64 v[244:245], s[28:29], 0, v[134:135]
	ds_read_b128 v[212:215], v146 offset:32768
	ds_read_b128 v[216:219], v146 offset:33792
	ds_read_b128 v[220:223], v146 offset:34816
	ds_read_b128 v[224:227], v146 offset:35840
	ds_read_b128 v[228:231], v146 offset:36864
	ds_read_b128 v[232:235], v146 offset:37888
	ds_read_b128 v[236:239], v146 offset:38912
	ds_read_b128 v[240:243], v146 offset:39936
	global_load_lds_dwordx4 v[244:245], off
	v_lshl_add_u64 v[244:245], s[28:29], 0, v[132:133]
	s_mov_b32 m0, s38
	s_nop 0
	global_load_lds_dwordx4 v[244:245], off
	s_waitcnt vmcnt(8)
	s_waitcnt lgkmcnt(0)
	s_setprio 1
	s_barrier
	v_mfma_f32_16x16x32_bf16 v[126:129], v[148:151], v[212:215], v[126:129]
	v_mfma_f32_16x16x32_bf16 v[122:125], v[156:159], v[212:215], v[122:125]
	v_mfma_f32_16x16x32_bf16 v[110:113], v[148:151], v[220:223], v[110:113]
	v_mfma_f32_16x16x32_bf16 v[106:109], v[156:159], v[220:223], v[106:109]
	v_mfma_f32_16x16x32_bf16 v[94:97], v[148:151], v[228:231], v[94:97]
	v_mfma_f32_16x16x32_bf16 v[90:93], v[156:159], v[228:231], v[90:93]
	v_mfma_f32_16x16x32_bf16 v[78:81], v[148:151], v[236:239], v[78:81]
	v_mfma_f32_16x16x32_bf16 v[74:77], v[156:159], v[236:239], v[74:77]
	v_mfma_f32_16x16x32_bf16 v[126:129], v[152:155], v[216:219], v[126:129]
	v_mfma_f32_16x16x32_bf16 v[122:125], v[160:163], v[216:219], v[122:125]
	v_mfma_f32_16x16x32_bf16 v[110:113], v[152:155], v[224:227], v[110:113]
	v_mfma_f32_16x16x32_bf16 v[106:109], v[160:163], v[224:227], v[106:109]
	v_mfma_f32_16x16x32_bf16 v[94:97], v[152:155], v[232:235], v[94:97]
	v_mfma_f32_16x16x32_bf16 v[90:93], v[160:163], v[232:235], v[90:93]
	v_mfma_f32_16x16x32_bf16 v[78:81], v[152:155], v[240:243], v[78:81]
	v_mfma_f32_16x16x32_bf16 v[74:77], v[160:163], v[240:243], v[74:77]
	v_mfma_f32_16x16x32_bf16 v[118:121], v[164:167], v[212:215], v[118:121]
	v_mfma_f32_16x16x32_bf16 v[114:117], v[172:175], v[212:215], v[114:117]
	v_mfma_f32_16x16x32_bf16 v[102:105], v[164:167], v[220:223], v[102:105]
	v_mfma_f32_16x16x32_bf16 v[98:101], v[172:175], v[220:223], v[98:101]
	v_mfma_f32_16x16x32_bf16 v[86:89], v[164:167], v[228:231], v[86:89]
	v_mfma_f32_16x16x32_bf16 v[82:85], v[172:175], v[228:231], v[82:85]
	v_mfma_f32_16x16x32_bf16 v[70:73], v[164:167], v[236:239], v[70:73]
	v_mfma_f32_16x16x32_bf16 v[66:69], v[172:175], v[236:239], v[66:69]
	v_mfma_f32_16x16x32_bf16 v[118:121], v[168:171], v[216:219], v[118:121]
	v_mfma_f32_16x16x32_bf16 v[114:117], v[196:199], v[216:219], v[114:117]
	v_mfma_f32_16x16x32_bf16 v[102:105], v[168:171], v[224:227], v[102:105]
	v_mfma_f32_16x16x32_bf16 v[98:101], v[196:199], v[224:227], v[98:101]
	v_mfma_f32_16x16x32_bf16 v[86:89], v[168:171], v[232:235], v[86:89]
	v_mfma_f32_16x16x32_bf16 v[82:85], v[196:199], v[232:235], v[82:85]
	v_mfma_f32_16x16x32_bf16 v[70:73], v[168:171], v[240:243], v[70:73]
	v_mfma_f32_16x16x32_bf16 v[66:69], v[196:199], v[240:243], v[66:69]
	s_barrier
	s_setprio 0
	s_add_i32 s28, s49, s31
	v_lshl_add_u64 v[142:143], v[142:143], 0, s[90:91]
	s_mov_b32 m0, s28
	ds_read_b128 v[212:215], v146 offset:49152
	ds_read_b128 v[216:219], v146 offset:50176
	ds_read_b128 v[220:223], v146 offset:51200
	ds_read_b128 v[224:227], v146 offset:52224
	ds_read_b128 v[228:231], v146 offset:53248
	ds_read_b128 v[232:235], v146 offset:54272
	ds_read_b128 v[236:239], v146 offset:55296
	ds_read_b128 v[240:243], v146 offset:56320
	global_load_lds_dwordx4 v[142:143], off
	s_add_i32 m0, s28, 0x2000
	s_add_u32 s14, s14, 0x40080
	v_lshl_add_u64 v[142:143], v[176:177], 0, s[90:91]
	s_addc_u32 s15, s15, 0
	s_add_i32 s28, s50, s31
	global_load_lds_dwordx4 v[142:143], off
	v_lshl_add_u64 v[142:143], s[14:15], 0, v[178:179]
	s_mov_b32 m0, s28
	s_nop 0
	global_load_lds_dwordx4 v[142:143], off
	v_lshl_add_u64 v[142:143], s[14:15], 0, v[130:131]
	s_add_i32 m0, s28, 0x2000
	s_nop 0
	global_load_lds_dwordx4 v[142:143], off
	v_lshl_add_u64 v[142:143], v[202:203], 0, s[90:91]
	s_mov_b32 m0, s39
	s_nop 0
	global_load_lds_dwordx4 v[142:143], off
	v_lshl_add_u64 v[142:143], v[206:207], 0, s[90:91]
	s_mov_b32 m0, s40
	s_nop 0
	global_load_lds_dwordx4 v[142:143], off
	s_waitcnt vmcnt(8)
	s_waitcnt lgkmcnt(0)
	s_setprio 1
	s_barrier
	v_mfma_f32_16x16x32_bf16 v[62:65], v[148:151], v[212:215], v[62:65]
	v_mfma_f32_16x16x32_bf16 v[58:61], v[156:159], v[212:215], v[58:61]
	v_mfma_f32_16x16x32_bf16 v[50:53], v[148:151], v[220:223], v[50:53]
	v_mfma_f32_16x16x32_bf16 v[42:45], v[156:159], v[220:223], v[42:45]
	v_mfma_f32_16x16x32_bf16 v[34:37], v[148:151], v[228:231], v[34:37]
	v_mfma_f32_16x16x32_bf16 v[26:29], v[156:159], v[228:231], v[26:29]
	v_mfma_f32_16x16x32_bf16 v[18:21], v[148:151], v[236:239], v[18:21]
	v_mfma_f32_16x16x32_bf16 v[10:13], v[156:159], v[236:239], v[10:13]
	v_mfma_f32_16x16x32_bf16 v[62:65], v[152:155], v[216:219], v[62:65]
	v_mfma_f32_16x16x32_bf16 v[58:61], v[160:163], v[216:219], v[58:61]
	v_mfma_f32_16x16x32_bf16 v[50:53], v[152:155], v[224:227], v[50:53]
	v_mfma_f32_16x16x32_bf16 v[42:45], v[160:163], v[224:227], v[42:45]
	v_mfma_f32_16x16x32_bf16 v[34:37], v[152:155], v[232:235], v[34:37]
	v_mfma_f32_16x16x32_bf16 v[26:29], v[160:163], v[232:235], v[26:29]
	v_mfma_f32_16x16x32_bf16 v[18:21], v[152:155], v[240:243], v[18:21]
	v_mfma_f32_16x16x32_bf16 v[10:13], v[160:163], v[240:243], v[10:13]
	v_mfma_f32_16x16x32_bf16 v[54:57], v[164:167], v[212:215], v[54:57]
	v_mfma_f32_16x16x32_bf16 v[46:49], v[172:175], v[212:215], v[46:49]
	v_mfma_f32_16x16x32_bf16 v[38:41], v[164:167], v[220:223], v[38:41]
	v_mfma_f32_16x16x32_bf16 v[30:33], v[172:175], v[220:223], v[30:33]
	v_mfma_f32_16x16x32_bf16 v[22:25], v[164:167], v[228:231], v[22:25]
	v_mfma_f32_16x16x32_bf16 v[14:17], v[172:175], v[228:231], v[14:17]
	v_mfma_f32_16x16x32_bf16 v[6:9], v[164:167], v[236:239], v[6:9]
	v_mfma_f32_16x16x32_bf16 v[2:5], v[172:175], v[236:239], v[2:5]
	v_mfma_f32_16x16x32_bf16 v[54:57], v[168:171], v[216:219], v[54:57]
	v_mfma_f32_16x16x32_bf16 v[46:49], v[196:199], v[216:219], v[46:49]
	v_mfma_f32_16x16x32_bf16 v[38:41], v[168:171], v[224:227], v[38:41]
	v_mfma_f32_16x16x32_bf16 v[30:33], v[196:199], v[224:227], v[30:33]
	v_mfma_f32_16x16x32_bf16 v[22:25], v[168:171], v[232:235], v[22:25]
	v_mfma_f32_16x16x32_bf16 v[14:17], v[196:199], v[232:235], v[14:17]
	v_mfma_f32_16x16x32_bf16 v[6:9], v[168:171], v[240:243], v[6:9]
	v_mfma_f32_16x16x32_bf16 v[2:5], v[196:199], v[240:243], v[2:5]
	s_barrier
	s_setprio 0
	s_add_i32 s48, s48, 2
	s_add_u32 s16, s16, 0x100
	s_addc_u32 s17, s17, 0
	s_add_u32 s46, s46, 0x100
	s_addc_u32 s47, s47, 0
	s_cmp_gt_u32 s48, 13
	s_cbranch_scc0 .LBB0_931
	s_and_b64 vcc, exec, s[8:9]
	s_cbranch_vccz .LBB0_934
	s_barrier

.LBB0_1019:
	s_add_u32 s16, s94, vcc_lo
	s_addc_u32 s17, s95, vcc_hi
	s_add_u32 s16, s16, 0x100
	s_addc_u32 s17, s17, 0
	s_add_u32 s51, s46, vcc_lo
	s_addc_u32 s62, s47, vcc_hi
	s_cmpk_eq_i32 vcc_lo, 0x700
	s_cselect_b32 s39, s21, s17
	s_cselect_b32 s38, s48, s16
	v_add_u32_e32 v147, s31, v145
	s_cselect_b32 s17, s35, s62
	s_cselect_b32 s16, s49, s51
	s_add_i32 s51, 0, 0x14000
	ds_read_b128 v[148:151], v147
	ds_read_b128 v[152:155], v147 offset:1024
	ds_read_b128 v[156:159], v147 offset:2048
	ds_read_b128 v[160:163], v147 offset:3072
	v_add_u32_e32 v147, s51, v145
	ds_read_b128 v[170:173], v147
	ds_read_b128 v[174:177], v147 offset:1024
	ds_read_b128 v[196:199], v147 offset:2048
	ds_read_b128 v[212:215], v147 offset:3072
	v_lshl_add_u64 v[164:165], v[140:141], 0, vcc
	s_add_i32 m0, s84, 0xc000
	ds_read_b128 v[216:219], v146
	ds_read_b128 v[220:223], v146 offset:1024
	ds_read_b128 v[224:227], v146 offset:2048
	ds_read_b128 v[228:231], v146 offset:3072
	ds_read_b128 v[232:235], v146 offset:4096
	ds_read_b128 v[236:239], v146 offset:5120
	ds_read_b128 v[240:243], v146 offset:6144
	ds_read_b128 v[244:247], v146 offset:7168
	global_load_lds_dwordx4 v[164:165], off
	v_lshl_add_u64 v[164:165], v[142:143], 0, vcc
	s_add_i32 m0, s84, 0xe000
	s_nop 0
	global_load_lds_dwordx4 v[164:165], off
	s_waitcnt vmcnt(8)
	s_waitcnt lgkmcnt(0)
	s_setprio 1
	s_barrier
	v_mfma_f32_16x16x32_bf16 v[6:9], v[148:151], v[216:219], v[6:9]
	v_mfma_f32_16x16x32_bf16 v[2:5], v[156:159], v[216:219], v[2:5]
	v_mfma_f32_16x16x32_bf16 v[30:33], v[148:151], v[224:227], v[30:33]
	v_mfma_f32_16x16x32_bf16 v[26:29], v[156:159], v[224:227], v[26:29]
	v_mfma_f32_16x16x32_bf16 v[58:61], v[148:151], v[232:235], v[58:61]
	v_mfma_f32_16x16x32_bf16 v[50:53], v[156:159], v[232:235], v[50:53]
	v_mfma_f32_16x16x32_bf16 v[86:89], v[148:151], v[240:243], v[86:89]
	v_mfma_f32_16x16x32_bf16 v[82:85], v[156:159], v[240:243], v[82:85]
	v_mfma_f32_16x16x32_bf16 v[6:9], v[152:155], v[220:223], v[6:9]
	v_mfma_f32_16x16x32_bf16 v[2:5], v[160:163], v[220:223], v[2:5]
	v_mfma_f32_16x16x32_bf16 v[30:33], v[152:155], v[228:231], v[30:33]
	v_mfma_f32_16x16x32_bf16 v[26:29], v[160:163], v[228:231], v[26:29]
	v_mfma_f32_16x16x32_bf16 v[58:61], v[152:155], v[236:239], v[58:61]
	v_mfma_f32_16x16x32_bf16 v[50:53], v[160:163], v[236:239], v[50:53]
	v_mfma_f32_16x16x32_bf16 v[86:89], v[152:155], v[244:247], v[86:89]
	v_mfma_f32_16x16x32_bf16 v[82:85], v[160:163], v[244:247], v[82:85]
	v_mfma_f32_16x16x32_bf16 v[14:17], v[170:173], v[216:219], v[14:17]
	v_mfma_f32_16x16x32_bf16 v[10:13], v[196:199], v[216:219], v[10:13]
	v_mfma_f32_16x16x32_bf16 v[46:49], v[170:173], v[224:227], v[46:49]
	v_mfma_f32_16x16x32_bf16 v[42:45], v[196:199], v[224:227], v[42:45]
	v_mfma_f32_16x16x32_bf16 v[70:73], v[170:173], v[232:235], v[70:73]
	v_mfma_f32_16x16x32_bf16 v[66:69], v[196:199], v[232:235], v[66:69]
	v_mfma_f32_16x16x32_bf16 v[94:97], v[170:173], v[240:243], v[94:97]
	v_mfma_f32_16x16x32_bf16 v[90:93], v[196:199], v[240:243], v[90:93]
	v_mfma_f32_16x16x32_bf16 v[14:17], v[174:177], v[220:223], v[14:17]
	v_mfma_f32_16x16x32_bf16 v[10:13], v[212:215], v[220:223], v[10:13]
	v_mfma_f32_16x16x32_bf16 v[46:49], v[174:177], v[228:231], v[46:49]
	v_mfma_f32_16x16x32_bf16 v[42:45], v[212:215], v[228:231], v[42:45]
	v_mfma_f32_16x16x32_bf16 v[70:73], v[174:177], v[236:239], v[70:73]
	v_mfma_f32_16x16x32_bf16 v[66:69], v[212:215], v[236:239], v[66:69]
	v_mfma_f32_16x16x32_bf16 v[94:97], v[174:177], v[244:247], v[94:97]
	v_mfma_f32_16x16x32_bf16 v[90:93], v[212:215], v[244:247], v[90:93]
	s_barrier
	s_setprio 0
	s_add_i32 s62, s31, s11
	v_lshl_add_u64 v[164:165], s[16:17], 0, v[178:179]
	s_mov_b32 m0, s62
	ds_read_b128 v[216:219], v146 offset:16384
	ds_read_b128 v[220:223], v146 offset:17408
	ds_read_b128 v[224:227], v146 offset:18432
	ds_read_b128 v[228:231], v146 offset:19456
	ds_read_b128 v[232:235], v146 offset:20480
	ds_read_b128 v[236:239], v146 offset:21504
	ds_read_b128 v[240:243], v146 offset:22528
	ds_read_b128 v[244:247], v146 offset:23552
	global_load_lds_dwordx4 v[164:165], off
	s_add_i32 m0, s62, 0x2000
	s_add_u32 s62, s16, 0x40000
	v_lshl_add_u64 v[202:203], s[16:17], 0, v[130:131]
	s_addc_u32 s63, s17, 0
	s_add_i32 s51, s51, s11
	global_load_lds_dwordx4 v[202:203], off
	v_lshl_add_u64 v[206:207], s[62:63], 0, v[178:179]
	s_mov_b32 m0, s51
	v_lshl_add_u64 v[248:249], s[38:39], 0, v[132:133]
	global_load_lds_dwordx4 v[206:207], off
	v_lshl_add_u64 v[206:207], s[62:63], 0, v[130:131]
	s_add_i32 m0, s51, 0x2000
	s_nop 0
	global_load_lds_dwordx4 v[206:207], off
	v_lshl_add_u64 v[206:207], s[38:39], 0, v[134:135]
	s_mov_b32 m0, s84
	s_nop 0
	global_load_lds_dwordx4 v[206:207], off
	s_mov_b32 m0, s85
	s_nop 0
	global_load_lds_dwordx4 v[248:249], off
	s_waitcnt vmcnt(8)
	s_waitcnt lgkmcnt(0)
	s_setprio 1
	s_barrier
	v_mfma_f32_16x16x32_bf16 v[110:113], v[148:151], v[216:219], v[110:113]
	v_mfma_f32_16x16x32_bf16 v[106:109], v[156:159], v[216:219], v[106:109]
	v_mfma_f32_16x16x32_bf16 v[126:129], v[148:151], v[224:227], v[126:129]
	v_mfma_f32_16x16x32_bf16 v[122:125], v[156:159], v[224:227], v[122:125]
	v_mfma_f32_16x16x32_bf16 v[78:81], v[148:151], v[232:235], v[78:81]
	v_mfma_f32_16x16x32_bf16 v[74:77], v[156:159], v[232:235], v[74:77]
	v_mfma_f32_16x16x32_bf16 v[38:41], v[148:151], v[240:243], v[38:41]
	v_mfma_f32_16x16x32_bf16 v[34:37], v[156:159], v[240:243], v[34:37]
	v_mfma_f32_16x16x32_bf16 v[110:113], v[152:155], v[220:223], v[110:113]
	v_mfma_f32_16x16x32_bf16 v[106:109], v[160:163], v[220:223], v[106:109]
	v_mfma_f32_16x16x32_bf16 v[126:129], v[152:155], v[228:231], v[126:129]
	v_mfma_f32_16x16x32_bf16 v[122:125], v[160:163], v[228:231], v[122:125]
	v_mfma_f32_16x16x32_bf16 v[78:81], v[152:155], v[236:239], v[78:81]
	v_mfma_f32_16x16x32_bf16 v[74:77], v[160:163], v[236:239], v[74:77]
	v_mfma_f32_16x16x32_bf16 v[38:41], v[152:155], v[244:247], v[38:41]
	v_mfma_f32_16x16x32_bf16 v[34:37], v[160:163], v[244:247], v[34:37]
	v_mfma_f32_16x16x32_bf16 v[118:121], v[170:173], v[216:219], v[118:121]
	v_mfma_f32_16x16x32_bf16 v[114:117], v[196:199], v[216:219], v[114:117]
	v_mfma_f32_16x16x32_bf16 v[102:105], v[170:173], v[224:227], v[102:105]
	v_mfma_f32_16x16x32_bf16 v[98:101], v[196:199], v[224:227], v[98:101]
	v_mfma_f32_16x16x32_bf16 v[62:65], v[170:173], v[232:235], v[62:65]
	v_mfma_f32_16x16x32_bf16 v[54:57], v[196:199], v[232:235], v[54:57]
	v_mfma_f32_16x16x32_bf16 v[22:25], v[170:173], v[240:243], v[22:25]
	v_mfma_f32_16x16x32_bf16 v[18:21], v[196:199], v[240:243], v[18:21]
	v_mfma_f32_16x16x32_bf16 v[118:121], v[174:177], v[220:223], v[118:121]
	v_mfma_f32_16x16x32_bf16 v[114:117], v[212:215], v[220:223], v[114:117]
	v_mfma_f32_16x16x32_bf16 v[102:105], v[174:177], v[228:231], v[102:105]
	v_mfma_f32_16x16x32_bf16 v[98:101], v[212:215], v[228:231], v[98:101]
	v_mfma_f32_16x16x32_bf16 v[62:65], v[174:177], v[236:239], v[62:65]
	v_mfma_f32_16x16x32_bf16 v[54:57], v[212:215], v[236:239], v[54:57]
	v_mfma_f32_16x16x32_bf16 v[22:25], v[174:177], v[244:247], v[22:25]
	v_mfma_f32_16x16x32_bf16 v[18:21], v[212:215], v[244:247], v[18:21]
	s_barrier
	s_setprio 0
	s_add_i32 s51, 0, 0x18000
	v_add_u32_e32 v147, s51, v145
	s_add_i32 s62, 0, 0x1c000
	ds_read_b128 v[148:151], v147
	ds_read_b128 v[152:155], v147 offset:1024
	ds_read_b128 v[156:159], v147 offset:2048
	ds_read_b128 v[160:163], v147 offset:3072
	v_add_u32_e32 v147, s62, v145
	ds_read_b128 v[170:173], v147
	ds_read_b128 v[174:177], v147 offset:1024
	ds_read_b128 v[196:199], v147 offset:2048
	ds_read_b128 v[212:215], v147 offset:3072
	s_add_u32 s38, s38, 0x40000
	s_addc_u32 s39, s39, 0
	s_mov_b32 m0, s40
	v_lshl_add_u64 v[250:251], s[38:39], 0, v[134:135]
	ds_read_b128 v[216:219], v146 offset:32768
	ds_read_b128 v[220:223], v146 offset:33792
	ds_read_b128 v[224:227], v146 offset:34816
	ds_read_b128 v[228:231], v146 offset:35840
	ds_read_b128 v[232:235], v146 offset:36864
	ds_read_b128 v[236:239], v146 offset:37888
	ds_read_b128 v[240:243], v146 offset:38912
	ds_read_b128 v[244:247], v146 offset:39936
	global_load_lds_dwordx4 v[250:251], off
	v_lshl_add_u64 v[250:251], s[38:39], 0, v[132:133]
	s_mov_b32 m0, s41
	s_nop 0
	global_load_lds_dwordx4 v[250:251], off
	s_waitcnt vmcnt(8)
	s_waitcnt lgkmcnt(0)
	s_setprio 1
	s_barrier
	v_mfma_f32_16x16x32_bf16 v[6:9], v[148:151], v[216:219], v[6:9]
	v_mfma_f32_16x16x32_bf16 v[2:5], v[156:159], v[216:219], v[2:5]
	v_mfma_f32_16x16x32_bf16 v[30:33], v[148:151], v[224:227], v[30:33]
	v_mfma_f32_16x16x32_bf16 v[26:29], v[156:159], v[224:227], v[26:29]
	v_mfma_f32_16x16x32_bf16 v[58:61], v[148:151], v[232:235], v[58:61]
	v_mfma_f32_16x16x32_bf16 v[50:53], v[156:159], v[232:235], v[50:53]
	v_mfma_f32_16x16x32_bf16 v[86:89], v[148:151], v[240:243], v[86:89]
	v_mfma_f32_16x16x32_bf16 v[82:85], v[156:159], v[240:243], v[82:85]
	v_mfma_f32_16x16x32_bf16 v[6:9], v[152:155], v[220:223], v[6:9]
	v_mfma_f32_16x16x32_bf16 v[2:5], v[160:163], v[220:223], v[2:5]
	v_mfma_f32_16x16x32_bf16 v[30:33], v[152:155], v[228:231], v[30:33]
	v_mfma_f32_16x16x32_bf16 v[26:29], v[160:163], v[228:231], v[26:29]
	v_mfma_f32_16x16x32_bf16 v[58:61], v[152:155], v[236:239], v[58:61]
	v_mfma_f32_16x16x32_bf16 v[50:53], v[160:163], v[236:239], v[50:53]
	v_mfma_f32_16x16x32_bf16 v[86:89], v[152:155], v[244:247], v[86:89]
	v_mfma_f32_16x16x32_bf16 v[82:85], v[160:163], v[244:247], v[82:85]
	v_mfma_f32_16x16x32_bf16 v[14:17], v[170:173], v[216:219], v[14:17]
	v_mfma_f32_16x16x32_bf16 v[10:13], v[196:199], v[216:219], v[10:13]
	v_mfma_f32_16x16x32_bf16 v[46:49], v[170:173], v[224:227], v[46:49]
	v_mfma_f32_16x16x32_bf16 v[42:45], v[196:199], v[224:227], v[42:45]
	v_mfma_f32_16x16x32_bf16 v[70:73], v[170:173], v[232:235], v[70:73]
	v_mfma_f32_16x16x32_bf16 v[66:69], v[196:199], v[232:235], v[66:69]
	v_mfma_f32_16x16x32_bf16 v[94:97], v[170:173], v[240:243], v[94:97]
	v_mfma_f32_16x16x32_bf16 v[90:93], v[196:199], v[240:243], v[90:93]
	v_mfma_f32_16x16x32_bf16 v[14:17], v[174:177], v[220:223], v[14:17]
	v_mfma_f32_16x16x32_bf16 v[10:13], v[212:215], v[220:223], v[10:13]
	v_mfma_f32_16x16x32_bf16 v[46:49], v[174:177], v[228:231], v[46:49]
	v_mfma_f32_16x16x32_bf16 v[42:45], v[212:215], v[228:231], v[42:45]
	v_mfma_f32_16x16x32_bf16 v[70:73], v[174:177], v[236:239], v[70:73]
	v_mfma_f32_16x16x32_bf16 v[66:69], v[212:215], v[236:239], v[66:69]
	v_mfma_f32_16x16x32_bf16 v[94:97], v[174:177], v[244:247], v[94:97]
	v_mfma_f32_16x16x32_bf16 v[90:93], v[212:215], v[244:247], v[90:93]
	s_barrier
	s_setprio 0
	s_add_i32 s38, s51, s11
	v_lshl_add_u64 v[164:165], v[164:165], 0, s[90:91]
	s_mov_b32 m0, s38
	ds_read_b128 v[216:219], v146 offset:49152
	ds_read_b128 v[220:223], v146 offset:50176
	ds_read_b128 v[224:227], v146 offset:51200
	ds_read_b128 v[228:231], v146 offset:52224
	ds_read_b128 v[232:235], v146 offset:53248
	ds_read_b128 v[236:239], v146 offset:54272
	ds_read_b128 v[240:243], v146 offset:55296
	ds_read_b128 v[244:247], v146 offset:56320
	global_load_lds_dwordx4 v[164:165], off
	s_add_i32 m0, s38, 0x2000
	s_add_u32 s16, s16, 0x40080
	v_lshl_add_u64 v[164:165], v[202:203], 0, s[90:91]
	s_addc_u32 s17, s17, 0
	s_add_i32 s38, s62, s11
	global_load_lds_dwordx4 v[164:165], off
	v_lshl_add_u64 v[164:165], s[16:17], 0, v[178:179]
	s_mov_b32 m0, s38
	s_nop 0
	global_load_lds_dwordx4 v[164:165], off
	v_lshl_add_u64 v[164:165], s[16:17], 0, v[130:131]
	s_add_i32 m0, s38, 0x2000
	s_nop 0
	global_load_lds_dwordx4 v[164:165], off
	v_lshl_add_u64 v[164:165], v[206:207], 0, s[90:91]
	s_mov_b32 m0, s42
	s_nop 0
	global_load_lds_dwordx4 v[164:165], off
	v_lshl_add_u64 v[164:165], v[248:249], 0, s[90:91]
	s_mov_b32 m0, s43
	s_nop 0
	global_load_lds_dwordx4 v[164:165], off
	s_waitcnt vmcnt(8)
	s_waitcnt lgkmcnt(0)
	s_setprio 1
	s_barrier
	v_mfma_f32_16x16x32_bf16 v[110:113], v[148:151], v[216:219], v[110:113]
	v_mfma_f32_16x16x32_bf16 v[106:109], v[156:159], v[216:219], v[106:109]
	v_mfma_f32_16x16x32_bf16 v[126:129], v[148:151], v[224:227], v[126:129]
	v_mfma_f32_16x16x32_bf16 v[122:125], v[156:159], v[224:227], v[122:125]
	v_mfma_f32_16x16x32_bf16 v[78:81], v[148:151], v[232:235], v[78:81]
	v_mfma_f32_16x16x32_bf16 v[74:77], v[156:159], v[232:235], v[74:77]
	v_mfma_f32_16x16x32_bf16 v[38:41], v[148:151], v[240:243], v[38:41]
	v_mfma_f32_16x16x32_bf16 v[34:37], v[156:159], v[240:243], v[34:37]
	v_mfma_f32_16x16x32_bf16 v[110:113], v[152:155], v[220:223], v[110:113]
	v_mfma_f32_16x16x32_bf16 v[106:109], v[160:163], v[220:223], v[106:109]
	v_mfma_f32_16x16x32_bf16 v[126:129], v[152:155], v[228:231], v[126:129]
	v_mfma_f32_16x16x32_bf16 v[122:125], v[160:163], v[228:231], v[122:125]
	v_mfma_f32_16x16x32_bf16 v[78:81], v[152:155], v[236:239], v[78:81]
	v_mfma_f32_16x16x32_bf16 v[74:77], v[160:163], v[236:239], v[74:77]
	v_mfma_f32_16x16x32_bf16 v[38:41], v[152:155], v[244:247], v[38:41]
	v_mfma_f32_16x16x32_bf16 v[34:37], v[160:163], v[244:247], v[34:37]
	v_mfma_f32_16x16x32_bf16 v[118:121], v[170:173], v[216:219], v[118:121]
	v_mfma_f32_16x16x32_bf16 v[114:117], v[196:199], v[216:219], v[114:117]
	v_mfma_f32_16x16x32_bf16 v[102:105], v[170:173], v[224:227], v[102:105]
	v_mfma_f32_16x16x32_bf16 v[98:101], v[196:199], v[224:227], v[98:101]
	v_mfma_f32_16x16x32_bf16 v[62:65], v[170:173], v[232:235], v[62:65]
	v_mfma_f32_16x16x32_bf16 v[54:57], v[196:199], v[232:235], v[54:57]
	v_mfma_f32_16x16x32_bf16 v[22:25], v[170:173], v[240:243], v[22:25]
	v_mfma_f32_16x16x32_bf16 v[18:21], v[196:199], v[240:243], v[18:21]
	v_mfma_f32_16x16x32_bf16 v[118:121], v[174:177], v[220:223], v[118:121]
	v_mfma_f32_16x16x32_bf16 v[114:117], v[212:215], v[220:223], v[114:117]
	v_mfma_f32_16x16x32_bf16 v[102:105], v[174:177], v[228:231], v[102:105]
	v_mfma_f32_16x16x32_bf16 v[98:101], v[212:215], v[228:231], v[98:101]
	v_mfma_f32_16x16x32_bf16 v[62:65], v[174:177], v[236:239], v[62:65]
	v_mfma_f32_16x16x32_bf16 v[54:57], v[212:215], v[236:239], v[54:57]
	v_mfma_f32_16x16x32_bf16 v[22:25], v[174:177], v[244:247], v[22:25]
	v_mfma_f32_16x16x32_bf16 v[18:21], v[212:215], v[244:247], v[18:21]
	s_barrier
	s_setprio 0
	s_add_i32 s50, s50, 2
	s_add_u32 vcc_lo, vcc_lo, 0x100
	s_addc_u32 vcc_hi, vcc_hi, 0
	s_cmp_gt_u32 s50, 13
	s_cbranch_scc0 .LBB0_1019
	s_add_u32 s16, s46, 0xffffff00
	s_addc_u32 s17, s47, -1
	s_andn2_b64 vcc, exec, s[6:7]
	s_cbranch_vccnz .LBB0_1022
	v_mov_b32_e32 v18, 0
	s_mov_b32 s0, s34
	s_mov_b32 s10, s20
	s_mov_b64 s[94:95], s[60:61]
	s_mov_b32 s44, s45
	v_mov_b32_e32 v19, v18
	v_mov_b32_e32 v20, v18
	v_mov_b32_e32 v21, v18
	v_mov_b32_e32 v22, v18
	v_mov_b32_e32 v23, v18
	v_mov_b32_e32 v24, v18
	v_mov_b32_e32 v25, v18
	v_mov_b32_e32 v54, v18
	v_mov_b32_e32 v55, v18
	v_mov_b32_e32 v56, v18
	v_mov_b32_e32 v57, v18
	v_mov_b32_e32 v62, v18
	v_mov_b32_e32 v63, v18
	v_mov_b32_e32 v64, v18
	v_mov_b32_e32 v65, v18
	v_mov_b32_e32 v98, v18
	v_mov_b32_e32 v99, v18
	v_mov_b32_e32 v100, v18
	v_mov_b32_e32 v101, v18
	v_mov_b32_e32 v102, v18
	v_mov_b32_e32 v103, v18
	v_mov_b32_e32 v104, v18
	v_mov_b32_e32 v105, v18
	v_mov_b32_e32 v114, v18
	v_mov_b32_e32 v115, v18
	v_mov_b32_e32 v116, v18
	v_mov_b32_e32 v117, v18
	v_mov_b32_e32 v118, v18
	v_mov_b32_e32 v119, v18
	v_mov_b32_e32 v120, v18
	v_mov_b32_e32 v121, v18
	v_mov_b32_e32 v34, v18
	v_mov_b32_e32 v35, v18
	v_mov_b32_e32 v36, v18
	v_mov_b32_e32 v37, v18
	v_mov_b32_e32 v38, v18
	v_mov_b32_e32 v39, v18
	v_mov_b32_e32 v40, v18
	v_mov_b32_e32 v41, v18
	v_mov_b32_e32 v74, v18
	v_mov_b32_e32 v75, v18
	v_mov_b32_e32 v76, v18
	v_mov_b32_e32 v77, v18
	v_mov_b32_e32 v78, v18
	v_mov_b32_e32 v79, v18
	v_mov_b32_e32 v80, v18
	v_mov_b32_e32 v81, v18
	v_mov_b32_e32 v122, v18
	v_mov_b32_e32 v123, v18
	v_mov_b32_e32 v124, v18
	v_mov_b32_e32 v125, v18
	v_mov_b32_e32 v126, v18
	v_mov_b32_e32 v127, v18
	v_mov_b32_e32 v128, v18
	v_mov_b32_e32 v129, v18
	v_mov_b32_e32 v106, v18
	v_mov_b32_e32 v107, v18
	v_mov_b32_e32 v108, v18
	v_mov_b32_e32 v109, v18
	v_mov_b32_e32 v110, v18
	v_mov_b32_e32 v111, v18
	v_mov_b32_e32 v112, v18
	v_mov_b32_e32 v113, v18
	v_mov_b32_e32 v90, v18
	v_mov_b32_e32 v91, v18
	v_mov_b32_e32 v92, v18
	v_mov_b32_e32 v93, v18
	v_mov_b32_e32 v94, v18
	v_mov_b32_e32 v95, v18
	v_mov_b32_e32 v96, v18
	v_mov_b32_e32 v97, v18
	v_mov_b32_e32 v66, v18
	v_mov_b32_e32 v67, v18
	v_mov_b32_e32 v68, v18
	v_mov_b32_e32 v69, v18
	v_mov_b32_e32 v70, v18
	v_mov_b32_e32 v71, v18
	v_mov_b32_e32 v72, v18
	v_mov_b32_e32 v73, v18
	v_mov_b32_e32 v42, v18
	v_mov_b32_e32 v43, v18
	v_mov_b32_e32 v44, v18
	v_mov_b32_e32 v45, v18
	v_mov_b32_e32 v46, v18
	v_mov_b32_e32 v47, v18
	v_mov_b32_e32 v48, v18
	v_mov_b32_e32 v49, v18
	v_mov_b32_e32 v10, v18
	v_mov_b32_e32 v11, v18
	v_mov_b32_e32 v12, v18
	v_mov_b32_e32 v13, v18
	v_mov_b32_e32 v14, v18
	v_mov_b32_e32 v15, v18
	v_mov_b32_e32 v16, v18
	v_mov_b32_e32 v17, v18
	v_mov_b32_e32 v82, v18
	v_mov_b32_e32 v83, v18
	v_mov_b32_e32 v84, v18
	v_mov_b32_e32 v85, v18
	v_mov_b32_e32 v86, v18
	v_mov_b32_e32 v87, v18
	v_mov_b32_e32 v88, v18
	v_mov_b32_e32 v89, v18
	v_mov_b32_e32 v50, v18
	v_mov_b32_e32 v51, v18
	v_mov_b32_e32 v52, v18
	v_mov_b32_e32 v53, v18
	v_mov_b32_e32 v58, v18
	v_mov_b32_e32 v59, v18
	v_mov_b32_e32 v60, v18
	v_mov_b32_e32 v61, v18
	v_mov_b32_e32 v26, v18
	v_mov_b32_e32 v27, v18
	v_mov_b32_e32 v28, v18
	v_mov_b32_e32 v29, v18
	v_mov_b32_e32 v30, v18
	v_mov_b32_e32 v31, v18
	v_mov_b32_e32 v32, v18
	v_mov_b32_e32 v33, v18
	v_mov_b32_e32 v2, v18
	v_mov_b32_e32 v3, v18
	v_mov_b32_e32 v4, v18
	v_mov_b32_e32 v5, v18
	v_mov_b32_e32 v6, v18
	v_mov_b32_e32 v7, v18
	v_mov_b32_e32 v8, v18
	v_mov_b32_e32 v9, v18
	s_andn2_b64 vcc, exec, s[4:5]
	s_cbranch_vccnz .LBB0_1023
	s_branch .LBB0_1024

.LBB0_1128:
	s_add_u32 s14, s0, 0xfffc0080
	s_addc_u32 s15, s1, -1
	s_cmp_eq_u32 s43, 12
	s_cselect_b32 s17, s25, s15
	s_cselect_b32 s16, s33, s14
	v_add_u32_e32 v140, s31, v143
	s_cselect_b32 s15, s23, s42
	s_cselect_b32 s14, s40, s41
	s_add_i32 s46, 0, 0x14000
	ds_read_b128 v[146:149], v140
	ds_read_b128 v[150:153], v140 offset:1024
	ds_read_b128 v[154:157], v140 offset:2048
	ds_read_b128 v[158:161], v140 offset:3072
	v_add_u32_e32 v140, s46, v143
	ds_read_b128 v[162:165], v140
	ds_read_b128 v[166:169], v140 offset:1024
	ds_read_b128 v[170:173], v140 offset:2048
	ds_read_b128 v[174:177], v140 offset:3072
	v_lshl_add_u64 v[140:141], s[0:1], 0, v[136:137]
	s_add_i32 m0, s21, 0xc000
	ds_read_b128 v[196:199], v145
	ds_read_b128 v[212:215], v145 offset:1024
	ds_read_b128 v[216:219], v145 offset:2048
	ds_read_b128 v[220:223], v145 offset:3072
	ds_read_b128 v[224:227], v145 offset:4096
	ds_read_b128 v[228:231], v145 offset:5120
	ds_read_b128 v[232:235], v145 offset:6144
	ds_read_b128 v[236:239], v145 offset:7168
	global_load_lds_dwordx4 v[140:141], off
	v_lshl_add_u64 v[140:141], s[0:1], 0, v[138:139]
	s_add_i32 m0, s21, 0xe000
	s_nop 0
	global_load_lds_dwordx4 v[140:141], off
	s_waitcnt vmcnt(8)
	s_waitcnt lgkmcnt(0)
	s_setprio 1
	s_barrier
	v_mfma_f32_16x16x32_bf16 v[126:129], v[146:149], v[196:199], v[126:129]
	v_mfma_f32_16x16x32_bf16 v[118:121], v[154:157], v[196:199], v[118:121]
	v_mfma_f32_16x16x32_bf16 v[110:113], v[146:149], v[216:219], v[110:113]
	v_mfma_f32_16x16x32_bf16 v[102:105], v[154:157], v[216:219], v[102:105]
	v_mfma_f32_16x16x32_bf16 v[94:97], v[146:149], v[224:227], v[94:97]
	v_mfma_f32_16x16x32_bf16 v[86:89], v[154:157], v[224:227], v[86:89]
	v_mfma_f32_16x16x32_bf16 v[78:81], v[146:149], v[232:235], v[78:81]
	v_mfma_f32_16x16x32_bf16 v[70:73], v[154:157], v[232:235], v[70:73]
	v_mfma_f32_16x16x32_bf16 v[126:129], v[150:153], v[212:215], v[126:129]
	v_mfma_f32_16x16x32_bf16 v[118:121], v[158:161], v[212:215], v[118:121]
	v_mfma_f32_16x16x32_bf16 v[110:113], v[150:153], v[220:223], v[110:113]
	v_mfma_f32_16x16x32_bf16 v[102:105], v[158:161], v[220:223], v[102:105]
	v_mfma_f32_16x16x32_bf16 v[94:97], v[150:153], v[228:231], v[94:97]
	v_mfma_f32_16x16x32_bf16 v[86:89], v[158:161], v[228:231], v[86:89]
	v_mfma_f32_16x16x32_bf16 v[78:81], v[150:153], v[236:239], v[78:81]
	v_mfma_f32_16x16x32_bf16 v[70:73], v[158:161], v[236:239], v[70:73]
	v_mfma_f32_16x16x32_bf16 v[122:125], v[162:165], v[196:199], v[122:125]
	v_mfma_f32_16x16x32_bf16 v[114:117], v[170:173], v[196:199], v[114:117]
	v_mfma_f32_16x16x32_bf16 v[106:109], v[162:165], v[216:219], v[106:109]
	v_mfma_f32_16x16x32_bf16 v[98:101], v[170:173], v[216:219], v[98:101]
	v_mfma_f32_16x16x32_bf16 v[90:93], v[162:165], v[224:227], v[90:93]
	v_mfma_f32_16x16x32_bf16 v[82:85], v[170:173], v[224:227], v[82:85]
	v_mfma_f32_16x16x32_bf16 v[74:77], v[162:165], v[232:235], v[74:77]
	v_mfma_f32_16x16x32_bf16 v[66:69], v[170:173], v[232:235], v[66:69]
	v_mfma_f32_16x16x32_bf16 v[122:125], v[166:169], v[212:215], v[122:125]
	v_mfma_f32_16x16x32_bf16 v[114:117], v[174:177], v[212:215], v[114:117]
	v_mfma_f32_16x16x32_bf16 v[106:109], v[166:169], v[220:223], v[106:109]
	v_mfma_f32_16x16x32_bf16 v[98:101], v[174:177], v[220:223], v[98:101]
	v_mfma_f32_16x16x32_bf16 v[90:93], v[166:169], v[228:231], v[90:93]
	v_mfma_f32_16x16x32_bf16 v[82:85], v[174:177], v[228:231], v[82:85]
	v_mfma_f32_16x16x32_bf16 v[74:77], v[166:169], v[236:239], v[74:77]
	v_mfma_f32_16x16x32_bf16 v[66:69], v[174:177], v[236:239], v[66:69]
	s_barrier
	s_setprio 0
	s_add_i32 s44, s31, s20
	v_lshl_add_u64 v[140:141], s[14:15], 0, v[178:179]
	s_mov_b32 m0, s44
	ds_read_b128 v[196:199], v145 offset:16384
	ds_read_b128 v[212:215], v145 offset:17408
	ds_read_b128 v[216:219], v145 offset:18432
	ds_read_b128 v[220:223], v145 offset:19456
	ds_read_b128 v[224:227], v145 offset:20480
	ds_read_b128 v[228:231], v145 offset:21504
	ds_read_b128 v[232:235], v145 offset:22528
	ds_read_b128 v[236:239], v145 offset:23552
	global_load_lds_dwordx4 v[140:141], off
	s_add_i32 m0, s44, 0x2000
	s_add_u32 s44, s14, 0x40000
	v_lshl_add_u64 v[202:203], s[14:15], 0, v[130:131]
	s_addc_u32 s45, s15, 0
	s_add_i32 s46, s46, s20
	global_load_lds_dwordx4 v[202:203], off
	v_lshl_add_u64 v[206:207], s[44:45], 0, v[178:179]
	s_mov_b32 m0, s46
	v_lshl_add_u64 v[240:241], s[16:17], 0, v[132:133]
	global_load_lds_dwordx4 v[206:207], off
	v_lshl_add_u64 v[206:207], s[44:45], 0, v[130:131]
	s_add_i32 m0, s46, 0x2000
	s_nop 0
	global_load_lds_dwordx4 v[206:207], off
	v_lshl_add_u64 v[206:207], s[16:17], 0, v[134:135]
	s_mov_b32 m0, s21
	s_nop 0
	global_load_lds_dwordx4 v[206:207], off
	s_mov_b32 m0, s38
	s_nop 0
	global_load_lds_dwordx4 v[240:241], off
	s_waitcnt vmcnt(8)
	s_waitcnt lgkmcnt(0)
	s_setprio 1
	s_barrier
	v_mfma_f32_16x16x32_bf16 v[62:65], v[146:149], v[196:199], v[62:65]
	v_mfma_f32_16x16x32_bf16 v[54:57], v[154:157], v[196:199], v[54:57]
	v_mfma_f32_16x16x32_bf16 v[46:49], v[146:149], v[216:219], v[46:49]
	v_mfma_f32_16x16x32_bf16 v[38:41], v[154:157], v[216:219], v[38:41]
	v_mfma_f32_16x16x32_bf16 v[30:33], v[146:149], v[224:227], v[30:33]
	v_mfma_f32_16x16x32_bf16 v[22:25], v[154:157], v[224:227], v[22:25]
	v_mfma_f32_16x16x32_bf16 v[14:17], v[146:149], v[232:235], v[14:17]
	v_mfma_f32_16x16x32_bf16 v[6:9], v[154:157], v[232:235], v[6:9]
	v_mfma_f32_16x16x32_bf16 v[62:65], v[150:153], v[212:215], v[62:65]
	v_mfma_f32_16x16x32_bf16 v[54:57], v[158:161], v[212:215], v[54:57]
	v_mfma_f32_16x16x32_bf16 v[46:49], v[150:153], v[220:223], v[46:49]
	v_mfma_f32_16x16x32_bf16 v[38:41], v[158:161], v[220:223], v[38:41]
	v_mfma_f32_16x16x32_bf16 v[30:33], v[150:153], v[228:231], v[30:33]
	v_mfma_f32_16x16x32_bf16 v[22:25], v[158:161], v[228:231], v[22:25]
	v_mfma_f32_16x16x32_bf16 v[14:17], v[150:153], v[236:239], v[14:17]
	v_mfma_f32_16x16x32_bf16 v[6:9], v[158:161], v[236:239], v[6:9]
	v_mfma_f32_16x16x32_bf16 v[58:61], v[162:165], v[196:199], v[58:61]
	v_mfma_f32_16x16x32_bf16 v[50:53], v[170:173], v[196:199], v[50:53]
	v_mfma_f32_16x16x32_bf16 v[42:45], v[162:165], v[216:219], v[42:45]
	v_mfma_f32_16x16x32_bf16 v[34:37], v[170:173], v[216:219], v[34:37]
	v_mfma_f32_16x16x32_bf16 v[26:29], v[162:165], v[224:227], v[26:29]
	v_mfma_f32_16x16x32_bf16 v[18:21], v[170:173], v[224:227], v[18:21]
	v_mfma_f32_16x16x32_bf16 v[10:13], v[162:165], v[232:235], v[10:13]
	v_mfma_f32_16x16x32_bf16 v[2:5], v[170:173], v[232:235], v[2:5]
	v_mfma_f32_16x16x32_bf16 v[58:61], v[166:169], v[212:215], v[58:61]
	v_mfma_f32_16x16x32_bf16 v[50:53], v[174:177], v[212:215], v[50:53]
	v_mfma_f32_16x16x32_bf16 v[42:45], v[166:169], v[220:223], v[42:45]
	v_mfma_f32_16x16x32_bf16 v[34:37], v[174:177], v[220:223], v[34:37]
	v_mfma_f32_16x16x32_bf16 v[26:29], v[166:169], v[228:231], v[26:29]
	v_mfma_f32_16x16x32_bf16 v[18:21], v[174:177], v[228:231], v[18:21]
	v_mfma_f32_16x16x32_bf16 v[10:13], v[166:169], v[236:239], v[10:13]
	v_mfma_f32_16x16x32_bf16 v[2:5], v[174:177], v[236:239], v[2:5]
	s_barrier
	s_setprio 0
	s_add_i32 s44, 0, 0x18000
	s_add_i32 s45, 0, 0x1c000
	v_add_u32_e32 v158, s44, v143
	v_add_u32_e32 v174, s45, v143
	ds_read_b128 v[146:149], v158
	ds_read_b128 v[150:153], v158 offset:1024
	ds_read_b128 v[154:157], v158 offset:2048
	ds_read_b128 v[158:161], v158 offset:3072
	ds_read_b128 v[162:165], v174
	ds_read_b128 v[166:169], v174 offset:1024
	ds_read_b128 v[170:173], v174 offset:2048
	ds_read_b128 v[174:177], v174 offset:3072
	s_add_u32 s16, s16, 0x40000
	s_addc_u32 s17, s17, 0
	s_mov_b32 m0, s39
	v_lshl_add_u64 v[242:243], s[16:17], 0, v[134:135]
	ds_read_b128 v[196:199], v145 offset:32768
	ds_read_b128 v[212:215], v145 offset:33792
	ds_read_b128 v[216:219], v145 offset:34816
	ds_read_b128 v[220:223], v145 offset:35840
	ds_read_b128 v[224:227], v145 offset:36864
	ds_read_b128 v[228:231], v145 offset:37888
	ds_read_b128 v[232:235], v145 offset:38912
	ds_read_b128 v[236:239], v145 offset:39936
	global_load_lds_dwordx4 v[242:243], off
	v_lshl_add_u64 v[242:243], s[16:17], 0, v[132:133]
	s_mov_b32 m0, s60
	s_nop 0
	global_load_lds_dwordx4 v[242:243], off
	s_waitcnt vmcnt(8)
	s_waitcnt lgkmcnt(0)
	s_setprio 1
	s_barrier
	v_mfma_f32_16x16x32_bf16 v[126:129], v[146:149], v[196:199], v[126:129]
	v_mfma_f32_16x16x32_bf16 v[118:121], v[154:157], v[196:199], v[118:121]
	v_mfma_f32_16x16x32_bf16 v[110:113], v[146:149], v[216:219], v[110:113]
	v_mfma_f32_16x16x32_bf16 v[102:105], v[154:157], v[216:219], v[102:105]
	v_mfma_f32_16x16x32_bf16 v[94:97], v[146:149], v[224:227], v[94:97]
	v_mfma_f32_16x16x32_bf16 v[86:89], v[154:157], v[224:227], v[86:89]
	v_mfma_f32_16x16x32_bf16 v[78:81], v[146:149], v[232:235], v[78:81]
	v_mfma_f32_16x16x32_bf16 v[70:73], v[154:157], v[232:235], v[70:73]
	v_mfma_f32_16x16x32_bf16 v[126:129], v[150:153], v[212:215], v[126:129]
	v_mfma_f32_16x16x32_bf16 v[118:121], v[158:161], v[212:215], v[118:121]
	v_mfma_f32_16x16x32_bf16 v[110:113], v[150:153], v[220:223], v[110:113]
	v_mfma_f32_16x16x32_bf16 v[102:105], v[158:161], v[220:223], v[102:105]
	v_mfma_f32_16x16x32_bf16 v[94:97], v[150:153], v[228:231], v[94:97]
	v_mfma_f32_16x16x32_bf16 v[86:89], v[158:161], v[228:231], v[86:89]
	v_mfma_f32_16x16x32_bf16 v[78:81], v[150:153], v[236:239], v[78:81]
	v_mfma_f32_16x16x32_bf16 v[70:73], v[158:161], v[236:239], v[70:73]
	v_mfma_f32_16x16x32_bf16 v[122:125], v[162:165], v[196:199], v[122:125]
	v_mfma_f32_16x16x32_bf16 v[114:117], v[170:173], v[196:199], v[114:117]
	v_mfma_f32_16x16x32_bf16 v[106:109], v[162:165], v[216:219], v[106:109]
	v_mfma_f32_16x16x32_bf16 v[98:101], v[170:173], v[216:219], v[98:101]
	v_mfma_f32_16x16x32_bf16 v[90:93], v[162:165], v[224:227], v[90:93]
	v_mfma_f32_16x16x32_bf16 v[82:85], v[170:173], v[224:227], v[82:85]
	v_mfma_f32_16x16x32_bf16 v[74:77], v[162:165], v[232:235], v[74:77]
	v_mfma_f32_16x16x32_bf16 v[66:69], v[170:173], v[232:235], v[66:69]
	v_mfma_f32_16x16x32_bf16 v[122:125], v[166:169], v[212:215], v[122:125]
	v_mfma_f32_16x16x32_bf16 v[114:117], v[174:177], v[212:215], v[114:117]
	v_mfma_f32_16x16x32_bf16 v[106:109], v[166:169], v[220:223], v[106:109]
	v_mfma_f32_16x16x32_bf16 v[98:101], v[174:177], v[220:223], v[98:101]
	v_mfma_f32_16x16x32_bf16 v[90:93], v[166:169], v[228:231], v[90:93]
	v_mfma_f32_16x16x32_bf16 v[82:85], v[174:177], v[228:231], v[82:85]
	v_mfma_f32_16x16x32_bf16 v[74:77], v[166:169], v[236:239], v[74:77]
	v_mfma_f32_16x16x32_bf16 v[66:69], v[174:177], v[236:239], v[66:69]
	s_barrier
	s_setprio 0
	s_add_i32 s16, s44, s20
	v_lshl_add_u64 v[140:141], v[140:141], 0, s[90:91]
	s_mov_b32 m0, s16
	ds_read_b128 v[196:199], v145 offset:49152
	ds_read_b128 v[212:215], v145 offset:50176
	ds_read_b128 v[216:219], v145 offset:51200
	ds_read_b128 v[220:223], v145 offset:52224
	ds_read_b128 v[224:227], v145 offset:53248
	ds_read_b128 v[228:231], v145 offset:54272
	ds_read_b128 v[232:235], v145 offset:55296
	ds_read_b128 v[236:239], v145 offset:56320
	global_load_lds_dwordx4 v[140:141], off
	s_add_i32 m0, s16, 0x2000
	s_add_u32 s14, s14, 0x40080
	v_lshl_add_u64 v[140:141], v[202:203], 0, s[90:91]
	s_addc_u32 s15, s15, 0
	s_add_i32 s16, s45, s20
	global_load_lds_dwordx4 v[140:141], off
	v_lshl_add_u64 v[140:141], s[14:15], 0, v[178:179]
	s_mov_b32 m0, s16
	s_nop 0
	global_load_lds_dwordx4 v[140:141], off
	v_lshl_add_u64 v[140:141], s[14:15], 0, v[130:131]
	s_add_i32 m0, s16, 0x2000
	s_nop 0
	global_load_lds_dwordx4 v[140:141], off
	v_lshl_add_u64 v[140:141], v[206:207], 0, s[90:91]
	s_mov_b32 m0, s61
	s_nop 0
	global_load_lds_dwordx4 v[140:141], off
	v_lshl_add_u64 v[140:141], v[240:241], 0, s[90:91]
	s_mov_b32 m0, s82
	s_nop 0
	global_load_lds_dwordx4 v[140:141], off
	s_waitcnt vmcnt(8)
	s_waitcnt lgkmcnt(0)
	s_setprio 1
	s_barrier
	v_mfma_f32_16x16x32_bf16 v[62:65], v[146:149], v[196:199], v[62:65]
	v_mfma_f32_16x16x32_bf16 v[54:57], v[154:157], v[196:199], v[54:57]
	v_mfma_f32_16x16x32_bf16 v[46:49], v[146:149], v[216:219], v[46:49]
	v_mfma_f32_16x16x32_bf16 v[38:41], v[154:157], v[216:219], v[38:41]
	v_mfma_f32_16x16x32_bf16 v[30:33], v[146:149], v[224:227], v[30:33]
	v_mfma_f32_16x16x32_bf16 v[22:25], v[154:157], v[224:227], v[22:25]
	v_mfma_f32_16x16x32_bf16 v[14:17], v[146:149], v[232:235], v[14:17]
	v_mfma_f32_16x16x32_bf16 v[6:9], v[154:157], v[232:235], v[6:9]
	v_mfma_f32_16x16x32_bf16 v[62:65], v[150:153], v[212:215], v[62:65]
	v_mfma_f32_16x16x32_bf16 v[54:57], v[158:161], v[212:215], v[54:57]
	v_mfma_f32_16x16x32_bf16 v[46:49], v[150:153], v[220:223], v[46:49]
	v_mfma_f32_16x16x32_bf16 v[38:41], v[158:161], v[220:223], v[38:41]
	v_mfma_f32_16x16x32_bf16 v[30:33], v[150:153], v[228:231], v[30:33]
	v_mfma_f32_16x16x32_bf16 v[22:25], v[158:161], v[228:231], v[22:25]
	v_mfma_f32_16x16x32_bf16 v[14:17], v[150:153], v[236:239], v[14:17]
	v_mfma_f32_16x16x32_bf16 v[6:9], v[158:161], v[236:239], v[6:9]
	v_mfma_f32_16x16x32_bf16 v[58:61], v[162:165], v[196:199], v[58:61]
	v_mfma_f32_16x16x32_bf16 v[50:53], v[170:173], v[196:199], v[50:53]
	v_mfma_f32_16x16x32_bf16 v[42:45], v[162:165], v[216:219], v[42:45]
	v_mfma_f32_16x16x32_bf16 v[34:37], v[170:173], v[216:219], v[34:37]
	v_mfma_f32_16x16x32_bf16 v[26:29], v[162:165], v[224:227], v[26:29]
	v_mfma_f32_16x16x32_bf16 v[18:21], v[170:173], v[224:227], v[18:21]
	v_mfma_f32_16x16x32_bf16 v[10:13], v[162:165], v[232:235], v[10:13]
	v_mfma_f32_16x16x32_bf16 v[2:5], v[170:173], v[232:235], v[2:5]
	v_mfma_f32_16x16x32_bf16 v[58:61], v[166:169], v[212:215], v[58:61]
	v_mfma_f32_16x16x32_bf16 v[50:53], v[174:177], v[212:215], v[50:53]
	v_mfma_f32_16x16x32_bf16 v[42:45], v[166:169], v[220:223], v[42:45]
	v_mfma_f32_16x16x32_bf16 v[34:37], v[174:177], v[220:223], v[34:37]
	v_mfma_f32_16x16x32_bf16 v[26:29], v[166:169], v[228:231], v[26:29]
	v_mfma_f32_16x16x32_bf16 v[18:21], v[174:177], v[228:231], v[18:21]
	v_mfma_f32_16x16x32_bf16 v[10:13], v[166:169], v[236:239], v[10:13]
	v_mfma_f32_16x16x32_bf16 v[2:5], v[174:177], v[236:239], v[2:5]
	s_barrier
	s_setprio 0
	s_add_i32 s43, s43, 2
	s_add_u32 s0, s0, 0x100
	s_addc_u32 s1, s1, 0
	s_add_u32 s41, s41, 0x100
	s_addc_u32 s42, s42, 0
	s_cmp_gt_u32 s43, 13
	s_cbranch_scc0 .LBB0_1128
	s_and_b64 vcc, exec, s[18:19]
	s_cbranch_vccz .LBB0_1131
	s_barrier

.LBB0_1149:
	s_add_u32 s14, s16, 0xfffc0080
	s_addc_u32 s15, s17, -1
	s_cmp_eq_u32 s49, 12
	s_cselect_b32 s39, s23, s15
	s_cselect_b32 s38, s45, s14
	v_add_u32_e32 v140, s31, v143
	s_cselect_b32 s15, s21, s48
	s_cselect_b32 s14, s46, s47
	s_add_i32 s60, 0, 0x14000
	ds_read_b128 v[146:149], v140
	ds_read_b128 v[150:153], v140 offset:1024
	ds_read_b128 v[154:157], v140 offset:2048
	ds_read_b128 v[158:161], v140 offset:3072
	v_add_u32_e32 v140, s60, v143
	ds_read_b128 v[162:165], v140
	ds_read_b128 v[166:169], v140 offset:1024
	ds_read_b128 v[170:173], v140 offset:2048
	ds_read_b128 v[174:177], v140 offset:3072
	v_lshl_add_u64 v[140:141], s[16:17], 0, v[136:137]
	s_add_i32 m0, s13, 0xc000
	ds_read_b128 v[196:199], v145
	ds_read_b128 v[212:215], v145 offset:1024
	ds_read_b128 v[216:219], v145 offset:2048
	ds_read_b128 v[220:223], v145 offset:3072
	ds_read_b128 v[224:227], v145 offset:4096
	ds_read_b128 v[228:231], v145 offset:5120
	ds_read_b128 v[232:235], v145 offset:6144
	ds_read_b128 v[236:239], v145 offset:7168
	global_load_lds_dwordx4 v[140:141], off
	v_lshl_add_u64 v[140:141], s[16:17], 0, v[138:139]
	s_add_i32 m0, s13, 0xe000
	s_nop 0
	global_load_lds_dwordx4 v[140:141], off
	s_waitcnt vmcnt(8)
	s_waitcnt lgkmcnt(0)
	s_setprio 1
	s_barrier
	v_mfma_f32_16x16x32_bf16 v[126:129], v[146:149], v[196:199], v[126:129]
	v_mfma_f32_16x16x32_bf16 v[122:125], v[154:157], v[196:199], v[122:125]
	v_mfma_f32_16x16x32_bf16 v[114:117], v[146:149], v[216:219], v[114:117]
	v_mfma_f32_16x16x32_bf16 v[106:109], v[154:157], v[216:219], v[106:109]
	v_mfma_f32_16x16x32_bf16 v[98:101], v[146:149], v[224:227], v[98:101]
	v_mfma_f32_16x16x32_bf16 v[90:93], v[154:157], v[224:227], v[90:93]
	v_mfma_f32_16x16x32_bf16 v[82:85], v[146:149], v[232:235], v[82:85]
	v_mfma_f32_16x16x32_bf16 v[74:77], v[154:157], v[232:235], v[74:77]
	v_mfma_f32_16x16x32_bf16 v[126:129], v[150:153], v[212:215], v[126:129]
	v_mfma_f32_16x16x32_bf16 v[122:125], v[158:161], v[212:215], v[122:125]
	v_mfma_f32_16x16x32_bf16 v[114:117], v[150:153], v[220:223], v[114:117]
	v_mfma_f32_16x16x32_bf16 v[106:109], v[158:161], v[220:223], v[106:109]
	v_mfma_f32_16x16x32_bf16 v[98:101], v[150:153], v[228:231], v[98:101]
	v_mfma_f32_16x16x32_bf16 v[90:93], v[158:161], v[228:231], v[90:93]
	v_mfma_f32_16x16x32_bf16 v[82:85], v[150:153], v[236:239], v[82:85]
	v_mfma_f32_16x16x32_bf16 v[74:77], v[158:161], v[236:239], v[74:77]
	v_mfma_f32_16x16x32_bf16 v[118:121], v[162:165], v[196:199], v[118:121]
	v_mfma_f32_16x16x32_bf16 v[110:113], v[170:173], v[196:199], v[110:113]
	v_mfma_f32_16x16x32_bf16 v[102:105], v[162:165], v[216:219], v[102:105]
	v_mfma_f32_16x16x32_bf16 v[94:97], v[170:173], v[216:219], v[94:97]
	v_mfma_f32_16x16x32_bf16 v[86:89], v[162:165], v[224:227], v[86:89]
	v_mfma_f32_16x16x32_bf16 v[78:81], v[170:173], v[224:227], v[78:81]
	v_mfma_f32_16x16x32_bf16 v[70:73], v[162:165], v[232:235], v[70:73]
	v_mfma_f32_16x16x32_bf16 v[66:69], v[170:173], v[232:235], v[66:69]
	v_mfma_f32_16x16x32_bf16 v[118:121], v[166:169], v[212:215], v[118:121]
	v_mfma_f32_16x16x32_bf16 v[110:113], v[174:177], v[212:215], v[110:113]
	v_mfma_f32_16x16x32_bf16 v[102:105], v[166:169], v[220:223], v[102:105]
	v_mfma_f32_16x16x32_bf16 v[94:97], v[174:177], v[220:223], v[94:97]
	v_mfma_f32_16x16x32_bf16 v[86:89], v[166:169], v[228:231], v[86:89]
	v_mfma_f32_16x16x32_bf16 v[78:81], v[174:177], v[228:231], v[78:81]
	v_mfma_f32_16x16x32_bf16 v[70:73], v[166:169], v[236:239], v[70:73]
	v_mfma_f32_16x16x32_bf16 v[66:69], v[174:177], v[236:239], v[66:69]
	s_barrier
	s_setprio 0
	s_add_i32 s50, s31, s12
	v_lshl_add_u64 v[140:141], s[14:15], 0, v[178:179]
	s_mov_b32 m0, s50
	ds_read_b128 v[196:199], v145 offset:16384
	ds_read_b128 v[212:215], v145 offset:17408
	ds_read_b128 v[216:219], v145 offset:18432
	ds_read_b128 v[220:223], v145 offset:19456
	ds_read_b128 v[224:227], v145 offset:20480
	ds_read_b128 v[228:231], v145 offset:21504
	ds_read_b128 v[232:235], v145 offset:22528
	ds_read_b128 v[236:239], v145 offset:23552
	global_load_lds_dwordx4 v[140:141], off
	s_add_i32 m0, s50, 0x2000
	s_add_u32 s50, s14, 0x40000
	v_lshl_add_u64 v[202:203], s[14:15], 0, v[130:131]
	s_addc_u32 s51, s15, 0
	s_add_i32 s60, s60, s12
	global_load_lds_dwordx4 v[202:203], off
	v_lshl_add_u64 v[206:207], s[50:51], 0, v[178:179]
	s_mov_b32 m0, s60
	v_lshl_add_u64 v[240:241], s[38:39], 0, v[132:133]
	global_load_lds_dwordx4 v[206:207], off
	v_lshl_add_u64 v[206:207], s[50:51], 0, v[130:131]
	s_add_i32 m0, s60, 0x2000
	s_nop 0
	global_load_lds_dwordx4 v[206:207], off
	v_lshl_add_u64 v[206:207], s[38:39], 0, v[134:135]
	s_mov_b32 m0, s13
	s_nop 0
	global_load_lds_dwordx4 v[206:207], off
	s_mov_b32 m0, s28
	s_nop 0
	global_load_lds_dwordx4 v[240:241], off
	s_waitcnt vmcnt(8)
	s_waitcnt lgkmcnt(0)
	s_setprio 1
	s_barrier
	v_mfma_f32_16x16x32_bf16 v[62:65], v[146:149], v[196:199], v[62:65]
	v_mfma_f32_16x16x32_bf16 v[58:61], v[154:157], v[196:199], v[58:61]
	v_mfma_f32_16x16x32_bf16 v[50:53], v[146:149], v[216:219], v[50:53]
	v_mfma_f32_16x16x32_bf16 v[42:45], v[154:157], v[216:219], v[42:45]
	v_mfma_f32_16x16x32_bf16 v[34:37], v[146:149], v[224:227], v[34:37]
	v_mfma_f32_16x16x32_bf16 v[26:29], v[154:157], v[224:227], v[26:29]
	v_mfma_f32_16x16x32_bf16 v[18:21], v[146:149], v[232:235], v[18:21]
	v_mfma_f32_16x16x32_bf16 v[10:13], v[154:157], v[232:235], v[10:13]
	v_mfma_f32_16x16x32_bf16 v[62:65], v[150:153], v[212:215], v[62:65]
	v_mfma_f32_16x16x32_bf16 v[58:61], v[158:161], v[212:215], v[58:61]
	v_mfma_f32_16x16x32_bf16 v[50:53], v[150:153], v[220:223], v[50:53]
	v_mfma_f32_16x16x32_bf16 v[42:45], v[158:161], v[220:223], v[42:45]
	v_mfma_f32_16x16x32_bf16 v[34:37], v[150:153], v[228:231], v[34:37]
	v_mfma_f32_16x16x32_bf16 v[26:29], v[158:161], v[228:231], v[26:29]
	v_mfma_f32_16x16x32_bf16 v[18:21], v[150:153], v[236:239], v[18:21]
	v_mfma_f32_16x16x32_bf16 v[10:13], v[158:161], v[236:239], v[10:13]
	v_mfma_f32_16x16x32_bf16 v[54:57], v[162:165], v[196:199], v[54:57]
	v_mfma_f32_16x16x32_bf16 v[46:49], v[170:173], v[196:199], v[46:49]
	v_mfma_f32_16x16x32_bf16 v[38:41], v[162:165], v[216:219], v[38:41]
	v_mfma_f32_16x16x32_bf16 v[30:33], v[170:173], v[216:219], v[30:33]
	v_mfma_f32_16x16x32_bf16 v[22:25], v[162:165], v[224:227], v[22:25]
	v_mfma_f32_16x16x32_bf16 v[14:17], v[170:173], v[224:227], v[14:17]
	v_mfma_f32_16x16x32_bf16 v[6:9], v[162:165], v[232:235], v[6:9]
	v_mfma_f32_16x16x32_bf16 v[2:5], v[170:173], v[232:235], v[2:5]
	v_mfma_f32_16x16x32_bf16 v[54:57], v[166:169], v[212:215], v[54:57]
	v_mfma_f32_16x16x32_bf16 v[46:49], v[174:177], v[212:215], v[46:49]
	v_mfma_f32_16x16x32_bf16 v[38:41], v[166:169], v[220:223], v[38:41]
	v_mfma_f32_16x16x32_bf16 v[30:33], v[174:177], v[220:223], v[30:33]
	v_mfma_f32_16x16x32_bf16 v[22:25], v[166:169], v[228:231], v[22:25]
	v_mfma_f32_16x16x32_bf16 v[14:17], v[174:177], v[228:231], v[14:17]
	v_mfma_f32_16x16x32_bf16 v[6:9], v[166:169], v[236:239], v[6:9]
	v_mfma_f32_16x16x32_bf16 v[2:5], v[174:177], v[236:239], v[2:5]
	s_barrier
	s_setprio 0
	s_add_i32 s50, 0, 0x18000
	s_add_i32 s51, 0, 0x1c000
	v_add_u32_e32 v158, s50, v143
	v_add_u32_e32 v174, s51, v143
	ds_read_b128 v[146:149], v158
	ds_read_b128 v[150:153], v158 offset:1024
	ds_read_b128 v[154:157], v158 offset:2048
	ds_read_b128 v[158:161], v158 offset:3072
	ds_read_b128 v[162:165], v174
	ds_read_b128 v[166:169], v174 offset:1024
	ds_read_b128 v[170:173], v174 offset:2048
	ds_read_b128 v[174:177], v174 offset:3072
	s_add_u32 s38, s38, 0x40000
	s_addc_u32 s39, s39, 0
	s_mov_b32 m0, s29
	v_lshl_add_u64 v[242:243], s[38:39], 0, v[134:135]
	ds_read_b128 v[196:199], v145 offset:32768
	ds_read_b128 v[212:215], v145 offset:33792
	ds_read_b128 v[216:219], v145 offset:34816
	ds_read_b128 v[220:223], v145 offset:35840
	ds_read_b128 v[224:227], v145 offset:36864
	ds_read_b128 v[228:231], v145 offset:37888
	ds_read_b128 v[232:235], v145 offset:38912
	ds_read_b128 v[236:239], v145 offset:39936
	global_load_lds_dwordx4 v[242:243], off
	v_lshl_add_u64 v[242:243], s[38:39], 0, v[132:133]
	s_mov_b32 m0, s33
	s_nop 0
	global_load_lds_dwordx4 v[242:243], off
	s_waitcnt vmcnt(8)
	s_waitcnt lgkmcnt(0)
	s_setprio 1
	s_barrier
	v_mfma_f32_16x16x32_bf16 v[126:129], v[146:149], v[196:199], v[126:129]
	v_mfma_f32_16x16x32_bf16 v[122:125], v[154:157], v[196:199], v[122:125]
	v_mfma_f32_16x16x32_bf16 v[114:117], v[146:149], v[216:219], v[114:117]
	v_mfma_f32_16x16x32_bf16 v[106:109], v[154:157], v[216:219], v[106:109]
	v_mfma_f32_16x16x32_bf16 v[98:101], v[146:149], v[224:227], v[98:101]
	v_mfma_f32_16x16x32_bf16 v[90:93], v[154:157], v[224:227], v[90:93]
	v_mfma_f32_16x16x32_bf16 v[82:85], v[146:149], v[232:235], v[82:85]
	v_mfma_f32_16x16x32_bf16 v[74:77], v[154:157], v[232:235], v[74:77]
	v_mfma_f32_16x16x32_bf16 v[126:129], v[150:153], v[212:215], v[126:129]
	v_mfma_f32_16x16x32_bf16 v[122:125], v[158:161], v[212:215], v[122:125]
	v_mfma_f32_16x16x32_bf16 v[114:117], v[150:153], v[220:223], v[114:117]
	v_mfma_f32_16x16x32_bf16 v[106:109], v[158:161], v[220:223], v[106:109]
	v_mfma_f32_16x16x32_bf16 v[98:101], v[150:153], v[228:231], v[98:101]
	v_mfma_f32_16x16x32_bf16 v[90:93], v[158:161], v[228:231], v[90:93]
	v_mfma_f32_16x16x32_bf16 v[82:85], v[150:153], v[236:239], v[82:85]
	v_mfma_f32_16x16x32_bf16 v[74:77], v[158:161], v[236:239], v[74:77]
	v_mfma_f32_16x16x32_bf16 v[118:121], v[162:165], v[196:199], v[118:121]
	v_mfma_f32_16x16x32_bf16 v[110:113], v[170:173], v[196:199], v[110:113]
	v_mfma_f32_16x16x32_bf16 v[102:105], v[162:165], v[216:219], v[102:105]
	v_mfma_f32_16x16x32_bf16 v[94:97], v[170:173], v[216:219], v[94:97]
	v_mfma_f32_16x16x32_bf16 v[86:89], v[162:165], v[224:227], v[86:89]
	v_mfma_f32_16x16x32_bf16 v[78:81], v[170:173], v[224:227], v[78:81]
	v_mfma_f32_16x16x32_bf16 v[70:73], v[162:165], v[232:235], v[70:73]
	v_mfma_f32_16x16x32_bf16 v[66:69], v[170:173], v[232:235], v[66:69]
	v_mfma_f32_16x16x32_bf16 v[118:121], v[166:169], v[212:215], v[118:121]
	v_mfma_f32_16x16x32_bf16 v[110:113], v[174:177], v[212:215], v[110:113]
	v_mfma_f32_16x16x32_bf16 v[102:105], v[166:169], v[220:223], v[102:105]
	v_mfma_f32_16x16x32_bf16 v[94:97], v[174:177], v[220:223], v[94:97]
	v_mfma_f32_16x16x32_bf16 v[86:89], v[166:169], v[228:231], v[86:89]
	v_mfma_f32_16x16x32_bf16 v[78:81], v[174:177], v[228:231], v[78:81]
	v_mfma_f32_16x16x32_bf16 v[70:73], v[166:169], v[236:239], v[70:73]
	v_mfma_f32_16x16x32_bf16 v[66:69], v[174:177], v[236:239], v[66:69]
	s_barrier
	s_setprio 0
	s_add_i32 s38, s50, s12
	v_lshl_add_u64 v[140:141], v[140:141], 0, s[90:91]
	s_mov_b32 m0, s38
	ds_read_b128 v[196:199], v145 offset:49152
	ds_read_b128 v[212:215], v145 offset:50176
	ds_read_b128 v[216:219], v145 offset:51200
	ds_read_b128 v[220:223], v145 offset:52224
	ds_read_b128 v[224:227], v145 offset:53248
	ds_read_b128 v[228:231], v145 offset:54272
	ds_read_b128 v[232:235], v145 offset:55296
	ds_read_b128 v[236:239], v145 offset:56320
	global_load_lds_dwordx4 v[140:141], off
	s_add_i32 m0, s38, 0x2000
	s_add_u32 s14, s14, 0x40080
	v_lshl_add_u64 v[140:141], v[202:203], 0, s[90:91]
	s_addc_u32 s15, s15, 0
	s_add_i32 s38, s51, s12
	global_load_lds_dwordx4 v[140:141], off
	v_lshl_add_u64 v[140:141], s[14:15], 0, v[178:179]
	s_mov_b32 m0, s38
	s_nop 0
	global_load_lds_dwordx4 v[140:141], off
	v_lshl_add_u64 v[140:141], s[14:15], 0, v[130:131]
	s_add_i32 m0, s38, 0x2000
	s_nop 0
	global_load_lds_dwordx4 v[140:141], off
	v_lshl_add_u64 v[140:141], v[206:207], 0, s[90:91]
	s_mov_b32 m0, s40
	s_nop 0
	global_load_lds_dwordx4 v[140:141], off
	v_lshl_add_u64 v[140:141], v[240:241], 0, s[90:91]
	s_mov_b32 m0, s41
	s_nop 0
	global_load_lds_dwordx4 v[140:141], off
	s_waitcnt vmcnt(8)
	s_waitcnt lgkmcnt(0)
	s_setprio 1
	s_barrier
	v_mfma_f32_16x16x32_bf16 v[62:65], v[146:149], v[196:199], v[62:65]
	v_mfma_f32_16x16x32_bf16 v[58:61], v[154:157], v[196:199], v[58:61]
	v_mfma_f32_16x16x32_bf16 v[50:53], v[146:149], v[216:219], v[50:53]
	v_mfma_f32_16x16x32_bf16 v[42:45], v[154:157], v[216:219], v[42:45]
	v_mfma_f32_16x16x32_bf16 v[34:37], v[146:149], v[224:227], v[34:37]
	v_mfma_f32_16x16x32_bf16 v[26:29], v[154:157], v[224:227], v[26:29]
	v_mfma_f32_16x16x32_bf16 v[18:21], v[146:149], v[232:235], v[18:21]
	v_mfma_f32_16x16x32_bf16 v[10:13], v[154:157], v[232:235], v[10:13]
	v_mfma_f32_16x16x32_bf16 v[62:65], v[150:153], v[212:215], v[62:65]
	v_mfma_f32_16x16x32_bf16 v[58:61], v[158:161], v[212:215], v[58:61]
	v_mfma_f32_16x16x32_bf16 v[50:53], v[150:153], v[220:223], v[50:53]
	v_mfma_f32_16x16x32_bf16 v[42:45], v[158:161], v[220:223], v[42:45]
	v_mfma_f32_16x16x32_bf16 v[34:37], v[150:153], v[228:231], v[34:37]
	v_mfma_f32_16x16x32_bf16 v[26:29], v[158:161], v[228:231], v[26:29]
	v_mfma_f32_16x16x32_bf16 v[18:21], v[150:153], v[236:239], v[18:21]
	v_mfma_f32_16x16x32_bf16 v[10:13], v[158:161], v[236:239], v[10:13]
	v_mfma_f32_16x16x32_bf16 v[54:57], v[162:165], v[196:199], v[54:57]
	v_mfma_f32_16x16x32_bf16 v[46:49], v[170:173], v[196:199], v[46:49]
	v_mfma_f32_16x16x32_bf16 v[38:41], v[162:165], v[216:219], v[38:41]
	v_mfma_f32_16x16x32_bf16 v[30:33], v[170:173], v[216:219], v[30:33]
	v_mfma_f32_16x16x32_bf16 v[22:25], v[162:165], v[224:227], v[22:25]
	v_mfma_f32_16x16x32_bf16 v[14:17], v[170:173], v[224:227], v[14:17]
	v_mfma_f32_16x16x32_bf16 v[6:9], v[162:165], v[232:235], v[6:9]
	v_mfma_f32_16x16x32_bf16 v[2:5], v[170:173], v[232:235], v[2:5]
	v_mfma_f32_16x16x32_bf16 v[54:57], v[166:169], v[212:215], v[54:57]
	v_mfma_f32_16x16x32_bf16 v[46:49], v[174:177], v[212:215], v[46:49]
	v_mfma_f32_16x16x32_bf16 v[38:41], v[166:169], v[220:223], v[38:41]
	v_mfma_f32_16x16x32_bf16 v[30:33], v[174:177], v[220:223], v[30:33]
	v_mfma_f32_16x16x32_bf16 v[22:25], v[166:169], v[228:231], v[22:25]
	v_mfma_f32_16x16x32_bf16 v[14:17], v[174:177], v[228:231], v[14:17]
	v_mfma_f32_16x16x32_bf16 v[6:9], v[166:169], v[236:239], v[6:9]
	v_mfma_f32_16x16x32_bf16 v[2:5], v[174:177], v[236:239], v[2:5]
	s_barrier
	s_setprio 0
	s_add_i32 s49, s49, 2
	s_add_u32 s16, s16, 0x100
	s_addc_u32 s17, s17, 0
	s_add_u32 s47, s47, 0x100
	s_addc_u32 s48, s48, 0
	s_cmp_gt_u32 s49, 13
	s_cbranch_scc0 .LBB0_1149
	s_and_b64 vcc, exec, s[8:9]
	s_cbranch_vccz .LBB0_1152
	s_barrier

.LBB0_1224:
	s_add_u32 s14, s28, s16
	s_addc_u32 s15, s29, s17
	s_add_u32 s14, s14, 0x100
	s_addc_u32 s15, s15, 0
	s_add_u32 s49, s46, s16
	s_addc_u32 s50, s47, s17
	s_cmpk_eq_i32 s16, 0x1500
	s_cselect_b32 s21, s11, s15
	s_cselect_b32 s20, s10, s14
	v_add_u32_e32 v147, s31, v145
	s_cselect_b32 s15, s1, s50
	s_cselect_b32 s14, s0, s49
	s_add_i32 s49, 0, 0x14000
	ds_read_b128 v[148:151], v147
	ds_read_b128 v[152:155], v147 offset:1024
	ds_read_b128 v[156:159], v147 offset:2048
	ds_read_b128 v[160:163], v147 offset:3072
	v_add_u32_e32 v147, s49, v145
	ds_read_b128 v[170:173], v147
	ds_read_b128 v[174:177], v147 offset:1024
	ds_read_b128 v[196:199], v147 offset:2048
	ds_read_b128 v[212:215], v147 offset:3072
	v_lshl_add_u64 v[164:165], v[140:141], 0, s[16:17]
	s_add_i32 m0, s33, 0xc000
	ds_read_b128 v[216:219], v146
	ds_read_b128 v[220:223], v146 offset:1024
	ds_read_b128 v[224:227], v146 offset:2048
	ds_read_b128 v[228:231], v146 offset:3072
	ds_read_b128 v[232:235], v146 offset:4096
	ds_read_b128 v[236:239], v146 offset:5120
	ds_read_b128 v[240:243], v146 offset:6144
	ds_read_b128 v[244:247], v146 offset:7168
	global_load_lds_dwordx4 v[164:165], off
	v_lshl_add_u64 v[164:165], v[142:143], 0, s[16:17]
	s_add_i32 m0, s33, 0xe000
	s_nop 0
	global_load_lds_dwordx4 v[164:165], off
	s_waitcnt vmcnt(8)
	s_waitcnt lgkmcnt(0)
	s_setprio 1
	s_barrier
	v_mfma_f32_16x16x32_bf16 v[6:9], v[148:151], v[216:219], v[6:9]
	v_mfma_f32_16x16x32_bf16 v[2:5], v[156:159], v[216:219], v[2:5]
	v_mfma_f32_16x16x32_bf16 v[38:41], v[148:151], v[224:227], v[38:41]
	v_mfma_f32_16x16x32_bf16 v[34:37], v[156:159], v[224:227], v[34:37]
	v_mfma_f32_16x16x32_bf16 v[62:65], v[148:151], v[232:235], v[62:65]
	v_mfma_f32_16x16x32_bf16 v[58:61], v[156:159], v[232:235], v[58:61]
	v_mfma_f32_16x16x32_bf16 v[86:89], v[148:151], v[240:243], v[86:89]
	v_mfma_f32_16x16x32_bf16 v[82:85], v[156:159], v[240:243], v[82:85]
	v_mfma_f32_16x16x32_bf16 v[6:9], v[152:155], v[220:223], v[6:9]
	v_mfma_f32_16x16x32_bf16 v[2:5], v[160:163], v[220:223], v[2:5]
	v_mfma_f32_16x16x32_bf16 v[38:41], v[152:155], v[228:231], v[38:41]
	v_mfma_f32_16x16x32_bf16 v[34:37], v[160:163], v[228:231], v[34:37]
	v_mfma_f32_16x16x32_bf16 v[62:65], v[152:155], v[236:239], v[62:65]
	v_mfma_f32_16x16x32_bf16 v[58:61], v[160:163], v[236:239], v[58:61]
	v_mfma_f32_16x16x32_bf16 v[86:89], v[152:155], v[244:247], v[86:89]
	v_mfma_f32_16x16x32_bf16 v[82:85], v[160:163], v[244:247], v[82:85]
	v_mfma_f32_16x16x32_bf16 v[18:21], v[170:173], v[216:219], v[18:21]
	v_mfma_f32_16x16x32_bf16 v[14:17], v[196:199], v[216:219], v[14:17]
	v_mfma_f32_16x16x32_bf16 v[46:49], v[170:173], v[224:227], v[46:49]
	v_mfma_f32_16x16x32_bf16 v[42:45], v[196:199], v[224:227], v[42:45]
	v_mfma_f32_16x16x32_bf16 v[70:73], v[170:173], v[232:235], v[70:73]
	v_mfma_f32_16x16x32_bf16 v[66:69], v[196:199], v[232:235], v[66:69]
	v_mfma_f32_16x16x32_bf16 v[94:97], v[170:173], v[240:243], v[94:97]
	v_mfma_f32_16x16x32_bf16 v[90:93], v[196:199], v[240:243], v[90:93]
	v_mfma_f32_16x16x32_bf16 v[18:21], v[174:177], v[220:223], v[18:21]
	v_mfma_f32_16x16x32_bf16 v[14:17], v[212:215], v[220:223], v[14:17]
	v_mfma_f32_16x16x32_bf16 v[46:49], v[174:177], v[228:231], v[46:49]
	v_mfma_f32_16x16x32_bf16 v[42:45], v[212:215], v[228:231], v[42:45]
	v_mfma_f32_16x16x32_bf16 v[70:73], v[174:177], v[236:239], v[70:73]
	v_mfma_f32_16x16x32_bf16 v[66:69], v[212:215], v[236:239], v[66:69]
	v_mfma_f32_16x16x32_bf16 v[94:97], v[174:177], v[244:247], v[94:97]
	v_mfma_f32_16x16x32_bf16 v[90:93], v[212:215], v[244:247], v[90:93]
	s_barrier
	s_setprio 0
	s_add_i32 s50, s31, s39
	v_lshl_add_u64 v[164:165], s[14:15], 0, v[178:179]
	s_mov_b32 m0, s50
	ds_read_b128 v[216:219], v146 offset:16384
	ds_read_b128 v[220:223], v146 offset:17408
	ds_read_b128 v[224:227], v146 offset:18432
	ds_read_b128 v[228:231], v146 offset:19456
	ds_read_b128 v[232:235], v146 offset:20480
	ds_read_b128 v[236:239], v146 offset:21504
	ds_read_b128 v[240:243], v146 offset:22528
	ds_read_b128 v[244:247], v146 offset:23552
	global_load_lds_dwordx4 v[164:165], off
	s_add_i32 m0, s50, 0x2000
	s_add_u32 s50, s14, 0xb0000
	v_lshl_add_u64 v[202:203], s[14:15], 0, v[130:131]
	s_addc_u32 s51, s15, 0
	s_add_i32 s49, s49, s39
	global_load_lds_dwordx4 v[202:203], off
	v_lshl_add_u64 v[206:207], s[50:51], 0, v[178:179]
	s_mov_b32 m0, s49
	v_lshl_add_u64 v[248:249], s[20:21], 0, v[132:133]
	global_load_lds_dwordx4 v[206:207], off
	v_lshl_add_u64 v[206:207], s[50:51], 0, v[130:131]
	s_add_i32 m0, s49, 0x2000
	s_nop 0
	global_load_lds_dwordx4 v[206:207], off
	v_lshl_add_u64 v[206:207], s[20:21], 0, v[134:135]
	s_mov_b32 m0, s33
	s_nop 0
	global_load_lds_dwordx4 v[206:207], off
	s_mov_b32 m0, s94
	s_nop 0
	global_load_lds_dwordx4 v[248:249], off
	s_waitcnt vmcnt(8)
	s_waitcnt lgkmcnt(0)
	s_setprio 1
	s_barrier
	v_mfma_f32_16x16x32_bf16 v[110:113], v[148:151], v[216:219], v[110:113]
	v_mfma_f32_16x16x32_bf16 v[106:109], v[156:159], v[216:219], v[106:109]
	v_mfma_f32_16x16x32_bf16 v[126:129], v[148:151], v[224:227], v[126:129]
	v_mfma_f32_16x16x32_bf16 v[118:121], v[156:159], v[224:227], v[118:121]
	v_mfma_f32_16x16x32_bf16 v[78:81], v[148:151], v[232:235], v[78:81]
	v_mfma_f32_16x16x32_bf16 v[74:77], v[156:159], v[232:235], v[74:77]
	v_mfma_f32_16x16x32_bf16 v[30:33], v[148:151], v[240:243], v[30:33]
	v_mfma_f32_16x16x32_bf16 v[26:29], v[156:159], v[240:243], v[26:29]
	v_mfma_f32_16x16x32_bf16 v[110:113], v[152:155], v[220:223], v[110:113]
	v_mfma_f32_16x16x32_bf16 v[106:109], v[160:163], v[220:223], v[106:109]
	v_mfma_f32_16x16x32_bf16 v[126:129], v[152:155], v[228:231], v[126:129]
	v_mfma_f32_16x16x32_bf16 v[118:121], v[160:163], v[228:231], v[118:121]
	v_mfma_f32_16x16x32_bf16 v[78:81], v[152:155], v[236:239], v[78:81]
	v_mfma_f32_16x16x32_bf16 v[74:77], v[160:163], v[236:239], v[74:77]
	v_mfma_f32_16x16x32_bf16 v[30:33], v[152:155], v[244:247], v[30:33]
	v_mfma_f32_16x16x32_bf16 v[26:29], v[160:163], v[244:247], v[26:29]
	v_mfma_f32_16x16x32_bf16 v[122:125], v[170:173], v[216:219], v[122:125]
	v_mfma_f32_16x16x32_bf16 v[114:117], v[196:199], v[216:219], v[114:117]
	v_mfma_f32_16x16x32_bf16 v[102:105], v[170:173], v[224:227], v[102:105]
	v_mfma_f32_16x16x32_bf16 v[98:101], v[196:199], v[224:227], v[98:101]
	v_mfma_f32_16x16x32_bf16 v[54:57], v[170:173], v[232:235], v[54:57]
	v_mfma_f32_16x16x32_bf16 v[50:53], v[196:199], v[232:235], v[50:53]
	v_mfma_f32_16x16x32_bf16 v[22:25], v[170:173], v[240:243], v[22:25]
	v_mfma_f32_16x16x32_bf16 v[10:13], v[196:199], v[240:243], v[10:13]
	v_mfma_f32_16x16x32_bf16 v[122:125], v[174:177], v[220:223], v[122:125]
	v_mfma_f32_16x16x32_bf16 v[114:117], v[212:215], v[220:223], v[114:117]
	v_mfma_f32_16x16x32_bf16 v[102:105], v[174:177], v[228:231], v[102:105]
	v_mfma_f32_16x16x32_bf16 v[98:101], v[212:215], v[228:231], v[98:101]
	v_mfma_f32_16x16x32_bf16 v[54:57], v[174:177], v[236:239], v[54:57]
	v_mfma_f32_16x16x32_bf16 v[50:53], v[212:215], v[236:239], v[50:53]
	v_mfma_f32_16x16x32_bf16 v[22:25], v[174:177], v[244:247], v[22:25]
	v_mfma_f32_16x16x32_bf16 v[10:13], v[212:215], v[244:247], v[10:13]
	s_barrier
	s_setprio 0
	s_add_i32 s49, 0, 0x18000
	v_add_u32_e32 v147, s49, v145
	s_add_i32 s50, 0, 0x1c000
	ds_read_b128 v[148:151], v147
	ds_read_b128 v[152:155], v147 offset:1024
	ds_read_b128 v[156:159], v147 offset:2048
	ds_read_b128 v[160:163], v147 offset:3072
	v_add_u32_e32 v147, s50, v145
	ds_read_b128 v[170:173], v147
	ds_read_b128 v[174:177], v147 offset:1024
	ds_read_b128 v[196:199], v147 offset:2048
	ds_read_b128 v[212:215], v147 offset:3072
	s_add_u32 s20, s20, 0xb0000
	s_addc_u32 s21, s21, 0
	s_mov_b32 m0, s4
	v_lshl_add_u64 v[250:251], s[20:21], 0, v[134:135]
	ds_read_b128 v[216:219], v146 offset:32768
	ds_read_b128 v[220:223], v146 offset:33792
	ds_read_b128 v[224:227], v146 offset:34816
	ds_read_b128 v[228:231], v146 offset:35840
	ds_read_b128 v[232:235], v146 offset:36864
	ds_read_b128 v[236:239], v146 offset:37888
	ds_read_b128 v[240:243], v146 offset:38912
	ds_read_b128 v[244:247], v146 offset:39936
	global_load_lds_dwordx4 v[250:251], off
	v_lshl_add_u64 v[250:251], s[20:21], 0, v[132:133]
	s_mov_b32 m0, s5
	s_nop 0
	global_load_lds_dwordx4 v[250:251], off
	s_waitcnt vmcnt(8)
	s_waitcnt lgkmcnt(0)
	s_setprio 1
	s_barrier
	v_mfma_f32_16x16x32_bf16 v[6:9], v[148:151], v[216:219], v[6:9]
	v_mfma_f32_16x16x32_bf16 v[2:5], v[156:159], v[216:219], v[2:5]
	v_mfma_f32_16x16x32_bf16 v[38:41], v[148:151], v[224:227], v[38:41]
	v_mfma_f32_16x16x32_bf16 v[34:37], v[156:159], v[224:227], v[34:37]
	v_mfma_f32_16x16x32_bf16 v[62:65], v[148:151], v[232:235], v[62:65]
	v_mfma_f32_16x16x32_bf16 v[58:61], v[156:159], v[232:235], v[58:61]
	v_mfma_f32_16x16x32_bf16 v[86:89], v[148:151], v[240:243], v[86:89]
	v_mfma_f32_16x16x32_bf16 v[82:85], v[156:159], v[240:243], v[82:85]
	v_mfma_f32_16x16x32_bf16 v[6:9], v[152:155], v[220:223], v[6:9]
	v_mfma_f32_16x16x32_bf16 v[2:5], v[160:163], v[220:223], v[2:5]
	v_mfma_f32_16x16x32_bf16 v[38:41], v[152:155], v[228:231], v[38:41]
	v_mfma_f32_16x16x32_bf16 v[34:37], v[160:163], v[228:231], v[34:37]
	v_mfma_f32_16x16x32_bf16 v[62:65], v[152:155], v[236:239], v[62:65]
	v_mfma_f32_16x16x32_bf16 v[58:61], v[160:163], v[236:239], v[58:61]
	v_mfma_f32_16x16x32_bf16 v[86:89], v[152:155], v[244:247], v[86:89]
	v_mfma_f32_16x16x32_bf16 v[82:85], v[160:163], v[244:247], v[82:85]
	v_mfma_f32_16x16x32_bf16 v[18:21], v[170:173], v[216:219], v[18:21]
	v_mfma_f32_16x16x32_bf16 v[14:17], v[196:199], v[216:219], v[14:17]
	v_mfma_f32_16x16x32_bf16 v[46:49], v[170:173], v[224:227], v[46:49]
	v_mfma_f32_16x16x32_bf16 v[42:45], v[196:199], v[224:227], v[42:45]
	v_mfma_f32_16x16x32_bf16 v[70:73], v[170:173], v[232:235], v[70:73]
	v_mfma_f32_16x16x32_bf16 v[66:69], v[196:199], v[232:235], v[66:69]
	v_mfma_f32_16x16x32_bf16 v[94:97], v[170:173], v[240:243], v[94:97]
	v_mfma_f32_16x16x32_bf16 v[90:93], v[196:199], v[240:243], v[90:93]
	v_mfma_f32_16x16x32_bf16 v[18:21], v[174:177], v[220:223], v[18:21]
	v_mfma_f32_16x16x32_bf16 v[14:17], v[212:215], v[220:223], v[14:17]
	v_mfma_f32_16x16x32_bf16 v[46:49], v[174:177], v[228:231], v[46:49]
	v_mfma_f32_16x16x32_bf16 v[42:45], v[212:215], v[228:231], v[42:45]
	v_mfma_f32_16x16x32_bf16 v[70:73], v[174:177], v[236:239], v[70:73]
	v_mfma_f32_16x16x32_bf16 v[66:69], v[212:215], v[236:239], v[66:69]
	v_mfma_f32_16x16x32_bf16 v[94:97], v[174:177], v[244:247], v[94:97]
	v_mfma_f32_16x16x32_bf16 v[90:93], v[212:215], v[244:247], v[90:93]
	s_barrier
	s_setprio 0
	s_add_i32 s20, s49, s39
	v_lshl_add_u64 v[164:165], v[164:165], 0, s[90:91]
	s_mov_b32 m0, s20
	ds_read_b128 v[216:219], v146 offset:49152
	ds_read_b128 v[220:223], v146 offset:50176
	ds_read_b128 v[224:227], v146 offset:51200
	ds_read_b128 v[228:231], v146 offset:52224
	ds_read_b128 v[232:235], v146 offset:53248
	ds_read_b128 v[236:239], v146 offset:54272
	ds_read_b128 v[240:243], v146 offset:55296
	ds_read_b128 v[244:247], v146 offset:56320
	global_load_lds_dwordx4 v[164:165], off
	s_add_i32 m0, s20, 0x2000
	s_add_u32 s14, s14, 0xb0080
	v_lshl_add_u64 v[164:165], v[202:203], 0, s[90:91]
	s_addc_u32 s15, s15, 0
	s_add_i32 s20, s50, s39
	global_load_lds_dwordx4 v[164:165], off
	v_lshl_add_u64 v[164:165], s[14:15], 0, v[178:179]
	s_mov_b32 m0, s20
	s_nop 0
	global_load_lds_dwordx4 v[164:165], off
	v_lshl_add_u64 v[164:165], s[14:15], 0, v[130:131]
	s_add_i32 m0, s20, 0x2000
	s_nop 0
	global_load_lds_dwordx4 v[164:165], off
	v_lshl_add_u64 v[164:165], v[206:207], 0, s[90:91]
	s_mov_b32 m0, s40
	s_nop 0
	global_load_lds_dwordx4 v[164:165], off
	v_lshl_add_u64 v[164:165], v[248:249], 0, s[90:91]
	s_mov_b32 m0, s41
	s_nop 0
	global_load_lds_dwordx4 v[164:165], off
	s_waitcnt vmcnt(8)
	s_waitcnt lgkmcnt(0)
	s_setprio 1
	s_barrier
	v_mfma_f32_16x16x32_bf16 v[110:113], v[148:151], v[216:219], v[110:113]
	v_mfma_f32_16x16x32_bf16 v[106:109], v[156:159], v[216:219], v[106:109]
	v_mfma_f32_16x16x32_bf16 v[126:129], v[148:151], v[224:227], v[126:129]
	v_mfma_f32_16x16x32_bf16 v[118:121], v[156:159], v[224:227], v[118:121]
	v_mfma_f32_16x16x32_bf16 v[78:81], v[148:151], v[232:235], v[78:81]
	v_mfma_f32_16x16x32_bf16 v[74:77], v[156:159], v[232:235], v[74:77]
	v_mfma_f32_16x16x32_bf16 v[30:33], v[148:151], v[240:243], v[30:33]
	v_mfma_f32_16x16x32_bf16 v[26:29], v[156:159], v[240:243], v[26:29]
	v_mfma_f32_16x16x32_bf16 v[110:113], v[152:155], v[220:223], v[110:113]
	v_mfma_f32_16x16x32_bf16 v[106:109], v[160:163], v[220:223], v[106:109]
	v_mfma_f32_16x16x32_bf16 v[126:129], v[152:155], v[228:231], v[126:129]
	v_mfma_f32_16x16x32_bf16 v[118:121], v[160:163], v[228:231], v[118:121]
	v_mfma_f32_16x16x32_bf16 v[78:81], v[152:155], v[236:239], v[78:81]
	v_mfma_f32_16x16x32_bf16 v[74:77], v[160:163], v[236:239], v[74:77]
	v_mfma_f32_16x16x32_bf16 v[30:33], v[152:155], v[244:247], v[30:33]
	v_mfma_f32_16x16x32_bf16 v[26:29], v[160:163], v[244:247], v[26:29]
	v_mfma_f32_16x16x32_bf16 v[122:125], v[170:173], v[216:219], v[122:125]
	v_mfma_f32_16x16x32_bf16 v[114:117], v[196:199], v[216:219], v[114:117]
	v_mfma_f32_16x16x32_bf16 v[102:105], v[170:173], v[224:227], v[102:105]
	v_mfma_f32_16x16x32_bf16 v[98:101], v[196:199], v[224:227], v[98:101]
	v_mfma_f32_16x16x32_bf16 v[54:57], v[170:173], v[232:235], v[54:57]
	v_mfma_f32_16x16x32_bf16 v[50:53], v[196:199], v[232:235], v[50:53]
	v_mfma_f32_16x16x32_bf16 v[22:25], v[170:173], v[240:243], v[22:25]
	v_mfma_f32_16x16x32_bf16 v[10:13], v[196:199], v[240:243], v[10:13]
	v_mfma_f32_16x16x32_bf16 v[122:125], v[174:177], v[220:223], v[122:125]
	v_mfma_f32_16x16x32_bf16 v[114:117], v[212:215], v[220:223], v[114:117]
	v_mfma_f32_16x16x32_bf16 v[102:105], v[174:177], v[228:231], v[102:105]
	v_mfma_f32_16x16x32_bf16 v[98:101], v[212:215], v[228:231], v[98:101]
	v_mfma_f32_16x16x32_bf16 v[54:57], v[174:177], v[236:239], v[54:57]
	v_mfma_f32_16x16x32_bf16 v[50:53], v[212:215], v[236:239], v[50:53]
	v_mfma_f32_16x16x32_bf16 v[22:25], v[174:177], v[244:247], v[22:25]
	v_mfma_f32_16x16x32_bf16 v[10:13], v[212:215], v[244:247], v[10:13]
	s_barrier
	s_setprio 0
	s_add_i32 s48, s48, 2
	s_add_u32 s16, s16, 0x100
	s_addc_u32 s17, s17, 0
	s_cmp_gt_u32 s48, 41
	s_cbranch_scc0 .LBB0_1224
	s_add_u32 s14, s46, 0xffffff00
	s_addc_u32 s15, s47, -1
	s_and_b64 vcc, exec, s[8:9]
	s_cbranch_vccnz .LBB0_1227
	v_mov_b32_e32 v10, 0
	s_mov_b32 s24, s43
	s_mov_b32 s93, s44
	s_mov_b64 s[28:29], s[10:11]
	s_mov_b32 s42, s45
	v_mov_b32_e32 v11, v10
	v_mov_b32_e32 v12, v10
	v_mov_b32_e32 v13, v10
	v_mov_b32_e32 v22, v10
	v_mov_b32_e32 v23, v10
	v_mov_b32_e32 v24, v10
	v_mov_b32_e32 v25, v10
	v_mov_b32_e32 v50, v10
	v_mov_b32_e32 v51, v10
	v_mov_b32_e32 v52, v10
	v_mov_b32_e32 v53, v10
	v_mov_b32_e32 v54, v10
	v_mov_b32_e32 v55, v10
	v_mov_b32_e32 v56, v10
	v_mov_b32_e32 v57, v10
	v_mov_b32_e32 v98, v10
	v_mov_b32_e32 v99, v10
	v_mov_b32_e32 v100, v10
	v_mov_b32_e32 v101, v10
	v_mov_b32_e32 v102, v10
	v_mov_b32_e32 v103, v10
	v_mov_b32_e32 v104, v10
	v_mov_b32_e32 v105, v10
	v_mov_b32_e32 v114, v10
	v_mov_b32_e32 v115, v10
	v_mov_b32_e32 v116, v10
	v_mov_b32_e32 v117, v10
	v_mov_b32_e32 v122, v10
	v_mov_b32_e32 v123, v10
	v_mov_b32_e32 v124, v10
	v_mov_b32_e32 v125, v10
	v_mov_b32_e32 v26, v10
	v_mov_b32_e32 v27, v10
	v_mov_b32_e32 v28, v10
	v_mov_b32_e32 v29, v10
	v_mov_b32_e32 v30, v10
	v_mov_b32_e32 v31, v10
	v_mov_b32_e32 v32, v10
	v_mov_b32_e32 v33, v10
	v_mov_b32_e32 v74, v10
	v_mov_b32_e32 v75, v10
	v_mov_b32_e32 v76, v10
	v_mov_b32_e32 v77, v10
	v_mov_b32_e32 v78, v10
	v_mov_b32_e32 v79, v10
	v_mov_b32_e32 v80, v10
	v_mov_b32_e32 v81, v10
	v_mov_b32_e32 v118, v10
	v_mov_b32_e32 v119, v10
	v_mov_b32_e32 v120, v10
	v_mov_b32_e32 v121, v10
	v_mov_b32_e32 v126, v10
	v_mov_b32_e32 v127, v10
	v_mov_b32_e32 v128, v10
	v_mov_b32_e32 v129, v10
	v_mov_b32_e32 v106, v10
	v_mov_b32_e32 v107, v10
	v_mov_b32_e32 v108, v10
	v_mov_b32_e32 v109, v10
	v_mov_b32_e32 v110, v10
	v_mov_b32_e32 v111, v10
	v_mov_b32_e32 v112, v10
	v_mov_b32_e32 v113, v10
	v_mov_b32_e32 v90, v10
	v_mov_b32_e32 v91, v10
	v_mov_b32_e32 v92, v10
	v_mov_b32_e32 v93, v10
	v_mov_b32_e32 v94, v10
	v_mov_b32_e32 v95, v10
	v_mov_b32_e32 v96, v10
	v_mov_b32_e32 v97, v10
	v_mov_b32_e32 v66, v10
	v_mov_b32_e32 v67, v10
	v_mov_b32_e32 v68, v10
	v_mov_b32_e32 v69, v10
	v_mov_b32_e32 v70, v10
	v_mov_b32_e32 v71, v10
	v_mov_b32_e32 v72, v10
	v_mov_b32_e32 v73, v10
	v_mov_b32_e32 v42, v10
	v_mov_b32_e32 v43, v10
	v_mov_b32_e32 v44, v10
	v_mov_b32_e32 v45, v10
	v_mov_b32_e32 v46, v10
	v_mov_b32_e32 v47, v10
	v_mov_b32_e32 v48, v10
	v_mov_b32_e32 v49, v10
	v_mov_b32_e32 v14, v10
	v_mov_b32_e32 v15, v10
	v_mov_b32_e32 v16, v10
	v_mov_b32_e32 v17, v10
	v_mov_b32_e32 v18, v10
	v_mov_b32_e32 v19, v10
	v_mov_b32_e32 v20, v10
	v_mov_b32_e32 v21, v10
	v_mov_b32_e32 v82, v10
	v_mov_b32_e32 v83, v10
	v_mov_b32_e32 v84, v10
	v_mov_b32_e32 v85, v10
	v_mov_b32_e32 v86, v10
	v_mov_b32_e32 v87, v10
	v_mov_b32_e32 v88, v10
	v_mov_b32_e32 v89, v10
	v_mov_b32_e32 v58, v10
	v_mov_b32_e32 v59, v10
	v_mov_b32_e32 v60, v10
	v_mov_b32_e32 v61, v10
	v_mov_b32_e32 v62, v10
	v_mov_b32_e32 v63, v10
	v_mov_b32_e32 v64, v10
	v_mov_b32_e32 v65, v10
	v_mov_b32_e32 v34, v10
	v_mov_b32_e32 v35, v10
	v_mov_b32_e32 v36, v10
	v_mov_b32_e32 v37, v10
	v_mov_b32_e32 v38, v10
	v_mov_b32_e32 v39, v10
	v_mov_b32_e32 v40, v10
	v_mov_b32_e32 v41, v10
	v_mov_b32_e32 v2, v10
	v_mov_b32_e32 v3, v10
	v_mov_b32_e32 v4, v10
	v_mov_b32_e32 v5, v10
	v_mov_b32_e32 v6, v10
	v_mov_b32_e32 v7, v10
	v_mov_b32_e32 v8, v10
	v_mov_b32_e32 v9, v10
	s_andn2_b64 vcc, exec, s[6:7]
	s_cbranch_vccnz .LBB0_1228
	s_branch .LBB0_1229

.LBB0_1289:
	s_add_u32 s14, s88, s16
	s_addc_u32 s15, s89, s17
	s_add_u32 s14, s14, 0x100
	s_addc_u32 s15, s15, 0
	s_add_u32 s49, s46, s16
	s_addc_u32 s50, s47, s17
	s_cmpk_eq_i32 s16, 0x1500
	s_cselect_b32 s21, s9, s15
	s_cselect_b32 s20, s8, s14
	v_add_u32_e32 v147, s31, v145
	s_cselect_b32 s15, s1, s50
	s_cselect_b32 s14, s0, s49
	s_add_i32 s49, 0, 0x14000
	ds_read_b128 v[148:151], v147
	ds_read_b128 v[152:155], v147 offset:1024
	ds_read_b128 v[156:159], v147 offset:2048
	ds_read_b128 v[160:163], v147 offset:3072
	v_add_u32_e32 v147, s49, v145
	ds_read_b128 v[168:171], v147
	ds_read_b128 v[172:175], v147 offset:1024
	ds_read_b128 v[196:199], v147 offset:2048
	ds_read_b128 v[212:215], v147 offset:3072
	v_lshl_add_u64 v[176:177], v[140:141], 0, s[16:17]
	s_add_i32 m0, s33, 0xc000
	ds_read_b128 v[216:219], v146
	ds_read_b128 v[220:223], v146 offset:1024
	ds_read_b128 v[224:227], v146 offset:2048
	ds_read_b128 v[228:231], v146 offset:3072
	ds_read_b128 v[232:235], v146 offset:4096
	ds_read_b128 v[236:239], v146 offset:5120
	ds_read_b128 v[240:243], v146 offset:6144
	ds_read_b128 v[244:247], v146 offset:7168
	global_load_lds_dwordx4 v[176:177], off
	v_lshl_add_u64 v[176:177], v[142:143], 0, s[16:17]
	s_add_i32 m0, s33, 0xe000
	s_nop 0
	global_load_lds_dwordx4 v[176:177], off
	s_waitcnt vmcnt(8)
	s_waitcnt lgkmcnt(0)
	s_setprio 1
	s_barrier
	v_mfma_f32_16x16x32_bf16 v[6:9], v[148:151], v[216:219], v[6:9]
	v_mfma_f32_16x16x32_bf16 v[2:5], v[156:159], v[216:219], v[2:5]
	v_mfma_f32_16x16x32_bf16 v[38:41], v[148:151], v[224:227], v[38:41]
	v_mfma_f32_16x16x32_bf16 v[34:37], v[156:159], v[224:227], v[34:37]
	v_mfma_f32_16x16x32_bf16 v[62:65], v[148:151], v[232:235], v[62:65]
	v_mfma_f32_16x16x32_bf16 v[58:61], v[156:159], v[232:235], v[58:61]
	v_mfma_f32_16x16x32_bf16 v[94:97], v[148:151], v[240:243], v[94:97]
	v_mfma_f32_16x16x32_bf16 v[90:93], v[156:159], v[240:243], v[90:93]
	v_mfma_f32_16x16x32_bf16 v[6:9], v[152:155], v[220:223], v[6:9]
	v_mfma_f32_16x16x32_bf16 v[2:5], v[160:163], v[220:223], v[2:5]
	v_mfma_f32_16x16x32_bf16 v[38:41], v[152:155], v[228:231], v[38:41]
	v_mfma_f32_16x16x32_bf16 v[34:37], v[160:163], v[228:231], v[34:37]
	v_mfma_f32_16x16x32_bf16 v[62:65], v[152:155], v[236:239], v[62:65]
	v_mfma_f32_16x16x32_bf16 v[58:61], v[160:163], v[236:239], v[58:61]
	v_mfma_f32_16x16x32_bf16 v[94:97], v[152:155], v[244:247], v[94:97]
	v_mfma_f32_16x16x32_bf16 v[90:93], v[160:163], v[244:247], v[90:93]
	v_mfma_f32_16x16x32_bf16 v[22:25], v[168:171], v[216:219], v[22:25]
	v_mfma_f32_16x16x32_bf16 v[18:21], v[196:199], v[216:219], v[18:21]
	v_mfma_f32_16x16x32_bf16 v[46:49], v[168:171], v[224:227], v[46:49]
	v_mfma_f32_16x16x32_bf16 v[42:45], v[196:199], v[224:227], v[42:45]
	v_mfma_f32_16x16x32_bf16 v[78:81], v[168:171], v[232:235], v[78:81]
	v_mfma_f32_16x16x32_bf16 v[74:77], v[196:199], v[232:235], v[74:77]
	v_mfma_f32_16x16x32_bf16 v[102:105], v[168:171], v[240:243], v[102:105]
	v_mfma_f32_16x16x32_bf16 v[98:101], v[196:199], v[240:243], v[98:101]
	v_mfma_f32_16x16x32_bf16 v[22:25], v[172:175], v[220:223], v[22:25]
	v_mfma_f32_16x16x32_bf16 v[18:21], v[212:215], v[220:223], v[18:21]
	v_mfma_f32_16x16x32_bf16 v[46:49], v[172:175], v[228:231], v[46:49]
	v_mfma_f32_16x16x32_bf16 v[42:45], v[212:215], v[228:231], v[42:45]
	v_mfma_f32_16x16x32_bf16 v[78:81], v[172:175], v[236:239], v[78:81]
	v_mfma_f32_16x16x32_bf16 v[74:77], v[212:215], v[236:239], v[74:77]
	v_mfma_f32_16x16x32_bf16 v[102:105], v[172:175], v[244:247], v[102:105]
	v_mfma_f32_16x16x32_bf16 v[98:101], v[212:215], v[244:247], v[98:101]
	s_barrier
	s_setprio 0
	s_add_i32 s50, s31, s39
	v_lshl_add_u64 v[176:177], s[14:15], 0, v[178:179]
	s_mov_b32 m0, s50
	ds_read_b128 v[216:219], v146 offset:16384
	ds_read_b128 v[220:223], v146 offset:17408
	ds_read_b128 v[224:227], v146 offset:18432
	ds_read_b128 v[228:231], v146 offset:19456
	ds_read_b128 v[232:235], v146 offset:20480
	ds_read_b128 v[236:239], v146 offset:21504
	ds_read_b128 v[240:243], v146 offset:22528
	ds_read_b128 v[244:247], v146 offset:23552
	global_load_lds_dwordx4 v[176:177], off
	s_add_i32 m0, s50, 0x2000
	s_add_u32 s50, s14, 0xb0000
	v_lshl_add_u64 v[202:203], s[14:15], 0, v[130:131]
	s_addc_u32 s51, s15, 0
	s_add_i32 s49, s49, s39
	global_load_lds_dwordx4 v[202:203], off
	v_lshl_add_u64 v[206:207], s[50:51], 0, v[178:179]
	s_mov_b32 m0, s49
	v_lshl_add_u64 v[248:249], s[20:21], 0, v[132:133]
	global_load_lds_dwordx4 v[206:207], off
	v_lshl_add_u64 v[206:207], s[50:51], 0, v[130:131]
	s_add_i32 m0, s49, 0x2000
	s_nop 0
	global_load_lds_dwordx4 v[206:207], off
	v_lshl_add_u64 v[206:207], s[20:21], 0, v[134:135]
	s_mov_b32 m0, s33
	s_nop 0
	global_load_lds_dwordx4 v[206:207], off
	s_mov_b32 m0, s4
	s_nop 0
	global_load_lds_dwordx4 v[248:249], off
	s_waitcnt vmcnt(8)
	s_waitcnt lgkmcnt(0)
	s_setprio 1
	s_barrier
	v_mfma_f32_16x16x32_bf16 v[118:121], v[148:151], v[216:219], v[118:121]
	v_mfma_f32_16x16x32_bf16 v[114:117], v[156:159], v[216:219], v[114:117]
	v_mfma_f32_16x16x32_bf16 v[110:113], v[148:151], v[224:227], v[110:113]
	v_mfma_f32_16x16x32_bf16 v[106:109], v[156:159], v[224:227], v[106:109]
	v_mfma_f32_16x16x32_bf16 v[70:73], v[148:151], v[232:235], v[70:73]
	v_mfma_f32_16x16x32_bf16 v[66:69], v[156:159], v[232:235], v[66:69]
	v_mfma_f32_16x16x32_bf16 v[30:33], v[148:151], v[240:243], v[30:33]
	v_mfma_f32_16x16x32_bf16 v[26:29], v[156:159], v[240:243], v[26:29]
	v_mfma_f32_16x16x32_bf16 v[118:121], v[152:155], v[220:223], v[118:121]
	v_mfma_f32_16x16x32_bf16 v[114:117], v[160:163], v[220:223], v[114:117]
	v_mfma_f32_16x16x32_bf16 v[110:113], v[152:155], v[228:231], v[110:113]
	v_mfma_f32_16x16x32_bf16 v[106:109], v[160:163], v[228:231], v[106:109]
	v_mfma_f32_16x16x32_bf16 v[70:73], v[152:155], v[236:239], v[70:73]
	v_mfma_f32_16x16x32_bf16 v[66:69], v[160:163], v[236:239], v[66:69]
	v_mfma_f32_16x16x32_bf16 v[30:33], v[152:155], v[244:247], v[30:33]
	v_mfma_f32_16x16x32_bf16 v[26:29], v[160:163], v[244:247], v[26:29]
	v_mfma_f32_16x16x32_bf16 v[126:129], v[168:171], v[216:219], v[126:129]
	v_mfma_f32_16x16x32_bf16 v[122:125], v[196:199], v[216:219], v[122:125]
	v_mfma_f32_16x16x32_bf16 v[86:89], v[168:171], v[224:227], v[86:89]
	v_mfma_f32_16x16x32_bf16 v[82:85], v[196:199], v[224:227], v[82:85]
	v_mfma_f32_16x16x32_bf16 v[54:57], v[168:171], v[232:235], v[54:57]
	v_mfma_f32_16x16x32_bf16 v[50:53], v[196:199], v[232:235], v[50:53]
	v_mfma_f32_16x16x32_bf16 v[14:17], v[168:171], v[240:243], v[14:17]
	v_mfma_f32_16x16x32_bf16 v[10:13], v[196:199], v[240:243], v[10:13]
	v_mfma_f32_16x16x32_bf16 v[126:129], v[172:175], v[220:223], v[126:129]
	v_mfma_f32_16x16x32_bf16 v[122:125], v[212:215], v[220:223], v[122:125]
	v_mfma_f32_16x16x32_bf16 v[86:89], v[172:175], v[228:231], v[86:89]
	v_mfma_f32_16x16x32_bf16 v[82:85], v[212:215], v[228:231], v[82:85]
	v_mfma_f32_16x16x32_bf16 v[54:57], v[172:175], v[236:239], v[54:57]
	v_mfma_f32_16x16x32_bf16 v[50:53], v[212:215], v[236:239], v[50:53]
	v_mfma_f32_16x16x32_bf16 v[14:17], v[172:175], v[244:247], v[14:17]
	v_mfma_f32_16x16x32_bf16 v[10:13], v[212:215], v[244:247], v[10:13]
	s_barrier
	s_setprio 0
	s_add_i32 s49, 0, 0x18000
	v_add_u32_e32 v147, s49, v145
	s_add_i32 s50, 0, 0x1c000
	ds_read_b128 v[148:151], v147
	ds_read_b128 v[152:155], v147 offset:1024
	ds_read_b128 v[156:159], v147 offset:2048
	ds_read_b128 v[160:163], v147 offset:3072
	v_add_u32_e32 v147, s50, v145
	ds_read_b128 v[168:171], v147
	ds_read_b128 v[172:175], v147 offset:1024
	ds_read_b128 v[196:199], v147 offset:2048
	ds_read_b128 v[212:215], v147 offset:3072
	s_add_u32 s20, s20, 0xb0000
	s_addc_u32 s21, s21, 0
	s_mov_b32 m0, s5
	v_lshl_add_u64 v[250:251], s[20:21], 0, v[134:135]
	ds_read_b128 v[216:219], v146 offset:32768
	ds_read_b128 v[220:223], v146 offset:33792
	ds_read_b128 v[224:227], v146 offset:34816
	ds_read_b128 v[228:231], v146 offset:35840
	ds_read_b128 v[232:235], v146 offset:36864
	ds_read_b128 v[236:239], v146 offset:37888
	ds_read_b128 v[240:243], v146 offset:38912
	ds_read_b128 v[244:247], v146 offset:39936
	global_load_lds_dwordx4 v[250:251], off
	v_lshl_add_u64 v[250:251], s[20:21], 0, v[132:133]
	s_mov_b32 m0, s40
	s_nop 0
	global_load_lds_dwordx4 v[250:251], off
	s_waitcnt vmcnt(8)
	s_waitcnt lgkmcnt(0)
	s_setprio 1
	s_barrier
	v_mfma_f32_16x16x32_bf16 v[6:9], v[148:151], v[216:219], v[6:9]
	v_mfma_f32_16x16x32_bf16 v[2:5], v[156:159], v[216:219], v[2:5]
	v_mfma_f32_16x16x32_bf16 v[38:41], v[148:151], v[224:227], v[38:41]
	v_mfma_f32_16x16x32_bf16 v[34:37], v[156:159], v[224:227], v[34:37]
	v_mfma_f32_16x16x32_bf16 v[62:65], v[148:151], v[232:235], v[62:65]
	v_mfma_f32_16x16x32_bf16 v[58:61], v[156:159], v[232:235], v[58:61]
	v_mfma_f32_16x16x32_bf16 v[94:97], v[148:151], v[240:243], v[94:97]
	v_mfma_f32_16x16x32_bf16 v[90:93], v[156:159], v[240:243], v[90:93]
	v_mfma_f32_16x16x32_bf16 v[6:9], v[152:155], v[220:223], v[6:9]
	v_mfma_f32_16x16x32_bf16 v[2:5], v[160:163], v[220:223], v[2:5]
	v_mfma_f32_16x16x32_bf16 v[38:41], v[152:155], v[228:231], v[38:41]
	v_mfma_f32_16x16x32_bf16 v[34:37], v[160:163], v[228:231], v[34:37]
	v_mfma_f32_16x16x32_bf16 v[62:65], v[152:155], v[236:239], v[62:65]
	v_mfma_f32_16x16x32_bf16 v[58:61], v[160:163], v[236:239], v[58:61]
	v_mfma_f32_16x16x32_bf16 v[94:97], v[152:155], v[244:247], v[94:97]
	v_mfma_f32_16x16x32_bf16 v[90:93], v[160:163], v[244:247], v[90:93]
	v_mfma_f32_16x16x32_bf16 v[22:25], v[168:171], v[216:219], v[22:25]
	v_mfma_f32_16x16x32_bf16 v[18:21], v[196:199], v[216:219], v[18:21]
	v_mfma_f32_16x16x32_bf16 v[46:49], v[168:171], v[224:227], v[46:49]
	v_mfma_f32_16x16x32_bf16 v[42:45], v[196:199], v[224:227], v[42:45]
	v_mfma_f32_16x16x32_bf16 v[78:81], v[168:171], v[232:235], v[78:81]
	v_mfma_f32_16x16x32_bf16 v[74:77], v[196:199], v[232:235], v[74:77]
	v_mfma_f32_16x16x32_bf16 v[102:105], v[168:171], v[240:243], v[102:105]
	v_mfma_f32_16x16x32_bf16 v[98:101], v[196:199], v[240:243], v[98:101]
	v_mfma_f32_16x16x32_bf16 v[22:25], v[172:175], v[220:223], v[22:25]
	v_mfma_f32_16x16x32_bf16 v[18:21], v[212:215], v[220:223], v[18:21]
	v_mfma_f32_16x16x32_bf16 v[46:49], v[172:175], v[228:231], v[46:49]
	v_mfma_f32_16x16x32_bf16 v[42:45], v[212:215], v[228:231], v[42:45]
	v_mfma_f32_16x16x32_bf16 v[78:81], v[172:175], v[236:239], v[78:81]
	v_mfma_f32_16x16x32_bf16 v[74:77], v[212:215], v[236:239], v[74:77]
	v_mfma_f32_16x16x32_bf16 v[102:105], v[172:175], v[244:247], v[102:105]
	v_mfma_f32_16x16x32_bf16 v[98:101], v[212:215], v[244:247], v[98:101]
	s_barrier
	s_setprio 0
	s_add_i32 s20, s49, s39
	v_lshl_add_u64 v[176:177], v[176:177], 0, s[90:91]
	s_mov_b32 m0, s20
	ds_read_b128 v[216:219], v146 offset:49152
	ds_read_b128 v[220:223], v146 offset:50176
	ds_read_b128 v[224:227], v146 offset:51200
	ds_read_b128 v[228:231], v146 offset:52224
	ds_read_b128 v[232:235], v146 offset:53248
	ds_read_b128 v[236:239], v146 offset:54272
	ds_read_b128 v[240:243], v146 offset:55296
	ds_read_b128 v[244:247], v146 offset:56320
	global_load_lds_dwordx4 v[176:177], off
	s_add_i32 m0, s20, 0x2000
	s_add_u32 s14, s14, 0xb0080
	v_lshl_add_u64 v[176:177], v[202:203], 0, s[90:91]
	s_addc_u32 s15, s15, 0
	s_add_i32 s20, s50, s39
	global_load_lds_dwordx4 v[176:177], off
	v_lshl_add_u64 v[176:177], s[14:15], 0, v[178:179]
	s_mov_b32 m0, s20
	s_nop 0
	global_load_lds_dwordx4 v[176:177], off
	v_lshl_add_u64 v[176:177], s[14:15], 0, v[130:131]
	s_add_i32 m0, s20, 0x2000
	s_nop 0
	global_load_lds_dwordx4 v[176:177], off
	v_lshl_add_u64 v[176:177], v[206:207], 0, s[90:91]
	s_mov_b32 m0, s41
	s_nop 0
	global_load_lds_dwordx4 v[176:177], off
	v_lshl_add_u64 v[176:177], v[248:249], 0, s[90:91]
	s_mov_b32 m0, s42
	s_nop 0
	global_load_lds_dwordx4 v[176:177], off
	s_waitcnt vmcnt(8)
	s_waitcnt lgkmcnt(0)
	s_setprio 1
	s_barrier
	v_mfma_f32_16x16x32_bf16 v[118:121], v[148:151], v[216:219], v[118:121]
	v_mfma_f32_16x16x32_bf16 v[114:117], v[156:159], v[216:219], v[114:117]
	v_mfma_f32_16x16x32_bf16 v[110:113], v[148:151], v[224:227], v[110:113]
	v_mfma_f32_16x16x32_bf16 v[106:109], v[156:159], v[224:227], v[106:109]
	v_mfma_f32_16x16x32_bf16 v[70:73], v[148:151], v[232:235], v[70:73]
	v_mfma_f32_16x16x32_bf16 v[66:69], v[156:159], v[232:235], v[66:69]
	v_mfma_f32_16x16x32_bf16 v[30:33], v[148:151], v[240:243], v[30:33]
	v_mfma_f32_16x16x32_bf16 v[26:29], v[156:159], v[240:243], v[26:29]
	v_mfma_f32_16x16x32_bf16 v[118:121], v[152:155], v[220:223], v[118:121]
	v_mfma_f32_16x16x32_bf16 v[114:117], v[160:163], v[220:223], v[114:117]
	v_mfma_f32_16x16x32_bf16 v[110:113], v[152:155], v[228:231], v[110:113]
	v_mfma_f32_16x16x32_bf16 v[106:109], v[160:163], v[228:231], v[106:109]
	v_mfma_f32_16x16x32_bf16 v[70:73], v[152:155], v[236:239], v[70:73]
	v_mfma_f32_16x16x32_bf16 v[66:69], v[160:163], v[236:239], v[66:69]
	v_mfma_f32_16x16x32_bf16 v[30:33], v[152:155], v[244:247], v[30:33]
	v_mfma_f32_16x16x32_bf16 v[26:29], v[160:163], v[244:247], v[26:29]
	v_mfma_f32_16x16x32_bf16 v[126:129], v[168:171], v[216:219], v[126:129]
	v_mfma_f32_16x16x32_bf16 v[122:125], v[196:199], v[216:219], v[122:125]
	v_mfma_f32_16x16x32_bf16 v[86:89], v[168:171], v[224:227], v[86:89]
	v_mfma_f32_16x16x32_bf16 v[82:85], v[196:199], v[224:227], v[82:85]
	v_mfma_f32_16x16x32_bf16 v[54:57], v[168:171], v[232:235], v[54:57]
	v_mfma_f32_16x16x32_bf16 v[50:53], v[196:199], v[232:235], v[50:53]
	v_mfma_f32_16x16x32_bf16 v[14:17], v[168:171], v[240:243], v[14:17]
	v_mfma_f32_16x16x32_bf16 v[10:13], v[196:199], v[240:243], v[10:13]
	v_mfma_f32_16x16x32_bf16 v[126:129], v[172:175], v[220:223], v[126:129]
	v_mfma_f32_16x16x32_bf16 v[122:125], v[212:215], v[220:223], v[122:125]
	v_mfma_f32_16x16x32_bf16 v[86:89], v[172:175], v[228:231], v[86:89]
	v_mfma_f32_16x16x32_bf16 v[82:85], v[212:215], v[228:231], v[82:85]
	v_mfma_f32_16x16x32_bf16 v[54:57], v[172:175], v[236:239], v[54:57]
	v_mfma_f32_16x16x32_bf16 v[50:53], v[212:215], v[236:239], v[50:53]
	v_mfma_f32_16x16x32_bf16 v[14:17], v[172:175], v[244:247], v[14:17]
	v_mfma_f32_16x16x32_bf16 v[10:13], v[212:215], v[244:247], v[10:13]
	s_barrier
	s_setprio 0
	s_add_i32 s48, s48, 2
	s_add_u32 s16, s16, 0x100
	s_addc_u32 s17, s17, 0
	s_cmp_gt_u32 s48, 41
	s_cbranch_scc0 .LBB0_1289
	s_add_u32 s14, s46, 0xffffff00
	s_addc_u32 s15, s47, -1
	s_and_b64 vcc, exec, s[6:7]
	s_cbranch_vccnz .LBB0_1292
	v_mov_b32_e32 v10, 0
	s_mov_b32 s12, s44
	s_mov_b32 s95, s45
	s_mov_b64 s[88:89], s[8:9]
	s_mov_b32 s43, s85
	v_mov_b32_e32 v11, v10
	v_mov_b32_e32 v12, v10
	v_mov_b32_e32 v13, v10
	v_mov_b32_e32 v14, v10
	v_mov_b32_e32 v15, v10
	v_mov_b32_e32 v16, v10
	v_mov_b32_e32 v17, v10
	v_mov_b32_e32 v50, v10
	v_mov_b32_e32 v51, v10
	v_mov_b32_e32 v52, v10
	v_mov_b32_e32 v53, v10
	v_mov_b32_e32 v54, v10
	v_mov_b32_e32 v55, v10
	v_mov_b32_e32 v56, v10
	v_mov_b32_e32 v57, v10
	v_mov_b32_e32 v82, v10
	v_mov_b32_e32 v83, v10
	v_mov_b32_e32 v84, v10
	v_mov_b32_e32 v85, v10
	v_mov_b32_e32 v86, v10
	v_mov_b32_e32 v87, v10
	v_mov_b32_e32 v88, v10
	v_mov_b32_e32 v89, v10
	v_mov_b32_e32 v122, v10
	v_mov_b32_e32 v123, v10
	v_mov_b32_e32 v124, v10
	v_mov_b32_e32 v125, v10
	v_mov_b32_e32 v126, v10
	v_mov_b32_e32 v127, v10
	v_mov_b32_e32 v128, v10
	v_mov_b32_e32 v129, v10
	v_mov_b32_e32 v26, v10
	v_mov_b32_e32 v27, v10
	v_mov_b32_e32 v28, v10
	v_mov_b32_e32 v29, v10
	v_mov_b32_e32 v30, v10
	v_mov_b32_e32 v31, v10
	v_mov_b32_e32 v32, v10
	v_mov_b32_e32 v33, v10
	v_mov_b32_e32 v66, v10
	v_mov_b32_e32 v67, v10
	v_mov_b32_e32 v68, v10
	v_mov_b32_e32 v69, v10
	v_mov_b32_e32 v70, v10
	v_mov_b32_e32 v71, v10
	v_mov_b32_e32 v72, v10
	v_mov_b32_e32 v73, v10
	v_mov_b32_e32 v106, v10
	v_mov_b32_e32 v107, v10
	v_mov_b32_e32 v108, v10
	v_mov_b32_e32 v109, v10
	v_mov_b32_e32 v110, v10
	v_mov_b32_e32 v111, v10
	v_mov_b32_e32 v112, v10
	v_mov_b32_e32 v113, v10
	v_mov_b32_e32 v114, v10
	v_mov_b32_e32 v115, v10
	v_mov_b32_e32 v116, v10
	v_mov_b32_e32 v117, v10
	v_mov_b32_e32 v118, v10
	v_mov_b32_e32 v119, v10
	v_mov_b32_e32 v120, v10
	v_mov_b32_e32 v121, v10
	v_mov_b32_e32 v98, v10
	v_mov_b32_e32 v99, v10
	v_mov_b32_e32 v100, v10
	v_mov_b32_e32 v101, v10
	v_mov_b32_e32 v102, v10
	v_mov_b32_e32 v103, v10
	v_mov_b32_e32 v104, v10
	v_mov_b32_e32 v105, v10
	v_mov_b32_e32 v74, v10
	v_mov_b32_e32 v75, v10
	v_mov_b32_e32 v76, v10
	v_mov_b32_e32 v77, v10
	v_mov_b32_e32 v78, v10
	v_mov_b32_e32 v79, v10
	v_mov_b32_e32 v80, v10
	v_mov_b32_e32 v81, v10
	v_mov_b32_e32 v42, v10
	v_mov_b32_e32 v43, v10
	v_mov_b32_e32 v44, v10
	v_mov_b32_e32 v45, v10
	v_mov_b32_e32 v46, v10
	v_mov_b32_e32 v47, v10
	v_mov_b32_e32 v48, v10
	v_mov_b32_e32 v49, v10
	v_mov_b32_e32 v18, v10
	v_mov_b32_e32 v19, v10
	v_mov_b32_e32 v20, v10
	v_mov_b32_e32 v21, v10
	v_mov_b32_e32 v22, v10
	v_mov_b32_e32 v23, v10
	v_mov_b32_e32 v24, v10
	v_mov_b32_e32 v25, v10
	v_mov_b32_e32 v90, v10
	v_mov_b32_e32 v91, v10
	v_mov_b32_e32 v92, v10
	v_mov_b32_e32 v93, v10
	v_mov_b32_e32 v94, v10
	v_mov_b32_e32 v95, v10
	v_mov_b32_e32 v96, v10
	v_mov_b32_e32 v97, v10
	v_mov_b32_e32 v58, v10
	v_mov_b32_e32 v59, v10
	v_mov_b32_e32 v60, v10
	v_mov_b32_e32 v61, v10
	v_mov_b32_e32 v62, v10
	v_mov_b32_e32 v63, v10
	v_mov_b32_e32 v64, v10
	v_mov_b32_e32 v65, v10
	v_mov_b32_e32 v34, v10
	v_mov_b32_e32 v35, v10
	v_mov_b32_e32 v36, v10
	v_mov_b32_e32 v37, v10
	v_mov_b32_e32 v38, v10
	v_mov_b32_e32 v39, v10
	v_mov_b32_e32 v40, v10
	v_mov_b32_e32 v41, v10
	v_mov_b32_e32 v2, v10
	v_mov_b32_e32 v3, v10
	v_mov_b32_e32 v4, v10
	v_mov_b32_e32 v5, v10
	v_mov_b32_e32 v6, v10
	v_mov_b32_e32 v7, v10
	v_mov_b32_e32 v8, v10
	v_mov_b32_e32 v9, v10
	s_andn2_b64 vcc, exec, s[10:11]
	s_cbranch_vccnz .LBB0_1293
	s_branch .LBB0_1294
